# v75 + nt on the once-read x row loads and the f32 row stores of the four resid_norm_row loops (keeps the GEMM-written Y rows and the XN rows in the Infinity Cache)
# speedup vs baseline: 1.0035x; 1.0035x over previous
.LBB0_1692:
	s_waitcnt lgkmcnt(0)
	v_lshl_add_u64 v[4:5], s[16:17], 0, v[68:69]
	global_load_dword v8, v[4:5], off
	global_load_dwordx4 v[160:163], v72, s[80:81] offset:0 nt
	global_load_dwordx2 v[224:225], v70, s[88:89] offset:0
	global_load_dwordx4 v[164:167], v72, s[80:81] offset:1024 nt
	global_load_dwordx2 v[226:227], v70, s[88:89] offset:512
	global_load_dwordx4 v[168:171], v72, s[80:81] offset:2048 nt
	global_load_dwordx2 v[228:229], v70, s[88:89] offset:1024
	global_load_dwordx4 v[172:175], v72, s[80:81] offset:3072 nt
	global_load_dwordx2 v[230:231], v70, s[88:89] offset:1536
	global_load_dwordx4 v[176:179], v72, s[82:83] offset:0 nt
	global_load_dwordx2 v[232:233], v70, s[88:89] offset:2048
	global_load_dwordx4 v[180:183], v72, s[82:83] offset:1024 nt
	global_load_dwordx2 v[234:235], v70, s[88:89] offset:2560
	global_load_dwordx4 v[184:187], v72, s[82:83] offset:2048 nt
	global_load_dwordx2 v[236:237], v70, s[88:89] offset:3072
	global_load_dwordx4 v[188:191], v72, s[82:83] offset:3072 nt
	global_load_dwordx2 v[238:239], v70, s[88:89] offset:3584
	global_load_dwordx4 v[192:195], v72, s[84:85] offset:0 nt
	global_load_dwordx2 v[240:241], v70, s[90:91] offset:0
	global_load_dwordx4 v[196:199], v72, s[84:85] offset:1024 nt
	global_load_dwordx2 v[242:243], v70, s[90:91] offset:512
	global_load_dwordx4 v[200:203], v72, s[84:85] offset:2048 nt
	global_load_dwordx2 v[244:245], v70, s[90:91] offset:1024
	global_load_dwordx4 v[204:207], v72, s[84:85] offset:3072 nt
	global_load_dwordx2 v[246:247], v70, s[90:91] offset:1536
	global_load_dwordx4 v[208:211], v72, s[86:87] offset:0 nt
	global_load_dwordx2 v[248:249], v70, s[90:91] offset:2048
	global_load_dwordx4 v[212:215], v72, s[86:87] offset:1024 nt
	global_load_dwordx2 v[250:251], v70, s[90:91] offset:2560
	global_load_dwordx4 v[216:219], v72, s[86:87] offset:2048 nt
	global_load_dwordx2 v[252:253], v70, s[90:91] offset:3072
	global_load_dwordx4 v[220:223], v72, s[86:87] offset:3072 nt
	global_load_dwordx2 v[254:255], v70, s[90:91] offset:3584
	ds_read_b128 v[0:3], v150 offset:0
	v_lshl_add_u64 v[12:13], s[12:13], 0, v[72:73]
	s_waitcnt vmcnt(31)
	s_nop 1
	v_mov_b32_e32 v4, v160
	v_mov_b32_e32 v5, v161
	v_mov_b32_e32 v6, v162
	v_mov_b32_e32 v7, v163
	v_lshl_add_u64 v[74:75], s[16:17], 0, v[70:71]
	v_add_co_u32_e32 v120, vcc, s28, v74
	s_waitcnt vmcnt(32) lgkmcnt(0)
	ds_bpermute_b32 v9, v126, v8
	v_addc_co_u32_e32 v121, vcc, 0, v75, vcc
	s_waitcnt vmcnt(30)
	s_nop 1
	v_mov_b32_e32 v76, v224
	v_mov_b32_e32 v77, v225
	v_add_co_u32_e32 v14, vcc, s15, v74
	s_waitcnt lgkmcnt(0)
	v_add_f32_e32 v8, v8, v9
	ds_bpermute_b32 v9, v127, v8
	v_addc_co_u32_e32 v15, vcc, 0, v75, vcc
	s_waitcnt lgkmcnt(0)
	v_mov_b32_e32 v78, v0
	s_waitcnt lgkmcnt(0)
	v_mov_b32_e32 v0, v4
	s_waitcnt lgkmcnt(0)
	v_add_f32_e32 v10, v8, v9
	ds_bpermute_b32 v11, v128, v10
	v_lshl_add_u64 v[8:9], s[16:17], 0, v[72:73]
	v_mov_b32_e32 v79, v2
	v_mov_b32_e32 v2, v1
	v_mov_b32_e32 v1, v6
	s_waitcnt lgkmcnt(0)
	v_add_f32_e32 v10, v10, v11
	ds_bpermute_b32 v11, v129, v10
	v_mov_b32_e32 v6, v5
	s_waitcnt lgkmcnt(0)
	v_add_f32_e32 v80, v10, v11
	ds_bpermute_b32 v81, v130, v80
	v_add_co_u32_e32 v10, vcc, s27, v8
	s_waitcnt lgkmcnt(0)
	v_add_f32_e32 v80, v80, v81
	ds_bpermute_b32 v81, v131, v80
	v_addc_co_u32_e32 v11, vcc, 0, v9, vcc
	s_waitcnt lgkmcnt(0)
	v_add_f32_e32 v4, v80, v81
	v_fmamk_f32 v4, v4, 0x39800000, v132
	v_mul_f32_e32 v5, 0x4f800000, v4
	v_cmp_gt_f32_e32 vcc, s11, v4
	s_nop 1
	v_cndmask_b32_e32 v80, v4, v5, vcc
	v_sqrt_f32_e32 v81, v80
	s_waitcnt lgkmcnt(0)
	v_lshlrev_b32_e32 v4, 16, v76
	v_add_u32_e32 v82, -1, v81
	v_add_u32_e32 v83, 1, v81
	v_fma_f32 v84, -v82, v81, v80
	v_fma_f32 v85, -v83, v81, v80
	v_cmp_ge_f32_e64 s[2:3], 0, v84
	v_and_b32_e32 v76, 0xffff0000, v76
	v_lshlrev_b32_e32 v5, 16, v77
	v_cndmask_b32_e64 v81, v81, v82, s[2:3]
	v_cmp_lt_f32_e64 s[2:3], 0, v85
	v_and_b32_e32 v77, 0xffff0000, v77
	s_nop 0
	v_cndmask_b32_e64 v81, v81, v83, s[2:3]
	v_mul_f32_e32 v82, 0x37800000, v81
	v_cndmask_b32_e32 v81, v81, v82, vcc
	v_cmp_class_f32_e32 vcc, v80, v133
	s_nop 1
	v_cndmask_b32_e32 v80, v81, v80, vcc
	v_div_scale_f32 v81, s[2:3], v80, v80, 1.0
	v_rcp_f32_e32 v82, v81
	v_div_scale_f32 v83, vcc, 1.0, v80, 1.0
	v_fma_f32 v84, -v81, v82, 1.0
	v_fmac_f32_e32 v82, v84, v82
	v_mul_f32_e32 v84, v83, v82
	v_fma_f32 v85, -v81, v84, v83
	v_fmac_f32_e32 v84, v85, v82
	v_fma_f32 v81, -v81, v84, v83
	v_div_fmas_f32 v81, v81, v82, v84
	v_div_fixup_f32 v122, v81, v80, 1.0
	v_pk_mul_f32 v[4:5], v[122:123], v[4:5] op_sel_hi:[0,1]
	v_pk_mul_f32 v[76:77], v[122:123], v[76:77] op_sel_hi:[0,1]
	v_pk_fma_f32 v[82:83], v[78:79], v[4:5], v[0:1]
	v_pk_fma_f32 v[76:77], v[2:3], v[76:77], v[6:7]
	v_mov_b32_e32 v0, v82
	v_mov_b32_e32 v1, v76
	v_mov_b32_e32 v2, v83
	v_mov_b32_e32 v3, v77
	global_store_dwordx4 v[10:11], v[0:3], off offset:-4096 nt
	s_waitcnt vmcnt(29)
	s_nop 1
	v_mov_b32_e32 v78, v226
	v_mov_b32_e32 v79, v227
	s_nop 0
	ds_read_b128 v[0:3], v150 offset:1024
	s_waitcnt vmcnt(30)
	s_nop 1
	v_mov_b32_e32 v4, v164
	v_mov_b32_e32 v5, v165
	v_mov_b32_e32 v6, v166
	v_mov_b32_e32 v7, v167
	v_add_co_u32_e32 v92, vcc, s26, v8
	s_waitcnt lgkmcnt(0)
	v_lshlrev_b32_e32 v81, 16, v79
	v_lshlrev_b32_e32 v80, 16, v78
	v_and_b32_e32 v79, 0xffff0000, v79
	v_and_b32_e32 v78, 0xffff0000, v78
	s_waitcnt lgkmcnt(0)
	v_mov_b32_e32 v84, v0
	v_mov_b32_e32 v85, v2
	s_waitcnt lgkmcnt(0)
	v_mov_b32_e32 v86, v4
	v_mov_b32_e32 v87, v6
	v_mov_b32_e32 v2, v1
	v_mov_b32_e32 v6, v5
	v_pk_mul_f32 v[0:1], v[122:123], v[80:81] op_sel_hi:[0,1]
	v_pk_mul_f32 v[4:5], v[122:123], v[78:79] op_sel_hi:[0,1]
	v_pk_fma_f32 v[86:87], v[84:85], v[0:1], v[86:87]
	v_pk_fma_f32 v[84:85], v[2:3], v[4:5], v[6:7]
	v_addc_co_u32_e32 v93, vcc, 0, v9, vcc
	v_mov_b32_e32 v0, v86
	v_mov_b32_e32 v1, v84
	v_mov_b32_e32 v2, v87
	v_mov_b32_e32 v3, v85
	global_store_dwordx4 v[92:93], v[0:3], off offset:1024 nt
	s_waitcnt vmcnt(28)
	s_nop 1
	v_mov_b32_e32 v78, v228
	v_mov_b32_e32 v79, v229
	s_nop 0
	s_waitcnt vmcnt(29)
	s_nop 1
	v_mov_b32_e32 v0, v168
	v_mov_b32_e32 v1, v169
	v_mov_b32_e32 v2, v170
	v_mov_b32_e32 v3, v171
	ds_read_b128 v[4:7], v150 offset:2048
	v_add_co_u32_e32 v104, vcc, s24, v12
	s_waitcnt lgkmcnt(0)
	v_lshlrev_b32_e32 v80, 16, v78
	v_and_b32_e32 v81, 0xffff0000, v78
	v_lshlrev_b32_e32 v78, 16, v79
	v_and_b32_e32 v79, 0xffff0000, v79
	v_pk_mul_f32 v[80:81], v[122:123], v[80:81] op_sel_hi:[0,1]
	v_pk_mul_f32 v[78:79], v[122:123], v[78:79] op_sel_hi:[0,1]
	s_waitcnt lgkmcnt(0)
	v_pk_fma_f32 v[0:1], v[4:5], v[80:81], v[0:1]
	v_pk_fma_f32 v[2:3], v[6:7], v[78:79], v[2:3]
	global_store_dwordx4 v[92:93], v[0:3], off offset:2048 nt
	s_waitcnt vmcnt(27)
	s_nop 1
	v_mov_b32_e32 v78, v230
	v_mov_b32_e32 v79, v231
	ds_read_b128 v[4:7], v150 offset:3072
	s_waitcnt vmcnt(28)
	s_nop 1
	v_mov_b32_e32 v88, v172
	v_mov_b32_e32 v89, v173
	v_mov_b32_e32 v90, v174
	v_mov_b32_e32 v91, v175
	v_addc_co_u32_e32 v105, vcc, 0, v13, vcc
	v_add_co_u32_e32 v110, vcc, s23, v12
	s_waitcnt lgkmcnt(0)
	v_lshlrev_b32_e32 v80, 16, v78
	v_and_b32_e32 v78, 0xffff0000, v78
	v_lshlrev_b32_e32 v81, 16, v79
	v_and_b32_e32 v79, 0xffff0000, v79
	s_waitcnt lgkmcnt(0)
	v_mov_b32_e32 v94, v4
	v_mov_b32_e32 v95, v6
	s_waitcnt lgkmcnt(0)
	v_mov_b32_e32 v96, v88
	v_mov_b32_e32 v97, v90
	v_mov_b32_e32 v6, v5
	v_mov_b32_e32 v90, v89
	v_pk_mul_f32 v[4:5], v[122:123], v[80:81] op_sel_hi:[0,1]
	v_pk_mul_f32 v[78:79], v[122:123], v[78:79] op_sel_hi:[0,1]
	v_pk_fma_f32 v[80:81], v[94:95], v[4:5], v[96:97]
	v_pk_fma_f32 v[78:79], v[6:7], v[78:79], v[90:91]
	v_mov_b32_e32 v4, v80
	v_mov_b32_e32 v5, v78
	v_mov_b32_e32 v6, v81
	v_mov_b32_e32 v7, v79
	global_store_dwordx4 v[92:93], v[4:7], off offset:3072 nt
	s_waitcnt vmcnt(26)
	s_nop 1
	v_mov_b32_e32 v88, v232
	v_mov_b32_e32 v89, v233
	s_nop 0
	ds_read_b128 v[4:7], v150 offset:4096
	s_waitcnt vmcnt(27)
	s_nop 1
	v_mov_b32_e32 v90, v176
	v_mov_b32_e32 v91, v177
	v_mov_b32_e32 v92, v178
	v_mov_b32_e32 v93, v179
	v_addc_co_u32_e32 v111, vcc, 0, v13, vcc
	v_add_co_u32_e32 v124, vcc, s30, v8
	s_waitcnt lgkmcnt(0)
	v_lshlrev_b32_e32 v95, 16, v89
	v_lshlrev_b32_e32 v94, 16, v88
	v_and_b32_e32 v89, 0xffff0000, v89
	v_and_b32_e32 v88, 0xffff0000, v88
	s_waitcnt lgkmcnt(0)
	v_mov_b32_e32 v96, v4
	v_mov_b32_e32 v97, v6
	s_waitcnt lgkmcnt(0)
	v_mov_b32_e32 v98, v90
	v_mov_b32_e32 v99, v92
	v_mov_b32_e32 v6, v5
	v_mov_b32_e32 v92, v91
	v_pk_mul_f32 v[4:5], v[122:123], v[94:95] op_sel_hi:[0,1]
	v_pk_mul_f32 v[88:89], v[122:123], v[88:89] op_sel_hi:[0,1]
	v_pk_fma_f32 v[90:91], v[96:97], v[4:5], v[98:99]
	v_pk_fma_f32 v[88:89], v[6:7], v[88:89], v[92:93]
	v_mov_b32_e32 v4, v90
	v_mov_b32_e32 v5, v88
	v_mov_b32_e32 v6, v91
	v_mov_b32_e32 v7, v89
	global_store_dwordx4 v[10:11], v[4:7], off nt
	s_waitcnt vmcnt(25)
	s_nop 1
	v_mov_b32_e32 v96, v234
	v_mov_b32_e32 v97, v235
	s_nop 0
	ds_read_b128 v[4:7], v150 offset:5120
	s_waitcnt vmcnt(26)
	s_nop 1
	v_mov_b32_e32 v92, v180
	v_mov_b32_e32 v93, v181
	v_mov_b32_e32 v94, v182
	v_mov_b32_e32 v95, v183
	v_addc_co_u32_e32 v125, vcc, 0, v9, vcc
	s_waitcnt lgkmcnt(0)
	v_lshlrev_b32_e32 v99, 16, v97
	v_lshlrev_b32_e32 v98, 16, v96
	v_and_b32_e32 v97, 0xffff0000, v97
	v_and_b32_e32 v96, 0xffff0000, v96
	s_waitcnt lgkmcnt(0)
	v_mov_b32_e32 v100, v4
	v_mov_b32_e32 v101, v6
	s_waitcnt lgkmcnt(0)
	v_mov_b32_e32 v102, v92
	v_mov_b32_e32 v103, v94
	v_mov_b32_e32 v6, v5
	v_mov_b32_e32 v94, v93
	v_pk_mul_f32 v[4:5], v[122:123], v[98:99] op_sel_hi:[0,1]
	v_pk_mul_f32 v[92:93], v[122:123], v[96:97] op_sel_hi:[0,1]
	v_pk_fma_f32 v[98:99], v[100:101], v[4:5], v[102:103]
	v_pk_fma_f32 v[94:95], v[6:7], v[92:93], v[94:95]
	v_mov_b32_e32 v4, v98
	v_mov_b32_e32 v5, v94
	v_mov_b32_e32 v6, v99
	v_mov_b32_e32 v7, v95
	global_store_dwordx4 v[10:11], v[4:7], off offset:1024 nt
	s_waitcnt vmcnt(24)
	s_nop 1
	v_mov_b32_e32 v92, v236
	v_mov_b32_e32 v93, v237
	s_nop 0
	s_waitcnt vmcnt(25)
	s_nop 1
	v_mov_b32_e32 v4, v184
	v_mov_b32_e32 v5, v185
	v_mov_b32_e32 v6, v186
	v_mov_b32_e32 v7, v187
	ds_read_b128 v[100:103], v150 offset:6144
	s_waitcnt lgkmcnt(0)
	v_lshlrev_b32_e32 v96, 16, v92
	v_and_b32_e32 v97, 0xffff0000, v92
	v_lshlrev_b32_e32 v92, 16, v93
	v_and_b32_e32 v93, 0xffff0000, v93
	v_pk_mul_f32 v[96:97], v[122:123], v[96:97] op_sel_hi:[0,1]
	v_pk_mul_f32 v[92:93], v[122:123], v[92:93] op_sel_hi:[0,1]
	s_waitcnt lgkmcnt(0)
	v_pk_fma_f32 v[4:5], v[100:101], v[96:97], v[4:5]
	v_pk_fma_f32 v[6:7], v[102:103], v[92:93], v[6:7]
	global_store_dwordx4 v[10:11], v[4:7], off offset:2048 nt
	s_waitcnt vmcnt(23)
	s_nop 1
	v_mov_b32_e32 v92, v238
	v_mov_b32_e32 v93, v239
	ds_read_b128 v[100:103], v150 offset:7168
	s_waitcnt vmcnt(24)
	s_nop 1
	v_mov_b32_e32 v106, v188
	v_mov_b32_e32 v107, v189
	v_mov_b32_e32 v108, v190
	v_mov_b32_e32 v109, v191
	s_waitcnt lgkmcnt(0)
	v_lshlrev_b32_e32 v14, 16, v92
	v_and_b32_e32 v92, 0xffff0000, v92
	v_lshlrev_b32_e32 v15, 16, v93
	v_and_b32_e32 v93, 0xffff0000, v93
	s_waitcnt lgkmcnt(0)
	v_mov_b32_e32 v96, v100
	v_mov_b32_e32 v97, v102
	s_waitcnt lgkmcnt(0)
	v_mov_b32_e32 v110, v106
	v_mov_b32_e32 v111, v108
	v_mov_b32_e32 v102, v101
	v_mov_b32_e32 v108, v107
	v_pk_mul_f32 v[14:15], v[122:123], v[14:15] op_sel_hi:[0,1]
	v_pk_mul_f32 v[92:93], v[122:123], v[92:93] op_sel_hi:[0,1]
	v_pk_fma_f32 v[96:97], v[96:97], v[14:15], v[110:111]
	v_pk_fma_f32 v[92:93], v[102:103], v[92:93], v[108:109]
	v_mov_b32_e32 v100, v96
	v_mov_b32_e32 v101, v92
	v_mov_b32_e32 v102, v97
	v_mov_b32_e32 v103, v93
	global_store_dwordx4 v[10:11], v[100:103], off offset:3072 nt
	s_waitcnt vmcnt(22)
	s_nop 1
	v_mov_b32_e32 v10, v240
	v_mov_b32_e32 v11, v241
	s_nop 0
	ds_read_b128 v[106:109], v150 offset:8192
	s_waitcnt vmcnt(23)
	s_nop 1
	v_mov_b32_e32 v110, v192
	v_mov_b32_e32 v111, v193
	v_mov_b32_e32 v112, v194
	v_mov_b32_e32 v113, v195
	s_waitcnt lgkmcnt(0)
	v_lshlrev_b32_e32 v15, 16, v11
	v_lshlrev_b32_e32 v14, 16, v10
	v_and_b32_e32 v11, 0xffff0000, v11
	v_and_b32_e32 v10, 0xffff0000, v10
	s_waitcnt lgkmcnt(0)
	v_mov_b32_e32 v100, v106
	v_mov_b32_e32 v101, v108
	s_waitcnt lgkmcnt(0)
	v_mov_b32_e32 v102, v110
	v_mov_b32_e32 v103, v112
	v_mov_b32_e32 v108, v107
	v_mov_b32_e32 v112, v111
	v_pk_mul_f32 v[14:15], v[122:123], v[14:15] op_sel_hi:[0,1]
	v_pk_mul_f32 v[10:11], v[122:123], v[10:11] op_sel_hi:[0,1]
	v_pk_fma_f32 v[102:103], v[100:101], v[14:15], v[102:103]
	v_pk_fma_f32 v[100:101], v[108:109], v[10:11], v[112:113]
	v_mov_b32_e32 v106, v102
	v_mov_b32_e32 v107, v100
	v_mov_b32_e32 v108, v103
	v_mov_b32_e32 v109, v101
	global_store_dwordx4 v[124:125], v[106:109], off offset:-4096 nt
	s_waitcnt vmcnt(21)
	s_nop 1
	v_mov_b32_e32 v10, v242
	v_mov_b32_e32 v11, v243
	s_nop 0
	ds_read_b128 v[106:109], v150 offset:9216
	s_waitcnt vmcnt(22)
	s_nop 1
	v_mov_b32_e32 v110, v196
	v_mov_b32_e32 v111, v197
	v_mov_b32_e32 v112, v198
	v_mov_b32_e32 v113, v199
	v_add_co_u32_e32 v14, vcc, s29, v8
	s_waitcnt lgkmcnt(0)
	v_lshlrev_b32_e32 v8, 16, v10
	v_addc_co_u32_e32 v15, vcc, 0, v9, vcc
	v_lshlrev_b32_e32 v9, 16, v11
	v_and_b32_e32 v11, 0xffff0000, v11
	v_and_b32_e32 v10, 0xffff0000, v10
	s_waitcnt lgkmcnt(0)
	v_mov_b32_e32 v114, v106
	v_mov_b32_e32 v115, v108
	s_waitcnt lgkmcnt(0)
	v_mov_b32_e32 v116, v110
	v_mov_b32_e32 v117, v112
	v_mov_b32_e32 v108, v107
	v_mov_b32_e32 v112, v111
	v_pk_mul_f32 v[8:9], v[122:123], v[8:9] op_sel_hi:[0,1]
	v_pk_mul_f32 v[10:11], v[122:123], v[10:11] op_sel_hi:[0,1]
	v_pk_fma_f32 v[110:111], v[114:115], v[8:9], v[116:117]
	v_pk_fma_f32 v[108:109], v[108:109], v[10:11], v[112:113]
	v_mov_b32_e32 v8, v110
	v_mov_b32_e32 v9, v108
	v_mov_b32_e32 v10, v111
	v_mov_b32_e32 v11, v109
	global_store_dwordx4 v[14:15], v[8:11], off offset:1024 nt
	s_waitcnt vmcnt(20)
	s_nop 1
	v_mov_b32_e32 v106, v244
	v_mov_b32_e32 v107, v245
	s_nop 0
	s_waitcnt vmcnt(21)
	s_nop 1
	v_mov_b32_e32 v8, v200
	v_mov_b32_e32 v9, v201
	v_mov_b32_e32 v10, v202
	v_mov_b32_e32 v11, v203
	ds_read_b128 v[112:115], v150 offset:10240
	v_add_co_u32_e32 v140, vcc, s25, v12
	s_waitcnt lgkmcnt(0)
	v_lshlrev_b32_e32 v116, 16, v106
	v_and_b32_e32 v117, 0xffff0000, v106
	v_lshlrev_b32_e32 v106, 16, v107
	v_and_b32_e32 v107, 0xffff0000, v107
	v_pk_mul_f32 v[116:117], v[122:123], v[116:117] op_sel_hi:[0,1]
	v_pk_mul_f32 v[106:107], v[122:123], v[106:107] op_sel_hi:[0,1]
	s_waitcnt lgkmcnt(0)
	v_pk_fma_f32 v[8:9], v[112:113], v[116:117], v[8:9]
	v_pk_fma_f32 v[10:11], v[114:115], v[106:107], v[10:11]
	global_store_dwordx4 v[14:15], v[8:11], off offset:2048 nt
	s_waitcnt vmcnt(19)
	s_nop 1
	v_mov_b32_e32 v106, v246
	v_mov_b32_e32 v107, v247
	ds_read_b128 v[112:115], v150 offset:11264
	s_waitcnt vmcnt(20)
	s_nop 1
	v_mov_b32_e32 v116, v204
	v_mov_b32_e32 v117, v205
	v_mov_b32_e32 v118, v206
	v_mov_b32_e32 v119, v207
	v_addc_co_u32_e32 v141, vcc, 0, v13, vcc
	s_andn2_b64 vcc, exec, s[4:5]
	s_waitcnt lgkmcnt(0)
	v_lshlrev_b32_e32 v104, 16, v106
	v_and_b32_e32 v106, 0xffff0000, v106
	v_lshlrev_b32_e32 v105, 16, v107
	v_and_b32_e32 v107, 0xffff0000, v107
	s_waitcnt lgkmcnt(0)
	v_mov_b32_e32 v136, v112
	v_mov_b32_e32 v137, v114
	s_waitcnt lgkmcnt(0)
	v_mov_b32_e32 v138, v116
	v_mov_b32_e32 v139, v118
	v_mov_b32_e32 v114, v113
	v_mov_b32_e32 v118, v117
	v_pk_mul_f32 v[104:105], v[122:123], v[104:105] op_sel_hi:[0,1]
	v_pk_mul_f32 v[112:113], v[122:123], v[106:107] op_sel_hi:[0,1]
	v_pk_fma_f32 v[106:107], v[136:137], v[104:105], v[138:139]
	v_pk_fma_f32 v[104:105], v[114:115], v[112:113], v[118:119]
	v_mov_b32_e32 v112, v106
	v_mov_b32_e32 v113, v104
	v_mov_b32_e32 v114, v107
	v_mov_b32_e32 v115, v105
	global_store_dwordx4 v[14:15], v[112:115], off offset:3072 nt
	s_waitcnt vmcnt(18)
	s_nop 1
	v_mov_b32_e32 v112, v248
	v_mov_b32_e32 v113, v249
	s_nop 0
	ds_read_b128 v[114:117], v150 offset:12288
	s_waitcnt vmcnt(19)
	s_nop 1
	v_mov_b32_e32 v12, v208
	v_mov_b32_e32 v13, v209
	v_mov_b32_e32 v14, v210
	v_mov_b32_e32 v15, v211
	s_waitcnt lgkmcnt(0)
	v_lshlrev_b32_e32 v119, 16, v113
	v_lshlrev_b32_e32 v118, 16, v112
	v_and_b32_e32 v113, 0xffff0000, v113
	v_and_b32_e32 v112, 0xffff0000, v112
	s_waitcnt lgkmcnt(0)
	v_mov_b32_e32 v136, v114
	v_mov_b32_e32 v137, v116
	s_waitcnt lgkmcnt(0)
	v_mov_b32_e32 v138, v12
	v_mov_b32_e32 v139, v14
	v_mov_b32_e32 v116, v115
	v_mov_b32_e32 v14, v13
	v_pk_mul_f32 v[12:13], v[122:123], v[118:119] op_sel_hi:[0,1]
	v_pk_mul_f32 v[112:113], v[122:123], v[112:113] op_sel_hi:[0,1]
	v_pk_fma_f32 v[114:115], v[136:137], v[12:13], v[138:139]
	v_pk_fma_f32 v[112:113], v[116:117], v[112:113], v[14:15]
	v_mov_b32_e32 v12, v114
	v_mov_b32_e32 v13, v112
	v_mov_b32_e32 v14, v115
	v_mov_b32_e32 v15, v113
	global_store_dwordx4 v[124:125], v[12:15], off nt
	s_waitcnt vmcnt(17)
	s_nop 1
	v_mov_b32_e32 v116, v250
	v_mov_b32_e32 v117, v251
	s_nop 0
	ds_read_b128 v[12:15], v150 offset:13312
	s_waitcnt vmcnt(18)
	s_nop 1
	v_mov_b32_e32 v136, v212
	v_mov_b32_e32 v137, v213
	v_mov_b32_e32 v138, v214
	v_mov_b32_e32 v139, v215
	s_waitcnt lgkmcnt(0)
	v_lshlrev_b32_e32 v119, 16, v117
	v_lshlrev_b32_e32 v118, 16, v116
	v_and_b32_e32 v117, 0xffff0000, v117
	v_and_b32_e32 v116, 0xffff0000, v116
	s_waitcnt lgkmcnt(0)
	v_mov_b32_e32 v142, v12
	v_mov_b32_e32 v143, v14
	s_waitcnt lgkmcnt(0)
	v_mov_b32_e32 v144, v136
	v_mov_b32_e32 v145, v138
	v_mov_b32_e32 v14, v13
	v_mov_b32_e32 v138, v137
	v_pk_mul_f32 v[12:13], v[122:123], v[118:119] op_sel_hi:[0,1]
	v_pk_mul_f32 v[116:117], v[122:123], v[116:117] op_sel_hi:[0,1]
	v_pk_fma_f32 v[118:119], v[142:143], v[12:13], v[144:145]
	v_pk_fma_f32 v[116:117], v[14:15], v[116:117], v[138:139]
	v_mov_b32_e32 v12, v118
	v_mov_b32_e32 v13, v116
	v_mov_b32_e32 v14, v119
	v_mov_b32_e32 v15, v117
	global_store_dwordx4 v[124:125], v[12:15], off offset:1024 nt
	s_waitcnt vmcnt(16)
	s_nop 1
	v_mov_b32_e32 v142, v252
	v_mov_b32_e32 v143, v253
	s_nop 0
	s_waitcnt vmcnt(17)
	s_nop 1
	v_mov_b32_e32 v12, v216
	v_mov_b32_e32 v13, v217
	v_mov_b32_e32 v14, v218
	v_mov_b32_e32 v15, v219
	ds_read_b128 v[136:139], v150 offset:14336
	s_waitcnt lgkmcnt(0)
	v_lshlrev_b32_e32 v144, 16, v142
	v_and_b32_e32 v145, 0xffff0000, v142
	v_lshlrev_b32_e32 v142, 16, v143
	v_and_b32_e32 v143, 0xffff0000, v143
	v_pk_mul_f32 v[144:145], v[122:123], v[144:145] op_sel_hi:[0,1]
	v_pk_mul_f32 v[142:143], v[122:123], v[142:143] op_sel_hi:[0,1]
	s_waitcnt lgkmcnt(0)
	v_pk_fma_f32 v[12:13], v[136:137], v[144:145], v[12:13]
	v_pk_fma_f32 v[14:15], v[138:139], v[142:143], v[14:15]
	global_store_dwordx4 v[124:125], v[12:15], off offset:2048 nt
	s_waitcnt vmcnt(15)
	s_nop 1
	v_mov_b32_e32 v120, v254
	v_mov_b32_e32 v121, v255
	s_nop 0
	ds_read_b128 v[136:139], v150 offset:15360
	s_nop 0
	s_waitcnt vmcnt(16)
	s_nop 1
	v_mov_b32_e32 v140, v220
	v_mov_b32_e32 v141, v221
	v_mov_b32_e32 v142, v222
	v_mov_b32_e32 v143, v223
	s_waitcnt lgkmcnt(0)
	v_lshlrev_b32_e32 v144, 16, v120
	v_and_b32_e32 v120, 0xffff0000, v120
	v_lshlrev_b32_e32 v145, 16, v121
	v_and_b32_e32 v121, 0xffff0000, v121
	s_waitcnt lgkmcnt(0)
	v_mov_b32_e32 v146, v136
	v_mov_b32_e32 v147, v138
	s_waitcnt lgkmcnt(0)
	v_mov_b32_e32 v148, v140
	v_mov_b32_e32 v149, v142
	v_mov_b32_e32 v138, v137
	v_mov_b32_e32 v142, v141
	v_pk_mul_f32 v[136:137], v[122:123], v[144:145] op_sel_hi:[0,1]
	v_pk_mul_f32 v[120:121], v[122:123], v[120:121] op_sel_hi:[0,1]
	v_pk_fma_f32 v[122:123], v[146:147], v[136:137], v[148:149]
	v_pk_fma_f32 v[120:121], v[138:139], v[120:121], v[142:143]
	v_mov_b32_e32 v136, v122
	v_mov_b32_e32 v137, v120
	v_mov_b32_e32 v138, v123
	v_mov_b32_e32 v139, v121
	global_store_dwordx4 v[124:125], v[136:139], off offset:3072 nt
	s_cbranch_vccnz .LBB0_1691
	v_mov_b32_e32 v124, v82
	v_mov_b32_e32 v125, v76
	v_mul_f32_e32 v136, v76, v76
	v_pk_fma_f32 v[124:125], v[124:125], v[124:125], v[136:137] op_sel_hi:[1,1,0]
	v_mov_b32_e32 v136, v83
	v_mov_b32_e32 v137, v77
	v_mul_f32_e32 v138, v77, v77
	v_pk_fma_f32 v[136:137], v[136:137], v[136:137], v[138:139] op_sel_hi:[1,1,0]
	v_pk_mul_f32 v[138:139], v[84:85], v[84:85]
	v_mul_f32_e32 v140, v1, v1
	v_pk_fma_f32 v[138:139], v[86:87], v[86:87], v[138:139]
	v_mul_f32_e32 v142, v3, v3
	v_pk_add_f32 v[138:139], v[138:139], v[138:139] op_sel:[0,1] op_sel_hi:[1,0]
	v_pk_fma_f32 v[140:141], v[0:1], v[0:1], v[140:141] op_sel_hi:[1,1,0]
	v_pk_fma_f32 v[142:143], v[2:3], v[2:3], v[142:143] op_sel_hi:[1,1,0]
	v_pk_mul_f32 v[144:145], v[78:79], v[78:79]
	v_pk_mul_f32 v[146:147], v[80:81], v[80:81]
	v_pk_add_f32 v[124:125], v[124:125], v[136:137]
	v_mov_b32_e32 v139, v144
	v_mov_b32_e32 v125, v146
	v_mov_b32_e32 v141, v147
	v_mov_b32_e32 v143, v145
	v_pk_add_f32 v[124:125], v[124:125], v[138:139]
	v_pk_add_f32 v[136:137], v[140:141], v[142:143]
	v_pk_mul_f32 v[138:139], v[94:95], v[94:95]
	v_pk_add_f32 v[124:125], v[124:125], v[136:137]
	v_pk_mul_f32 v[136:137], v[88:89], v[88:89]
	v_pk_add_f32 v[124:125], v[124:125], v[124:125] op_sel:[0,1] op_sel_hi:[1,0]
	v_pk_fma_f32 v[136:137], v[90:91], v[90:91], v[136:137]
	v_pk_fma_f32 v[138:139], v[98:99], v[98:99], v[138:139]
	v_pk_add_f32 v[136:137], v[136:137], v[136:137] op_sel:[0,1] op_sel_hi:[1,0]
	v_mul_f32_e32 v140, v5, v5
	v_mul_f32_e32 v142, v7, v7
	v_pk_add_f32 v[138:139], v[138:139], v[138:139] op_sel:[0,1] op_sel_hi:[1,0]
	v_pk_fma_f32 v[140:141], v[4:5], v[4:5], v[140:141] op_sel_hi:[1,1,0]
	v_pk_fma_f32 v[142:143], v[6:7], v[6:7], v[142:143] op_sel_hi:[1,1,0]
	v_pk_mul_f32 v[144:145], v[92:93], v[92:93]
	v_pk_mul_f32 v[146:147], v[96:97], v[96:97]
	v_pk_add_f32 v[124:125], v[124:125], v[136:137]
	v_mov_b32_e32 v139, v144
	v_mov_b32_e32 v125, v146
	v_mov_b32_e32 v141, v147
	v_mov_b32_e32 v143, v145
	v_pk_add_f32 v[124:125], v[124:125], v[138:139]
	v_pk_add_f32 v[136:137], v[140:141], v[142:143]
	v_pk_mul_f32 v[138:139], v[108:109], v[108:109]
	v_pk_add_f32 v[124:125], v[124:125], v[136:137]
	v_pk_mul_f32 v[136:137], v[100:101], v[100:101]
	v_pk_add_f32 v[124:125], v[124:125], v[124:125] op_sel:[0,1] op_sel_hi:[1,0]
	v_pk_fma_f32 v[136:137], v[102:103], v[102:103], v[136:137]
	v_pk_fma_f32 v[138:139], v[110:111], v[110:111], v[138:139]
	v_pk_add_f32 v[136:137], v[136:137], v[136:137] op_sel:[0,1] op_sel_hi:[1,0]
	v_mul_f32_e32 v140, v9, v9
	v_mul_f32_e32 v142, v11, v11
	v_pk_add_f32 v[138:139], v[138:139], v[138:139] op_sel:[0,1] op_sel_hi:[1,0]
	v_pk_fma_f32 v[140:141], v[8:9], v[8:9], v[140:141] op_sel_hi:[1,1,0]
	v_pk_fma_f32 v[142:143], v[10:11], v[10:11], v[142:143] op_sel_hi:[1,1,0]
	v_pk_mul_f32 v[144:145], v[104:105], v[104:105]
	v_pk_mul_f32 v[146:147], v[106:107], v[106:107]
	v_pk_add_f32 v[124:125], v[124:125], v[136:137]
	v_mov_b32_e32 v139, v144
	v_mov_b32_e32 v125, v146
	v_mov_b32_e32 v141, v147
	v_mov_b32_e32 v143, v145
	v_pk_add_f32 v[124:125], v[124:125], v[138:139]
	v_pk_add_f32 v[136:137], v[140:141], v[142:143]
	v_pk_mul_f32 v[138:139], v[116:117], v[116:117]
	v_pk_add_f32 v[124:125], v[124:125], v[136:137]
	v_pk_mul_f32 v[136:137], v[112:113], v[112:113]
	v_pk_add_f32 v[124:125], v[124:125], v[124:125] op_sel:[0,1] op_sel_hi:[1,0]
	v_pk_fma_f32 v[136:137], v[114:115], v[114:115], v[136:137]
	v_pk_fma_f32 v[138:139], v[118:119], v[118:119], v[138:139]
	v_pk_add_f32 v[136:137], v[136:137], v[136:137] op_sel:[0,1] op_sel_hi:[1,0]
	v_pk_add_f32 v[138:139], v[138:139], v[138:139] op_sel:[0,1] op_sel_hi:[1,0]
	v_pk_mul_f32 v[144:145], v[120:121], v[120:121]
	v_pk_mul_f32 v[146:147], v[122:123], v[122:123]
	v_pk_add_f32 v[124:125], v[124:125], v[136:137]
	v_mov_b32_e32 v139, v144
	v_mov_b32_e32 v125, v146
	v_pk_add_f32 v[124:125], v[124:125], v[138:139]
	ds_read_b128 v[136:139], v150 offset:16384
	v_mul_f32_e32 v140, v13, v13
	v_mul_f32_e32 v142, v15, v15
	v_pk_fma_f32 v[140:141], v[12:13], v[12:13], v[140:141] op_sel_hi:[1,1,0]
	v_pk_fma_f32 v[142:143], v[14:15], v[14:15], v[142:143] op_sel_hi:[1,1,0]
	v_mov_b32_e32 v141, v147
	v_mov_b32_e32 v143, v145
	v_pk_add_f32 v[140:141], v[140:141], v[142:143]
	s_nop 0
	v_pk_add_f32 v[124:125], v[124:125], v[140:141]
	s_nop 0
	v_add_f32_e32 v124, v124, v125
	ds_bpermute_b32 v125, v126, v124
	s_waitcnt lgkmcnt(0)
	v_add_f32_e32 v124, v124, v125
	ds_bpermute_b32 v125, v127, v124
	s_waitcnt lgkmcnt(0)
	v_add_f32_e32 v124, v124, v125
	ds_bpermute_b32 v125, v128, v124
	s_waitcnt lgkmcnt(0)
	v_add_f32_e32 v124, v124, v125
	ds_bpermute_b32 v125, v129, v124
	s_waitcnt lgkmcnt(0)
	v_add_f32_e32 v124, v124, v125
	ds_bpermute_b32 v125, v130, v124
	s_waitcnt lgkmcnt(0)
	v_add_f32_e32 v124, v124, v125
	ds_bpermute_b32 v125, v131, v124
	s_waitcnt lgkmcnt(0)
	v_add_f32_e32 v124, v124, v125
	v_fmamk_f32 v124, v124, 0x39800000, v132
	v_mul_f32_e32 v125, 0x4f800000, v124
	v_cmp_gt_f32_e32 vcc, s11, v124
	s_nop 1
	v_cndmask_b32_e32 v124, v124, v125, vcc
	v_sqrt_f32_e32 v125, v124
	s_nop 0
	v_add_u32_e32 v135, -1, v125
	v_fma_f32 v140, -v135, v125, v124
	v_cmp_ge_f32_e64 s[2:3], 0, v140
	v_add_u32_e32 v140, 1, v125
	s_nop 0
	v_cndmask_b32_e64 v135, v125, v135, s[2:3]
	v_fma_f32 v125, -v140, v125, v124
	v_cmp_lt_f32_e64 s[2:3], 0, v125
	s_nop 1
	v_cndmask_b32_e64 v125, v135, v140, s[2:3]
	v_mul_f32_e32 v135, 0x37800000, v125
	v_cndmask_b32_e32 v125, v125, v135, vcc
	v_cmp_class_f32_e32 vcc, v124, v133
	s_nop 1
	v_cndmask_b32_e32 v124, v125, v124, vcc
	v_div_scale_f32 v125, s[2:3], v124, v124, 1.0
	v_rcp_f32_e32 v135, v125
	s_nop 0
	v_fma_f32 v140, -v125, v135, 1.0
	v_fmac_f32_e32 v135, v140, v135
	v_div_scale_f32 v140, vcc, 1.0, v124, 1.0
	v_mul_f32_e32 v141, v140, v135
	v_fma_f32 v142, -v125, v141, v140
	v_fmac_f32_e32 v141, v142, v135
	v_fma_f32 v125, -v125, v141, v140
	v_div_fmas_f32 v125, v125, v135, v141
	v_div_fixup_f32 v124, v125, v124, 1.0
	v_pk_mul_f32 v[82:83], v[82:83], v[124:125] op_sel_hi:[1,0]
	s_waitcnt lgkmcnt(0)
	v_mov_b32_e32 v140, v136
	v_mov_b32_e32 v141, v138
	v_pk_mul_f32 v[82:83], v[140:141], v[82:83]
	v_pk_mul_f32 v[76:77], v[76:77], v[124:125] op_sel_hi:[1,0]
	v_mov_b32_e32 v138, v137
	v_pk_mul_f32 v[76:77], v[138:139], v[76:77]
	v_and_b32_sdwa v135, v82, v134 dst_sel:DWORD dst_unused:UNUSED_PAD src0_sel:WORD_1 src1_sel:DWORD
	v_and_b32_sdwa v125, v83, v134 dst_sel:DWORD dst_unused:UNUSED_PAD src0_sel:WORD_1 src1_sel:DWORD
	v_add3_u32 v82, v82, v135, s31
	v_and_b32_sdwa v135, v76, v134 dst_sel:DWORD dst_unused:UNUSED_PAD src0_sel:WORD_1 src1_sel:DWORD
	v_add3_u32 v83, v83, v125, s31
	v_and_b32_sdwa v125, v77, v134 dst_sel:DWORD dst_unused:UNUSED_PAD src0_sel:WORD_1 src1_sel:DWORD
	v_add3_u32 v76, v76, v135, s31
	v_add3_u32 v77, v77, v125, s31
	v_and_b32_e32 v76, 0xffff0000, v76
	v_and_b32_e32 v77, 0xffff0000, v77
	v_or_b32_sdwa v82, v76, v82 dst_sel:DWORD dst_unused:UNUSED_PAD src0_sel:DWORD src1_sel:WORD_1
	v_add_co_u32_e32 v76, vcc, s34, v74
	v_or_b32_sdwa v83, v77, v83 dst_sel:DWORD dst_unused:UNUSED_PAD src0_sel:DWORD src1_sel:WORD_1
	s_nop 0
	v_addc_co_u32_e32 v77, vcc, 0, v75, vcc
	global_store_dwordx2 v[76:77], v[82:83], off offset:-4096
	ds_read_b128 v[136:139], v150 offset:17408
	v_pk_mul_f32 v[82:83], v[86:87], v[124:125] op_sel_hi:[1,0]
	v_pk_mul_f32 v[84:85], v[84:85], v[124:125] op_sel_hi:[1,0]
	v_add_co_u32_e32 v74, vcc, s33, v74
	s_waitcnt lgkmcnt(0)
	v_mov_b32_e32 v87, v138
	v_mov_b32_e32 v138, v137
	v_mov_b32_e32 v86, v136
	v_pk_mul_f32 v[84:85], v[138:139], v[84:85]
	v_pk_mul_f32 v[82:83], v[86:87], v[82:83]
	v_and_b32_sdwa v125, v85, v134 dst_sel:DWORD dst_unused:UNUSED_PAD src0_sel:WORD_1 src1_sel:DWORD
	v_and_b32_sdwa v135, v84, v134 dst_sel:DWORD dst_unused:UNUSED_PAD src0_sel:WORD_1 src1_sel:DWORD
	v_and_b32_sdwa v86, v83, v134 dst_sel:DWORD dst_unused:UNUSED_PAD src0_sel:WORD_1 src1_sel:DWORD
	v_and_b32_sdwa v87, v82, v134 dst_sel:DWORD dst_unused:UNUSED_PAD src0_sel:WORD_1 src1_sel:DWORD
	v_add3_u32 v85, v85, v125, s31
	v_add3_u32 v84, v84, v135, s31
	v_add3_u32 v82, v82, v87, s31
	v_add3_u32 v83, v83, v86, s31
	v_and_b32_e32 v85, 0xffff0000, v85
	v_and_b32_e32 v84, 0xffff0000, v84
	v_addc_co_u32_e32 v75, vcc, 0, v75, vcc
	v_or_b32_sdwa v83, v85, v83 dst_sel:DWORD dst_unused:UNUSED_PAD src0_sel:DWORD src1_sel:WORD_1
	v_or_b32_sdwa v82, v84, v82 dst_sel:DWORD dst_unused:UNUSED_PAD src0_sel:DWORD src1_sel:WORD_1
	global_store_dwordx2 v[74:75], v[82:83], off offset:512
	ds_read_b128 v[82:85], v150 offset:18432
	v_mov_b32_e32 v86, v0
	v_mov_b32_e32 v87, v2
	v_mov_b32_e32 v2, v1
	v_pk_mul_f32 v[0:1], v[86:87], v[124:125] op_sel_hi:[1,0]
	v_pk_mul_f32 v[2:3], v[2:3], v[124:125] op_sel_hi:[1,0]
	v_pk_mul_f32 v[78:79], v[78:79], v[124:125] op_sel_hi:[1,0]
	v_pk_mul_f32 v[80:81], v[80:81], v[124:125] op_sel_hi:[1,0]
	s_waitcnt lgkmcnt(0)
	v_mov_b32_e32 v87, v84
	v_mov_b32_e32 v84, v83
	v_mov_b32_e32 v86, v82
	v_pk_mul_f32 v[2:3], v[84:85], v[2:3]
	v_pk_mul_f32 v[0:1], v[86:87], v[0:1]
	v_and_b32_sdwa v84, v3, v134 dst_sel:DWORD dst_unused:UNUSED_PAD src0_sel:WORD_1 src1_sel:DWORD
	v_and_b32_sdwa v85, v2, v134 dst_sel:DWORD dst_unused:UNUSED_PAD src0_sel:WORD_1 src1_sel:DWORD
	v_and_b32_sdwa v82, v1, v134 dst_sel:DWORD dst_unused:UNUSED_PAD src0_sel:WORD_1 src1_sel:DWORD
	v_and_b32_sdwa v83, v0, v134 dst_sel:DWORD dst_unused:UNUSED_PAD src0_sel:WORD_1 src1_sel:DWORD
	v_add3_u32 v3, v3, v84, s31
	v_add3_u32 v2, v2, v85, s31
	v_add3_u32 v0, v0, v83, s31
	v_add3_u32 v1, v1, v82, s31
	v_and_b32_e32 v3, 0xffff0000, v3
	v_and_b32_e32 v2, 0xffff0000, v2
	v_or_b32_sdwa v1, v3, v1 dst_sel:DWORD dst_unused:UNUSED_PAD src0_sel:DWORD src1_sel:WORD_1
	v_or_b32_sdwa v0, v2, v0 dst_sel:DWORD dst_unused:UNUSED_PAD src0_sel:DWORD src1_sel:WORD_1
	global_store_dwordx2 v[74:75], v[0:1], off offset:1024
	ds_read_b128 v[0:3], v150 offset:19456
	s_waitcnt lgkmcnt(0)
	v_mov_b32_e32 v83, v2
	v_mov_b32_e32 v2, v1
	v_mov_b32_e32 v82, v0
	v_pk_mul_f32 v[2:3], v[78:79], v[2:3]
	v_pk_mul_f32 v[0:1], v[80:81], v[82:83]
	v_and_b32_sdwa v80, v3, v134 dst_sel:DWORD dst_unused:UNUSED_PAD src0_sel:WORD_1 src1_sel:DWORD
	v_and_b32_sdwa v81, v2, v134 dst_sel:DWORD dst_unused:UNUSED_PAD src0_sel:WORD_1 src1_sel:DWORD
	v_and_b32_sdwa v78, v1, v134 dst_sel:DWORD dst_unused:UNUSED_PAD src0_sel:WORD_1 src1_sel:DWORD
	v_and_b32_sdwa v79, v0, v134 dst_sel:DWORD dst_unused:UNUSED_PAD src0_sel:WORD_1 src1_sel:DWORD
	v_add3_u32 v3, v3, v80, s31
	v_add3_u32 v2, v2, v81, s31
	v_add3_u32 v0, v0, v79, s31
	v_add3_u32 v1, v1, v78, s31
	v_and_b32_e32 v3, 0xffff0000, v3
	v_and_b32_e32 v2, 0xffff0000, v2
	v_or_b32_sdwa v1, v3, v1 dst_sel:DWORD dst_unused:UNUSED_PAD src0_sel:DWORD src1_sel:WORD_1
	v_or_b32_sdwa v0, v2, v0 dst_sel:DWORD dst_unused:UNUSED_PAD src0_sel:DWORD src1_sel:WORD_1
	global_store_dwordx2 v[74:75], v[0:1], off offset:1536
	ds_read_b128 v[0:3], v150 offset:20480
	v_pk_mul_f32 v[80:81], v[88:89], v[124:125] op_sel_hi:[1,0]
	v_pk_mul_f32 v[78:79], v[90:91], v[124:125] op_sel_hi:[1,0]
	s_waitcnt lgkmcnt(0)
	v_mov_b32_e32 v83, v2
	v_mov_b32_e32 v2, v1
	v_mov_b32_e32 v82, v0
	v_pk_mul_f32 v[2:3], v[80:81], v[2:3]
	v_pk_mul_f32 v[0:1], v[78:79], v[82:83]
	v_and_b32_sdwa v80, v3, v134 dst_sel:DWORD dst_unused:UNUSED_PAD src0_sel:WORD_1 src1_sel:DWORD
	v_and_b32_sdwa v81, v2, v134 dst_sel:DWORD dst_unused:UNUSED_PAD src0_sel:WORD_1 src1_sel:DWORD
	v_and_b32_sdwa v78, v1, v134 dst_sel:DWORD dst_unused:UNUSED_PAD src0_sel:WORD_1 src1_sel:DWORD
	v_and_b32_sdwa v79, v0, v134 dst_sel:DWORD dst_unused:UNUSED_PAD src0_sel:WORD_1 src1_sel:DWORD
	v_add3_u32 v3, v3, v80, s31
	v_add3_u32 v2, v2, v81, s31
	v_add3_u32 v0, v0, v79, s31
	v_add3_u32 v1, v1, v78, s31
	v_and_b32_e32 v3, 0xffff0000, v3
	v_and_b32_e32 v2, 0xffff0000, v2
	v_or_b32_sdwa v1, v3, v1 dst_sel:DWORD dst_unused:UNUSED_PAD src0_sel:DWORD src1_sel:WORD_1
	v_or_b32_sdwa v0, v2, v0 dst_sel:DWORD dst_unused:UNUSED_PAD src0_sel:DWORD src1_sel:WORD_1
	global_store_dwordx2 v[74:75], v[0:1], off offset:2048
	ds_read_b128 v[0:3], v150 offset:21504
	v_pk_mul_f32 v[80:81], v[94:95], v[124:125] op_sel_hi:[1,0]
	v_pk_mul_f32 v[78:79], v[98:99], v[124:125] op_sel_hi:[1,0]
	s_waitcnt lgkmcnt(0)
	v_mov_b32_e32 v83, v2
	v_mov_b32_e32 v2, v1
	v_mov_b32_e32 v82, v0
	v_pk_mul_f32 v[2:3], v[80:81], v[2:3]
	v_pk_mul_f32 v[0:1], v[78:79], v[82:83]
	v_and_b32_sdwa v80, v3, v134 dst_sel:DWORD dst_unused:UNUSED_PAD src0_sel:WORD_1 src1_sel:DWORD
	v_and_b32_sdwa v81, v2, v134 dst_sel:DWORD dst_unused:UNUSED_PAD src0_sel:WORD_1 src1_sel:DWORD
	v_and_b32_sdwa v78, v1, v134 dst_sel:DWORD dst_unused:UNUSED_PAD src0_sel:WORD_1 src1_sel:DWORD
	v_and_b32_sdwa v79, v0, v134 dst_sel:DWORD dst_unused:UNUSED_PAD src0_sel:WORD_1 src1_sel:DWORD
	v_add3_u32 v3, v3, v80, s31
	v_add3_u32 v2, v2, v81, s31
	v_add3_u32 v0, v0, v79, s31
	v_add3_u32 v1, v1, v78, s31
	v_and_b32_e32 v3, 0xffff0000, v3
	v_and_b32_e32 v2, 0xffff0000, v2
	v_or_b32_sdwa v1, v3, v1 dst_sel:DWORD dst_unused:UNUSED_PAD src0_sel:DWORD src1_sel:WORD_1
	v_or_b32_sdwa v0, v2, v0 dst_sel:DWORD dst_unused:UNUSED_PAD src0_sel:DWORD src1_sel:WORD_1
	global_store_dwordx2 v[74:75], v[0:1], off offset:2560
	ds_read_b128 v[0:3], v150 offset:22528
	v_mov_b32_e32 v78, v4
	v_mov_b32_e32 v79, v6
	v_mov_b32_e32 v6, v5
	v_pk_mul_f32 v[4:5], v[78:79], v[124:125] op_sel_hi:[1,0]
	v_pk_mul_f32 v[6:7], v[6:7], v[124:125] op_sel_hi:[1,0]
	s_waitcnt lgkmcnt(0)
	v_mov_b32_e32 v79, v2
	v_mov_b32_e32 v2, v1
	v_mov_b32_e32 v78, v0
	v_pk_mul_f32 v[2:3], v[6:7], v[2:3]
	v_pk_mul_f32 v[0:1], v[4:5], v[78:79]
	v_and_b32_sdwa v6, v3, v134 dst_sel:DWORD dst_unused:UNUSED_PAD src0_sel:WORD_1 src1_sel:DWORD
	v_and_b32_sdwa v7, v2, v134 dst_sel:DWORD dst_unused:UNUSED_PAD src0_sel:WORD_1 src1_sel:DWORD
	v_and_b32_sdwa v4, v1, v134 dst_sel:DWORD dst_unused:UNUSED_PAD src0_sel:WORD_1 src1_sel:DWORD
	v_and_b32_sdwa v5, v0, v134 dst_sel:DWORD dst_unused:UNUSED_PAD src0_sel:WORD_1 src1_sel:DWORD
	v_add3_u32 v3, v3, v6, s31
	v_add3_u32 v2, v2, v7, s31
	v_add3_u32 v0, v0, v5, s31
	v_add3_u32 v1, v1, v4, s31
	v_and_b32_e32 v3, 0xffff0000, v3
	v_and_b32_e32 v2, 0xffff0000, v2
	v_or_b32_sdwa v1, v3, v1 dst_sel:DWORD dst_unused:UNUSED_PAD src0_sel:DWORD src1_sel:WORD_1
	v_or_b32_sdwa v0, v2, v0 dst_sel:DWORD dst_unused:UNUSED_PAD src0_sel:DWORD src1_sel:WORD_1
	global_store_dwordx2 v[74:75], v[0:1], off offset:3072
	ds_read_b128 v[0:3], v150 offset:23552
	v_pk_mul_f32 v[6:7], v[92:93], v[124:125] op_sel_hi:[1,0]
	v_pk_mul_f32 v[4:5], v[96:97], v[124:125] op_sel_hi:[1,0]
	s_waitcnt lgkmcnt(0)
	v_mov_b32_e32 v79, v2
	v_mov_b32_e32 v2, v1
	v_mov_b32_e32 v78, v0
	v_pk_mul_f32 v[2:3], v[6:7], v[2:3]
	v_pk_mul_f32 v[0:1], v[4:5], v[78:79]
	v_and_b32_sdwa v6, v3, v134 dst_sel:DWORD dst_unused:UNUSED_PAD src0_sel:WORD_1 src1_sel:DWORD
	v_and_b32_sdwa v7, v2, v134 dst_sel:DWORD dst_unused:UNUSED_PAD src0_sel:WORD_1 src1_sel:DWORD
	v_and_b32_sdwa v4, v1, v134 dst_sel:DWORD dst_unused:UNUSED_PAD src0_sel:WORD_1 src1_sel:DWORD
	v_and_b32_sdwa v5, v0, v134 dst_sel:DWORD dst_unused:UNUSED_PAD src0_sel:WORD_1 src1_sel:DWORD
	v_add3_u32 v3, v3, v6, s31
	v_add3_u32 v2, v2, v7, s31
	v_add3_u32 v0, v0, v5, s31
	v_add3_u32 v1, v1, v4, s31
	v_and_b32_e32 v3, 0xffff0000, v3
	v_and_b32_e32 v2, 0xffff0000, v2
	v_or_b32_sdwa v1, v3, v1 dst_sel:DWORD dst_unused:UNUSED_PAD src0_sel:DWORD src1_sel:WORD_1
	v_or_b32_sdwa v0, v2, v0 dst_sel:DWORD dst_unused:UNUSED_PAD src0_sel:DWORD src1_sel:WORD_1
	global_store_dwordx2 v[74:75], v[0:1], off offset:3584
	ds_read_b128 v[0:3], v150 offset:24576
	v_pk_mul_f32 v[6:7], v[100:101], v[124:125] op_sel_hi:[1,0]
	v_pk_mul_f32 v[4:5], v[102:103], v[124:125] op_sel_hi:[1,0]
	s_waitcnt lgkmcnt(0)
	v_mov_b32_e32 v75, v2
	v_mov_b32_e32 v2, v1
	v_mov_b32_e32 v74, v0
	v_pk_mul_f32 v[2:3], v[6:7], v[2:3]
	v_pk_mul_f32 v[0:1], v[4:5], v[74:75]
	v_and_b32_sdwa v6, v3, v134 dst_sel:DWORD dst_unused:UNUSED_PAD src0_sel:WORD_1 src1_sel:DWORD
	v_and_b32_sdwa v7, v2, v134 dst_sel:DWORD dst_unused:UNUSED_PAD src0_sel:WORD_1 src1_sel:DWORD
	v_and_b32_sdwa v4, v1, v134 dst_sel:DWORD dst_unused:UNUSED_PAD src0_sel:WORD_1 src1_sel:DWORD
	v_and_b32_sdwa v5, v0, v134 dst_sel:DWORD dst_unused:UNUSED_PAD src0_sel:WORD_1 src1_sel:DWORD
	v_add3_u32 v3, v3, v6, s31
	v_add3_u32 v2, v2, v7, s31
	v_add3_u32 v0, v0, v5, s31
	v_add3_u32 v1, v1, v4, s31
	v_and_b32_e32 v3, 0xffff0000, v3
	v_and_b32_e32 v2, 0xffff0000, v2
	v_or_b32_sdwa v1, v3, v1 dst_sel:DWORD dst_unused:UNUSED_PAD src0_sel:DWORD src1_sel:WORD_1
	v_or_b32_sdwa v0, v2, v0 dst_sel:DWORD dst_unused:UNUSED_PAD src0_sel:DWORD src1_sel:WORD_1
	global_store_dwordx2 v[76:77], v[0:1], off
	ds_read_b128 v[0:3], v150 offset:25600
	v_pk_mul_f32 v[6:7], v[108:109], v[124:125] op_sel_hi:[1,0]
	v_pk_mul_f32 v[4:5], v[110:111], v[124:125] op_sel_hi:[1,0]
	s_waitcnt lgkmcnt(0)
	v_mov_b32_e32 v75, v2
	v_mov_b32_e32 v2, v1
	v_mov_b32_e32 v74, v0
	v_pk_mul_f32 v[2:3], v[6:7], v[2:3]
	v_pk_mul_f32 v[0:1], v[4:5], v[74:75]
	v_and_b32_sdwa v6, v3, v134 dst_sel:DWORD dst_unused:UNUSED_PAD src0_sel:WORD_1 src1_sel:DWORD
	v_and_b32_sdwa v7, v2, v134 dst_sel:DWORD dst_unused:UNUSED_PAD src0_sel:WORD_1 src1_sel:DWORD
	v_and_b32_sdwa v4, v1, v134 dst_sel:DWORD dst_unused:UNUSED_PAD src0_sel:WORD_1 src1_sel:DWORD
	v_and_b32_sdwa v5, v0, v134 dst_sel:DWORD dst_unused:UNUSED_PAD src0_sel:WORD_1 src1_sel:DWORD
	v_add3_u32 v3, v3, v6, s31
	v_add3_u32 v2, v2, v7, s31
	v_add3_u32 v0, v0, v5, s31
	v_add3_u32 v1, v1, v4, s31
	v_and_b32_e32 v3, 0xffff0000, v3
	v_and_b32_e32 v2, 0xffff0000, v2
	v_or_b32_sdwa v1, v3, v1 dst_sel:DWORD dst_unused:UNUSED_PAD src0_sel:DWORD src1_sel:WORD_1
	v_or_b32_sdwa v0, v2, v0 dst_sel:DWORD dst_unused:UNUSED_PAD src0_sel:DWORD src1_sel:WORD_1
	global_store_dwordx2 v[76:77], v[0:1], off offset:512
	ds_read_b128 v[0:3], v150 offset:26624
	v_mov_b32_e32 v5, v10
	v_mov_b32_e32 v10, v9
	v_mov_b32_e32 v4, v8
	v_pk_mul_f32 v[6:7], v[10:11], v[124:125] op_sel_hi:[1,0]
	v_pk_mul_f32 v[4:5], v[4:5], v[124:125] op_sel_hi:[1,0]
	s_waitcnt lgkmcnt(0)
	v_mov_b32_e32 v9, v2
	v_mov_b32_e32 v2, v1
	v_mov_b32_e32 v8, v0
	v_pk_mul_f32 v[2:3], v[6:7], v[2:3]
	v_pk_mul_f32 v[0:1], v[4:5], v[8:9]
	v_and_b32_sdwa v6, v3, v134 dst_sel:DWORD dst_unused:UNUSED_PAD src0_sel:WORD_1 src1_sel:DWORD
	v_and_b32_sdwa v7, v2, v134 dst_sel:DWORD dst_unused:UNUSED_PAD src0_sel:WORD_1 src1_sel:DWORD
	v_and_b32_sdwa v4, v1, v134 dst_sel:DWORD dst_unused:UNUSED_PAD src0_sel:WORD_1 src1_sel:DWORD
	v_and_b32_sdwa v5, v0, v134 dst_sel:DWORD dst_unused:UNUSED_PAD src0_sel:WORD_1 src1_sel:DWORD
	v_add3_u32 v3, v3, v6, s31
	v_add3_u32 v2, v2, v7, s31
	v_add3_u32 v0, v0, v5, s31
	v_add3_u32 v1, v1, v4, s31
	v_and_b32_e32 v3, 0xffff0000, v3
	v_and_b32_e32 v2, 0xffff0000, v2
	v_or_b32_sdwa v1, v3, v1 dst_sel:DWORD dst_unused:UNUSED_PAD src0_sel:DWORD src1_sel:WORD_1
	v_or_b32_sdwa v0, v2, v0 dst_sel:DWORD dst_unused:UNUSED_PAD src0_sel:DWORD src1_sel:WORD_1
	global_store_dwordx2 v[76:77], v[0:1], off offset:1024
	ds_read_b128 v[0:3], v150 offset:27648
	v_pk_mul_f32 v[6:7], v[104:105], v[124:125] op_sel_hi:[1,0]
	v_pk_mul_f32 v[4:5], v[106:107], v[124:125] op_sel_hi:[1,0]
	s_waitcnt lgkmcnt(0)
	v_mov_b32_e32 v9, v2
	v_mov_b32_e32 v2, v1
	v_mov_b32_e32 v8, v0
	v_pk_mul_f32 v[2:3], v[6:7], v[2:3]
	v_pk_mul_f32 v[0:1], v[4:5], v[8:9]
	v_and_b32_sdwa v6, v3, v134 dst_sel:DWORD dst_unused:UNUSED_PAD src0_sel:WORD_1 src1_sel:DWORD
	v_and_b32_sdwa v7, v2, v134 dst_sel:DWORD dst_unused:UNUSED_PAD src0_sel:WORD_1 src1_sel:DWORD
	v_and_b32_sdwa v4, v1, v134 dst_sel:DWORD dst_unused:UNUSED_PAD src0_sel:WORD_1 src1_sel:DWORD
	v_and_b32_sdwa v5, v0, v134 dst_sel:DWORD dst_unused:UNUSED_PAD src0_sel:WORD_1 src1_sel:DWORD
	v_add3_u32 v3, v3, v6, s31
	v_add3_u32 v2, v2, v7, s31
	v_add3_u32 v0, v0, v5, s31
	v_add3_u32 v1, v1, v4, s31
	v_and_b32_e32 v3, 0xffff0000, v3
	v_and_b32_e32 v2, 0xffff0000, v2
	v_or_b32_sdwa v1, v3, v1 dst_sel:DWORD dst_unused:UNUSED_PAD src0_sel:DWORD src1_sel:WORD_1
	v_or_b32_sdwa v0, v2, v0 dst_sel:DWORD dst_unused:UNUSED_PAD src0_sel:DWORD src1_sel:WORD_1
	global_store_dwordx2 v[76:77], v[0:1], off offset:1536
	ds_read_b128 v[0:3], v150 offset:28672
	v_pk_mul_f32 v[6:7], v[112:113], v[124:125] op_sel_hi:[1,0]
	v_pk_mul_f32 v[4:5], v[114:115], v[124:125] op_sel_hi:[1,0]
	s_waitcnt lgkmcnt(0)
	v_mov_b32_e32 v9, v2
	v_mov_b32_e32 v2, v1
	v_mov_b32_e32 v8, v0
	v_pk_mul_f32 v[2:3], v[6:7], v[2:3]
	v_pk_mul_f32 v[0:1], v[4:5], v[8:9]
	v_and_b32_sdwa v6, v3, v134 dst_sel:DWORD dst_unused:UNUSED_PAD src0_sel:WORD_1 src1_sel:DWORD
	v_and_b32_sdwa v7, v2, v134 dst_sel:DWORD dst_unused:UNUSED_PAD src0_sel:WORD_1 src1_sel:DWORD
	v_and_b32_sdwa v4, v1, v134 dst_sel:DWORD dst_unused:UNUSED_PAD src0_sel:WORD_1 src1_sel:DWORD
	v_and_b32_sdwa v5, v0, v134 dst_sel:DWORD dst_unused:UNUSED_PAD src0_sel:WORD_1 src1_sel:DWORD
	v_add3_u32 v3, v3, v6, s31
	v_add3_u32 v2, v2, v7, s31
	v_add3_u32 v0, v0, v5, s31
	v_add3_u32 v1, v1, v4, s31
	v_and_b32_e32 v3, 0xffff0000, v3
	v_and_b32_e32 v2, 0xffff0000, v2
	v_or_b32_sdwa v1, v3, v1 dst_sel:DWORD dst_unused:UNUSED_PAD src0_sel:DWORD src1_sel:WORD_1
	v_or_b32_sdwa v0, v2, v0 dst_sel:DWORD dst_unused:UNUSED_PAD src0_sel:DWORD src1_sel:WORD_1
	global_store_dwordx2 v[76:77], v[0:1], off offset:2048
	ds_read_b128 v[0:3], v150 offset:29696
	v_pk_mul_f32 v[6:7], v[116:117], v[124:125] op_sel_hi:[1,0]
	v_pk_mul_f32 v[4:5], v[118:119], v[124:125] op_sel_hi:[1,0]
	s_waitcnt lgkmcnt(0)
	v_mov_b32_e32 v9, v2
	v_mov_b32_e32 v2, v1
	v_mov_b32_e32 v8, v0
	v_pk_mul_f32 v[2:3], v[6:7], v[2:3]
	v_pk_mul_f32 v[0:1], v[4:5], v[8:9]
	v_and_b32_sdwa v6, v3, v134 dst_sel:DWORD dst_unused:UNUSED_PAD src0_sel:WORD_1 src1_sel:DWORD
	v_and_b32_sdwa v7, v2, v134 dst_sel:DWORD dst_unused:UNUSED_PAD src0_sel:WORD_1 src1_sel:DWORD
	v_and_b32_sdwa v4, v1, v134 dst_sel:DWORD dst_unused:UNUSED_PAD src0_sel:WORD_1 src1_sel:DWORD
	v_and_b32_sdwa v5, v0, v134 dst_sel:DWORD dst_unused:UNUSED_PAD src0_sel:WORD_1 src1_sel:DWORD
	v_add3_u32 v3, v3, v6, s31
	v_add3_u32 v2, v2, v7, s31
	v_add3_u32 v0, v0, v5, s31
	v_add3_u32 v1, v1, v4, s31
	v_and_b32_e32 v3, 0xffff0000, v3
	v_and_b32_e32 v2, 0xffff0000, v2
	v_or_b32_sdwa v1, v3, v1 dst_sel:DWORD dst_unused:UNUSED_PAD src0_sel:DWORD src1_sel:WORD_1
	v_or_b32_sdwa v0, v2, v0 dst_sel:DWORD dst_unused:UNUSED_PAD src0_sel:DWORD src1_sel:WORD_1
	global_store_dwordx2 v[76:77], v[0:1], off offset:2560
	ds_read_b128 v[0:3], v150 offset:30720
	v_mov_b32_e32 v5, v14
	v_mov_b32_e32 v14, v13
	v_mov_b32_e32 v4, v12
	v_pk_mul_f32 v[6:7], v[14:15], v[124:125] op_sel_hi:[1,0]
	v_pk_mul_f32 v[4:5], v[4:5], v[124:125] op_sel_hi:[1,0]
	s_waitcnt lgkmcnt(0)
	v_mov_b32_e32 v9, v2
	v_mov_b32_e32 v2, v1
	v_mov_b32_e32 v8, v0
	v_pk_mul_f32 v[2:3], v[6:7], v[2:3]
	v_pk_mul_f32 v[0:1], v[4:5], v[8:9]
	v_and_b32_sdwa v6, v3, v134 dst_sel:DWORD dst_unused:UNUSED_PAD src0_sel:WORD_1 src1_sel:DWORD
	v_and_b32_sdwa v7, v2, v134 dst_sel:DWORD dst_unused:UNUSED_PAD src0_sel:WORD_1 src1_sel:DWORD
	v_and_b32_sdwa v4, v1, v134 dst_sel:DWORD dst_unused:UNUSED_PAD src0_sel:WORD_1 src1_sel:DWORD
	v_and_b32_sdwa v5, v0, v134 dst_sel:DWORD dst_unused:UNUSED_PAD src0_sel:WORD_1 src1_sel:DWORD
	v_add3_u32 v3, v3, v6, s31
	v_add3_u32 v2, v2, v7, s31
	v_add3_u32 v0, v0, v5, s31
	v_add3_u32 v1, v1, v4, s31
	v_and_b32_e32 v3, 0xffff0000, v3
	v_and_b32_e32 v2, 0xffff0000, v2
	v_or_b32_sdwa v1, v3, v1 dst_sel:DWORD dst_unused:UNUSED_PAD src0_sel:DWORD src1_sel:WORD_1
	v_or_b32_sdwa v0, v2, v0 dst_sel:DWORD dst_unused:UNUSED_PAD src0_sel:DWORD src1_sel:WORD_1
	global_store_dwordx2 v[76:77], v[0:1], off offset:3072
	ds_read_b128 v[0:3], v150 offset:31744
	v_pk_mul_f32 v[6:7], v[120:121], v[124:125] op_sel_hi:[1,0]
	v_pk_mul_f32 v[4:5], v[122:123], v[124:125] op_sel_hi:[1,0]
	s_waitcnt lgkmcnt(0)
	v_mov_b32_e32 v9, v2
	v_mov_b32_e32 v2, v1
	v_mov_b32_e32 v8, v0
	v_pk_mul_f32 v[2:3], v[6:7], v[2:3]
	v_pk_mul_f32 v[0:1], v[4:5], v[8:9]
	v_and_b32_sdwa v6, v3, v134 dst_sel:DWORD dst_unused:UNUSED_PAD src0_sel:WORD_1 src1_sel:DWORD
	v_and_b32_sdwa v7, v2, v134 dst_sel:DWORD dst_unused:UNUSED_PAD src0_sel:WORD_1 src1_sel:DWORD
	v_and_b32_sdwa v4, v1, v134 dst_sel:DWORD dst_unused:UNUSED_PAD src0_sel:WORD_1 src1_sel:DWORD
	v_and_b32_sdwa v5, v0, v134 dst_sel:DWORD dst_unused:UNUSED_PAD src0_sel:WORD_1 src1_sel:DWORD
	v_add3_u32 v3, v3, v6, s31
	v_add3_u32 v2, v2, v7, s31
	v_add3_u32 v0, v0, v5, s31
	v_add3_u32 v1, v1, v4, s31
	v_and_b32_e32 v3, 0xffff0000, v3
	v_and_b32_e32 v2, 0xffff0000, v2
	v_or_b32_sdwa v1, v3, v1 dst_sel:DWORD dst_unused:UNUSED_PAD src0_sel:DWORD src1_sel:WORD_1
	v_or_b32_sdwa v0, v2, v0 dst_sel:DWORD dst_unused:UNUSED_PAD src0_sel:DWORD src1_sel:WORD_1
	global_store_dwordx2 v[76:77], v[0:1], off offset:3584
	s_branch .LBB0_1691

.LBB0_2076:
	s_waitcnt lgkmcnt(0)
	v_lshl_add_u64 v[6:7], s[14:15], 0, v[108:109]
	v_add_co_u32_e32 v28, vcc, s13, v6
	v_lshl_add_u64 v[8:9], s[14:15], 0, v[110:111]
	s_nop 0
	v_addc_co_u32_e32 v29, vcc, 0, v7, vcc
	v_add_co_u32_e32 v16, vcc, s25, v6
	v_lshl_add_u64 v[18:19], s[6:7], 0, v[110:111]
	s_nop 0
	v_addc_co_u32_e32 v17, vcc, 0, v7, vcc
	v_add_co_u32_e32 v12, vcc, s23, v8
	v_lshl_add_u64 v[4:5], s[14:15], 0, v[106:107]
	global_load_dword v14, v[4:5], off
	global_load_dwordx4 v[160:163], v110, s[80:81] offset:0 nt
	global_load_dwordx2 v[224:225], v108, s[88:89] offset:0
	global_load_dwordx4 v[164:167], v110, s[80:81] offset:1024 nt
	global_load_dwordx2 v[226:227], v108, s[88:89] offset:512
	global_load_dwordx4 v[168:171], v110, s[80:81] offset:2048 nt
	global_load_dwordx2 v[228:229], v108, s[88:89] offset:1024
	global_load_dwordx4 v[172:175], v110, s[80:81] offset:3072 nt
	global_load_dwordx2 v[230:231], v108, s[88:89] offset:1536
	global_load_dwordx4 v[176:179], v110, s[82:83] offset:0 nt
	global_load_dwordx2 v[232:233], v108, s[88:89] offset:2048
	global_load_dwordx4 v[180:183], v110, s[82:83] offset:1024 nt
	global_load_dwordx2 v[234:235], v108, s[88:89] offset:2560
	global_load_dwordx4 v[184:187], v110, s[82:83] offset:2048 nt
	global_load_dwordx2 v[236:237], v108, s[88:89] offset:3072
	global_load_dwordx4 v[188:191], v110, s[82:83] offset:3072 nt
	global_load_dwordx2 v[238:239], v108, s[88:89] offset:3584
	global_load_dwordx4 v[192:195], v110, s[84:85] offset:0 nt
	global_load_dwordx2 v[240:241], v108, s[90:91] offset:0
	global_load_dwordx4 v[196:199], v110, s[84:85] offset:1024 nt
	global_load_dwordx2 v[242:243], v108, s[90:91] offset:512
	global_load_dwordx4 v[200:203], v110, s[84:85] offset:2048 nt
	global_load_dwordx2 v[244:245], v108, s[90:91] offset:1024
	global_load_dwordx4 v[204:207], v110, s[84:85] offset:3072 nt
	global_load_dwordx2 v[246:247], v108, s[90:91] offset:1536
	global_load_dwordx4 v[208:211], v110, s[86:87] offset:0 nt
	global_load_dwordx2 v[248:249], v108, s[90:91] offset:2048
	global_load_dwordx4 v[212:215], v110, s[86:87] offset:1024 nt
	global_load_dwordx2 v[250:251], v108, s[90:91] offset:2560
	global_load_dwordx4 v[216:219], v110, s[86:87] offset:2048 nt
	global_load_dwordx2 v[252:253], v108, s[90:91] offset:3072
	global_load_dwordx4 v[220:223], v110, s[86:87] offset:3072 nt
	global_load_dwordx2 v[254:255], v108, s[90:91] offset:3584
	s_nop 0
	v_addc_co_u32_e32 v13, vcc, 0, v9, vcc
	v_add_co_u32_e32 v30, vcc, s24, v8
	ds_read_b128 v[0:3], v154 offset:0
	s_nop 0
	v_addc_co_u32_e32 v31, vcc, 0, v9, vcc
	v_add_co_u32_e32 v34, vcc, s20, v18
	s_add_i32 s12, s12, s10
	s_nop 0
	v_addc_co_u32_e32 v35, vcc, 0, v19, vcc
	v_add_co_u32_e32 v22, vcc, s21, v18
	v_lshl_add_u64 v[106:107], v[106:107], 0, s[4:5]
	s_nop 0
	v_addc_co_u32_e32 v23, vcc, 0, v19, vcc
	v_add_co_u32_e32 v32, vcc, s27, v8
	v_lshl_add_u64 v[108:109], v[108:109], 0, s[16:17]
	s_nop 0
	v_addc_co_u32_e32 v33, vcc, 0, v9, vcc
	v_add_co_u32_e32 v114, vcc, s28, v8
	v_lshl_add_u64 v[110:111], v[110:111], 0, s[18:19]
	s_nop 0
	v_addc_co_u32_e32 v115, vcc, 0, v9, vcc
	v_add_co_u32_e32 v116, vcc, s22, v18
	s_cmpk_gt_i32 s12, 0x3fff
	s_nop 0
	v_addc_co_u32_e32 v117, vcc, 0, v19, vcc
	v_add_co_u32_e32 v118, vcc, s30, v6
	s_nop 1
	v_addc_co_u32_e32 v119, vcc, 0, v7, vcc
	v_add_co_u32_e32 v112, vcc, s31, v6
	s_nop 1
	v_addc_co_u32_e32 v113, vcc, 0, v7, vcc
	s_waitcnt vmcnt(30)
	s_nop 1
	v_mov_b32_e32 v10, v224
	v_mov_b32_e32 v11, v225
	s_waitcnt vmcnt(31)
	s_nop 1
	v_mov_b32_e32 v6, v160
	v_mov_b32_e32 v7, v161
	v_mov_b32_e32 v8, v162
	v_mov_b32_e32 v9, v163
	s_waitcnt vmcnt(32) lgkmcnt(0)
	ds_bpermute_b32 v15, v123, v14
	s_waitcnt lgkmcnt(0)
	v_lshlrev_b32_e32 v4, 16, v10
	v_and_b32_e32 v5, 0xffff0000, v10
	v_lshlrev_b32_e32 v10, 16, v11
	v_and_b32_e32 v11, 0xffff0000, v11
	s_waitcnt lgkmcnt(0)
	v_add_f32_e32 v14, v14, v15
	ds_bpermute_b32 v15, v132, v14
	s_waitcnt lgkmcnt(0)
	v_add_f32_e32 v14, v14, v15
	ds_bpermute_b32 v15, v133, v14
	s_waitcnt lgkmcnt(0)
	v_add_f32_e32 v14, v14, v15
	ds_bpermute_b32 v15, v134, v14
	s_waitcnt lgkmcnt(0)
	v_add_f32_e32 v14, v14, v15
	ds_bpermute_b32 v15, v135, v14
	s_waitcnt lgkmcnt(0)
	v_add_f32_e32 v14, v14, v15
	ds_bpermute_b32 v15, v136, v14
	s_waitcnt lgkmcnt(0)
	v_add_f32_e32 v14, v14, v15
	v_fmamk_f32 v14, v14, 0x39800000, v137
	v_mul_f32_e32 v15, 0x4f800000, v14
	v_cmp_gt_f32_e32 vcc, s11, v14
	s_nop 1
	v_cndmask_b32_e32 v14, v14, v15, vcc
	v_sqrt_f32_e32 v15, v14
	s_nop 0
	v_add_u32_e32 v20, -1, v15
	v_add_u32_e32 v21, 1, v15
	v_fma_f32 v24, -v20, v15, v14
	v_fma_f32 v25, -v21, v15, v14
	v_cmp_ge_f32_e64 s[2:3], 0, v24
	s_nop 1
	v_cndmask_b32_e64 v15, v15, v20, s[2:3]
	v_cmp_lt_f32_e64 s[2:3], 0, v25
	s_nop 1
	v_cndmask_b32_e64 v15, v15, v21, s[2:3]
	v_mul_f32_e32 v20, 0x37800000, v15
	v_cndmask_b32_e32 v15, v15, v20, vcc
	v_cmp_class_f32_e32 vcc, v14, v138
	s_nop 1
	v_cndmask_b32_e32 v14, v15, v14, vcc
	v_div_scale_f32 v15, s[2:3], v14, v14, 1.0
	v_rcp_f32_e32 v21, v15
	v_div_scale_f32 v20, vcc, 1.0, v14, 1.0
	v_fma_f32 v24, -v15, v21, 1.0
	v_fmac_f32_e32 v21, v24, v21
	v_mul_f32_e32 v24, v20, v21
	v_fma_f32 v25, -v15, v24, v20
	v_fmac_f32_e32 v24, v25, v21
	v_fma_f32 v15, -v15, v24, v20
	v_div_fmas_f32 v15, v15, v21, v24
	v_div_fixup_f32 v122, v15, v14, 1.0
	v_pk_mul_f32 v[4:5], v[122:123], v[4:5] op_sel_hi:[0,1]
	v_pk_mul_f32 v[10:11], v[122:123], v[10:11] op_sel_hi:[0,1]
	s_waitcnt lgkmcnt(0)
	v_pk_fma_f32 v[0:1], v[0:1], v[4:5], v[6:7]
	v_pk_fma_f32 v[2:3], v[2:3], v[10:11], v[8:9]
	global_store_dwordx4 v[18:19], v[0:3], off nt
	v_mov_b32_e32 v120, v0
	v_mov_b32_e32 v121, v2
	v_mov_b32_e32 v2, v1
	s_waitcnt vmcnt(29)
	s_nop 1
	v_mov_b32_e32 v0, v226
	v_mov_b32_e32 v1, v227
	s_waitcnt vmcnt(30)
	s_nop 1
	v_mov_b32_e32 v4, v164
	v_mov_b32_e32 v5, v165
	v_mov_b32_e32 v6, v166
	v_mov_b32_e32 v7, v167
	ds_read_b128 v[8:11], v154 offset:1024
	v_pk_mul_f32 v[14:15], v[2:3], v[2:3]
	s_nop 0
	v_pk_fma_f32 v[14:15], v[120:121], v[120:121], v[14:15]
	s_nop 0
	v_pk_add_f32 v[40:41], v[14:15], v[14:15] op_sel:[0,1] op_sel_hi:[1,0]
	s_waitcnt lgkmcnt(0)
	v_lshlrev_b32_e32 v14, 16, v0
	v_and_b32_e32 v15, 0xffff0000, v0
	v_lshlrev_b32_e32 v0, 16, v1
	v_and_b32_e32 v1, 0xffff0000, v1
	v_pk_mul_f32 v[14:15], v[122:123], v[14:15] op_sel_hi:[0,1]
	v_pk_mul_f32 v[0:1], v[122:123], v[0:1] op_sel_hi:[0,1]
	s_waitcnt lgkmcnt(0)
	v_pk_fma_f32 v[4:5], v[8:9], v[14:15], v[4:5]
	v_pk_fma_f32 v[6:7], v[10:11], v[0:1], v[6:7]
	global_store_dwordx4 v[18:19], v[4:7], off offset:1024 nt
	v_mov_b32_e32 v0, v4
	v_mov_b32_e32 v1, v6
	v_mov_b32_e32 v6, v5
	s_waitcnt vmcnt(28)
	s_nop 1
	v_mov_b32_e32 v4, v228
	v_mov_b32_e32 v5, v229
	s_waitcnt vmcnt(29)
	s_nop 1
	v_mov_b32_e32 v8, v168
	v_mov_b32_e32 v9, v169
	v_mov_b32_e32 v10, v170
	v_mov_b32_e32 v11, v171
	ds_read_b128 v[24:27], v154 offset:2048
	v_pk_mul_f32 v[14:15], v[6:7], v[6:7]
	s_nop 0
	v_pk_fma_f32 v[14:15], v[0:1], v[0:1], v[14:15]
	s_nop 0
	v_pk_add_f32 v[42:43], v[14:15], v[14:15] op_sel:[0,1] op_sel_hi:[1,0]
	s_waitcnt lgkmcnt(0)
	v_lshlrev_b32_e32 v14, 16, v4
	v_and_b32_e32 v15, 0xffff0000, v4
	v_lshlrev_b32_e32 v4, 16, v5
	v_and_b32_e32 v5, 0xffff0000, v5
	v_pk_mul_f32 v[14:15], v[122:123], v[14:15] op_sel_hi:[0,1]
	v_pk_mul_f32 v[4:5], v[122:123], v[4:5] op_sel_hi:[0,1]
	s_waitcnt lgkmcnt(0)
	v_pk_fma_f32 v[8:9], v[24:25], v[14:15], v[8:9]
	v_pk_fma_f32 v[10:11], v[26:27], v[4:5], v[10:11]
	global_store_dwordx4 v[18:19], v[8:11], off offset:2048 nt
	s_waitcnt vmcnt(27)
	s_nop 1
	v_mov_b32_e32 v44, v230
	v_mov_b32_e32 v45, v231
	s_waitcnt vmcnt(28)
	s_nop 1
	v_mov_b32_e32 v24, v172
	v_mov_b32_e32 v25, v173
	v_mov_b32_e32 v26, v174
	v_mov_b32_e32 v27, v175
	ds_read_b128 v[36:39], v154 offset:3072
	v_mul_f32_e32 v14, v9, v9
	v_mul_f32_e32 v20, v11, v11
	v_mov_b32_e32 v4, v8
	v_mov_b32_e32 v5, v10
	v_pk_fma_f32 v[46:47], v[8:9], v[8:9], v[14:15] op_sel_hi:[1,1,0]
	v_pk_fma_f32 v[48:49], v[10:11], v[10:11], v[20:21] op_sel_hi:[1,1,0]
	v_mov_b32_e32 v10, v9
	s_waitcnt lgkmcnt(0)
	v_lshlrev_b32_e32 v8, 16, v44
	v_and_b32_e32 v9, 0xffff0000, v44
	v_lshlrev_b32_e32 v12, 16, v45
	v_and_b32_e32 v13, 0xffff0000, v45
	v_pk_mul_f32 v[8:9], v[122:123], v[8:9] op_sel_hi:[0,1]
	v_pk_mul_f32 v[14:15], v[122:123], v[12:13] op_sel_hi:[0,1]
	s_waitcnt lgkmcnt(0)
	v_pk_fma_f32 v[12:13], v[36:37], v[8:9], v[24:25]
	v_pk_fma_f32 v[14:15], v[38:39], v[14:15], v[26:27]
	global_store_dwordx4 v[18:19], v[12:15], off offset:3072 nt
	v_pk_mul_f32 v[36:37], v[12:13], v[12:13]
	v_pk_mul_f32 v[38:39], v[14:15], v[14:15]
	v_mov_b32_e32 v8, v12
	v_mov_b32_e32 v9, v14
	v_mov_b32_e32 v14, v13
	s_waitcnt vmcnt(26)
	s_nop 1
	v_mov_b32_e32 v12, v232
	v_mov_b32_e32 v13, v233
	s_waitcnt vmcnt(27)
	s_nop 1
	v_mov_b32_e32 v18, v176
	v_mov_b32_e32 v19, v177
	v_mov_b32_e32 v20, v178
	v_mov_b32_e32 v21, v179
	ds_read_b128 v[24:27], v154 offset:4096
	v_mov_b32_e32 v41, v36
	v_mov_b32_e32 v43, v37
	v_mov_b32_e32 v47, v38
	v_mov_b32_e32 v49, v39
	v_pk_add_f32 v[36:37], v[40:41], v[42:43]
	v_pk_add_f32 v[38:39], v[46:47], v[48:49]
	s_nop 0
	v_pk_add_f32 v[36:37], v[36:37], v[38:39]
	s_nop 0
	v_pk_add_f32 v[40:41], v[36:37], v[36:37] op_sel:[0,1] op_sel_hi:[1,0]
	s_waitcnt lgkmcnt(0)
	v_lshlrev_b32_e32 v36, 16, v12
	v_and_b32_e32 v37, 0xffff0000, v12
	v_lshlrev_b32_e32 v12, 16, v13
	v_and_b32_e32 v13, 0xffff0000, v13
	v_pk_mul_f32 v[36:37], v[122:123], v[36:37] op_sel_hi:[0,1]
	v_pk_mul_f32 v[12:13], v[122:123], v[12:13] op_sel_hi:[0,1]
	s_waitcnt lgkmcnt(0)
	v_pk_fma_f32 v[18:19], v[24:25], v[36:37], v[18:19]
	v_pk_fma_f32 v[20:21], v[26:27], v[12:13], v[20:21]
	global_store_dwordx4 v[22:23], v[18:21], off offset:-4096 nt
	v_mov_b32_e32 v12, v18
	v_mov_b32_e32 v13, v20
	v_mov_b32_e32 v20, v19
	s_waitcnt vmcnt(25)
	s_nop 1
	v_mov_b32_e32 v18, v234
	v_mov_b32_e32 v19, v235
	s_waitcnt vmcnt(26)
	s_nop 1
	v_mov_b32_e32 v24, v180
	v_mov_b32_e32 v25, v181
	v_mov_b32_e32 v26, v182
	v_mov_b32_e32 v27, v183
	ds_read_b128 v[36:39], v154 offset:5120
	v_pk_mul_f32 v[42:43], v[20:21], v[20:21]
	s_nop 0
	v_pk_fma_f32 v[42:43], v[12:13], v[12:13], v[42:43]
	s_nop 0
	v_pk_add_f32 v[46:47], v[42:43], v[42:43] op_sel:[0,1] op_sel_hi:[1,0]
	s_waitcnt lgkmcnt(0)
	v_lshlrev_b32_e32 v42, 16, v18
	v_and_b32_e32 v43, 0xffff0000, v18
	v_lshlrev_b32_e32 v18, 16, v19
	v_and_b32_e32 v19, 0xffff0000, v19
	v_pk_mul_f32 v[42:43], v[122:123], v[42:43] op_sel_hi:[0,1]
	v_pk_mul_f32 v[18:19], v[122:123], v[18:19] op_sel_hi:[0,1]
	s_waitcnt lgkmcnt(0)
	v_pk_fma_f32 v[24:25], v[36:37], v[42:43], v[24:25]
	v_pk_fma_f32 v[26:27], v[38:39], v[18:19], v[26:27]
	global_store_dwordx4 v[34:35], v[24:27], off offset:1024 nt
	s_waitcnt vmcnt(24)
	s_nop 1
	v_mov_b32_e32 v50, v236
	v_mov_b32_e32 v51, v237
	s_waitcnt vmcnt(25)
	s_nop 1
	v_mov_b32_e32 v36, v184
	v_mov_b32_e32 v37, v185
	v_mov_b32_e32 v38, v186
	v_mov_b32_e32 v39, v187
	ds_read_b128 v[42:45], v154 offset:6144
	v_mul_f32_e32 v18, v25, v25
	v_mul_f32_e32 v48, v27, v27
	v_mov_b32_e32 v124, v24
	v_mov_b32_e32 v125, v26
	v_pk_fma_f32 v[18:19], v[24:25], v[24:25], v[18:19] op_sel_hi:[1,1,0]
	v_pk_fma_f32 v[48:49], v[26:27], v[26:27], v[48:49] op_sel_hi:[1,1,0]
	v_mov_b32_e32 v26, v25
	s_waitcnt lgkmcnt(0)
	v_lshlrev_b32_e32 v24, 16, v50
	v_and_b32_e32 v25, 0xffff0000, v50
	v_lshlrev_b32_e32 v50, 16, v51
	v_and_b32_e32 v51, 0xffff0000, v51
	v_pk_mul_f32 v[24:25], v[122:123], v[24:25] op_sel_hi:[0,1]
	v_pk_mul_f32 v[50:51], v[122:123], v[50:51] op_sel_hi:[0,1]
	s_waitcnt lgkmcnt(0)
	v_pk_fma_f32 v[42:43], v[42:43], v[24:25], v[36:37]
	v_pk_fma_f32 v[44:45], v[44:45], v[50:51], v[38:39]
	global_store_dwordx4 v[34:35], v[42:45], off offset:2048 nt
	v_pk_mul_f32 v[24:25], v[42:43], v[42:43]
	v_pk_mul_f32 v[50:51], v[44:45], v[44:45]
	v_mov_b32_e32 v128, v42
	v_mov_b32_e32 v129, v44
	v_mov_b32_e32 v44, v43
	s_waitcnt vmcnt(23)
	s_nop 1
	v_mov_b32_e32 v42, v238
	v_mov_b32_e32 v43, v239
	s_nop 0
	s_waitcnt vmcnt(24)
	s_nop 1
	v_mov_b32_e32 v28, v188
	v_mov_b32_e32 v29, v189
	v_mov_b32_e32 v30, v190
	v_mov_b32_e32 v31, v191
	s_nop 0
	ds_read_b128 v[36:39], v154 offset:7168
	v_mov_b32_e32 v41, v24
	v_mov_b32_e32 v47, v25
	v_mov_b32_e32 v19, v50
	v_mov_b32_e32 v49, v51
	v_pk_add_f32 v[24:25], v[40:41], v[46:47]
	v_pk_add_f32 v[18:19], v[18:19], v[48:49]
	s_waitcnt lgkmcnt(0)
	v_lshlrev_b32_e32 v40, 16, v43
	v_pk_add_f32 v[18:19], v[24:25], v[18:19]
	v_lshlrev_b32_e32 v24, 16, v42
	v_and_b32_e32 v25, 0xffff0000, v42
	v_and_b32_e32 v41, 0xffff0000, v43
	v_pk_mul_f32 v[24:25], v[122:123], v[24:25] op_sel_hi:[0,1]
	v_pk_mul_f32 v[40:41], v[122:123], v[40:41] op_sel_hi:[0,1]
	s_waitcnt lgkmcnt(0)
	v_pk_fma_f32 v[46:47], v[36:37], v[24:25], v[28:29]
	v_pk_fma_f32 v[48:49], v[38:39], v[40:41], v[30:31]
	global_store_dwordx4 v[34:35], v[46:49], off offset:3072 nt
	s_waitcnt vmcnt(22)
	s_nop 1
	v_mov_b32_e32 v24, v240
	v_mov_b32_e32 v25, v241
	s_waitcnt vmcnt(23)
	s_nop 1
	v_mov_b32_e32 v28, v192
	v_mov_b32_e32 v29, v193
	v_mov_b32_e32 v30, v194
	v_mov_b32_e32 v31, v195
	s_nop 0
	ds_read_b128 v[34:37], v154 offset:8192
	v_mov_b32_e32 v130, v46
	v_mov_b32_e32 v131, v48
	v_mov_b32_e32 v48, v47
	v_pk_mul_f32 v[38:39], v[48:49], v[48:49]
	v_pk_add_f32 v[18:19], v[18:19], v[18:19] op_sel:[0,1] op_sel_hi:[1,0]
	v_pk_fma_f32 v[38:39], v[130:131], v[130:131], v[38:39]
	s_waitcnt lgkmcnt(0)
	v_lshlrev_b32_e32 v40, 16, v24
	v_and_b32_e32 v41, 0xffff0000, v24
	v_lshlrev_b32_e32 v24, 16, v25
	v_and_b32_e32 v25, 0xffff0000, v25
	v_pk_mul_f32 v[40:41], v[122:123], v[40:41] op_sel_hi:[0,1]
	v_pk_mul_f32 v[24:25], v[122:123], v[24:25] op_sel_hi:[0,1]
	s_waitcnt lgkmcnt(0)
	v_pk_fma_f32 v[50:51], v[34:35], v[40:41], v[28:29]
	v_pk_fma_f32 v[52:53], v[36:37], v[24:25], v[30:31]
	global_store_dwordx4 v[22:23], v[50:53], off nt
	s_waitcnt vmcnt(21)
	s_nop 1
	v_mov_b32_e32 v42, v242
	v_mov_b32_e32 v43, v243
	s_waitcnt vmcnt(22)
	s_nop 1
	v_mov_b32_e32 v28, v196
	v_mov_b32_e32 v29, v197
	v_mov_b32_e32 v30, v198
	v_mov_b32_e32 v31, v199
	ds_read_b128 v[34:37], v154 offset:9216
	v_mul_f32_e32 v40, v53, v53
	v_pk_fma_f32 v[46:47], v[52:53], v[52:53], v[40:41] op_sel_hi:[1,1,0]
	v_mul_f32_e32 v24, v51, v51
	v_mov_b32_e32 v144, v50
	v_mov_b32_e32 v145, v52
	v_pk_fma_f32 v[24:25], v[50:51], v[50:51], v[24:25] op_sel_hi:[1,1,0]
	v_mov_b32_e32 v52, v51
	v_pk_add_f32 v[38:39], v[38:39], v[38:39] op_sel:[0,1] op_sel_hi:[1,0]
	s_waitcnt lgkmcnt(0)
	v_lshlrev_b32_e32 v40, 16, v42
	v_and_b32_e32 v41, 0xffff0000, v42
	v_lshlrev_b32_e32 v42, 16, v43
	v_and_b32_e32 v43, 0xffff0000, v43
	v_pk_mul_f32 v[40:41], v[122:123], v[40:41] op_sel_hi:[0,1]
	v_pk_mul_f32 v[42:43], v[122:123], v[42:43] op_sel_hi:[0,1]
	s_waitcnt lgkmcnt(0)
	v_pk_fma_f32 v[34:35], v[34:35], v[40:41], v[28:29]
	v_pk_fma_f32 v[36:37], v[36:37], v[42:43], v[30:31]
	global_store_dwordx4 v[22:23], v[34:37], off offset:1024 nt
	v_pk_mul_f32 v[126:127], v[34:35], v[34:35]
	v_pk_mul_f32 v[140:141], v[36:37], v[36:37]
	v_mov_b32_e32 v50, v34
	v_mov_b32_e32 v51, v36
	v_mov_b32_e32 v36, v35
	s_waitcnt vmcnt(20)
	s_nop 1
	v_mov_b32_e32 v34, v244
	v_mov_b32_e32 v35, v245
	s_waitcnt vmcnt(21)
	s_nop 1
	v_mov_b32_e32 v28, v200
	v_mov_b32_e32 v29, v201
	v_mov_b32_e32 v30, v202
	v_mov_b32_e32 v31, v203
	ds_read_b128 v[40:43], v154 offset:10240
	v_mov_b32_e32 v19, v126
	v_mov_b32_e32 v39, v127
	v_mov_b32_e32 v25, v140
	v_mov_b32_e32 v47, v141
	v_pk_add_f32 v[18:19], v[18:19], v[38:39]
	v_pk_add_f32 v[24:25], v[24:25], v[46:47]
	s_nop 0
	v_pk_add_f32 v[18:19], v[18:19], v[24:25]
	s_waitcnt lgkmcnt(0)
	v_lshlrev_b32_e32 v24, 16, v34
	v_and_b32_e32 v25, 0xffff0000, v34
	v_lshlrev_b32_e32 v34, 16, v35
	v_and_b32_e32 v35, 0xffff0000, v35
	v_pk_mul_f32 v[24:25], v[122:123], v[24:25] op_sel_hi:[0,1]
	v_pk_mul_f32 v[34:35], v[122:123], v[34:35] op_sel_hi:[0,1]
	s_waitcnt lgkmcnt(0)
	v_pk_fma_f32 v[40:41], v[40:41], v[24:25], v[28:29]
	v_pk_fma_f32 v[42:43], v[42:43], v[34:35], v[30:31]
	global_store_dwordx4 v[22:23], v[40:43], off offset:2048 nt
	s_waitcnt vmcnt(19)
	s_nop 1
	v_mov_b32_e32 v24, v246
	v_mov_b32_e32 v25, v247
	s_waitcnt vmcnt(20)
	s_nop 1
	v_mov_b32_e32 v28, v204
	v_mov_b32_e32 v29, v205
	v_mov_b32_e32 v30, v206
	v_mov_b32_e32 v31, v207
	s_nop 0
	ds_read_b128 v[32:35], v154 offset:11264
	v_mov_b32_e32 v127, v42
	v_mov_b32_e32 v42, v41
	v_mov_b32_e32 v126, v40
	v_pk_mul_f32 v[38:39], v[42:43], v[42:43]
	v_pk_add_f32 v[18:19], v[18:19], v[18:19] op_sel:[0,1] op_sel_hi:[1,0]
	v_pk_fma_f32 v[38:39], v[126:127], v[126:127], v[38:39]
	s_nop 0
	v_pk_add_f32 v[46:47], v[38:39], v[38:39] op_sel:[0,1] op_sel_hi:[1,0]
	s_waitcnt lgkmcnt(0)
	v_lshlrev_b32_e32 v38, 16, v24
	v_and_b32_e32 v39, 0xffff0000, v24
	v_lshlrev_b32_e32 v24, 16, v25
	v_and_b32_e32 v25, 0xffff0000, v25
	v_pk_mul_f32 v[38:39], v[122:123], v[38:39] op_sel_hi:[0,1]
	v_pk_mul_f32 v[24:25], v[122:123], v[24:25] op_sel_hi:[0,1]
	s_waitcnt lgkmcnt(0)
	v_pk_fma_f32 v[38:39], v[32:33], v[38:39], v[28:29]
	v_pk_fma_f32 v[40:41], v[34:35], v[24:25], v[30:31]
	global_store_dwordx4 v[22:23], v[38:41], off offset:3072 nt
	s_waitcnt vmcnt(18)
	s_nop 1
	v_mov_b32_e32 v140, v248
	v_mov_b32_e32 v141, v249
	s_nop 0
	s_waitcnt vmcnt(19)
	s_nop 1
	v_mov_b32_e32 v22, v208
	v_mov_b32_e32 v23, v209
	v_mov_b32_e32 v24, v210
	v_mov_b32_e32 v25, v211
	ds_read_b128 v[28:31], v154 offset:12288
	v_mul_f32_e32 v32, v39, v39
	v_mul_f32_e32 v34, v41, v41
	v_pk_fma_f32 v[142:143], v[38:39], v[38:39], v[32:33] op_sel_hi:[1,1,0]
	v_pk_fma_f32 v[146:147], v[40:41], v[40:41], v[34:35] op_sel_hi:[1,1,0]
	s_waitcnt lgkmcnt(0)
	v_lshlrev_b32_e32 v32, 16, v140
	v_and_b32_e32 v33, 0xffff0000, v140
	v_lshlrev_b32_e32 v34, 16, v141
	v_and_b32_e32 v35, 0xffff0000, v141
	v_pk_mul_f32 v[32:33], v[122:123], v[32:33] op_sel_hi:[0,1]
	v_pk_mul_f32 v[34:35], v[122:123], v[34:35] op_sel_hi:[0,1]
	s_waitcnt lgkmcnt(0)
	v_pk_fma_f32 v[32:33], v[28:29], v[32:33], v[22:23]
	v_pk_fma_f32 v[34:35], v[30:31], v[34:35], v[24:25]
	global_store_dwordx4 v[116:117], v[32:35], off nt
	s_waitcnt vmcnt(17)
	s_nop 1
	v_mov_b32_e32 v150, v250
	v_mov_b32_e32 v151, v251
	s_waitcnt vmcnt(18)
	s_nop 1
	v_mov_b32_e32 v22, v212
	v_mov_b32_e32 v23, v213
	v_mov_b32_e32 v24, v214
	v_mov_b32_e32 v25, v215
	ds_read_b128 v[28:31], v154 offset:13312
	v_pk_mul_f32 v[140:141], v[32:33], v[32:33]
	v_pk_mul_f32 v[148:149], v[34:35], v[34:35]
	v_mov_b32_e32 v19, v140
	v_mov_b32_e32 v47, v141
	v_mov_b32_e32 v143, v148
	v_mov_b32_e32 v147, v149
	v_pk_add_f32 v[18:19], v[18:19], v[46:47]
	v_pk_add_f32 v[46:47], v[142:143], v[146:147]
	s_nop 0
	v_pk_add_f32 v[18:19], v[18:19], v[46:47]
	s_waitcnt lgkmcnt(0)
	v_lshlrev_b32_e32 v46, 16, v151
	v_pk_add_f32 v[146:147], v[18:19], v[18:19] op_sel:[0,1] op_sel_hi:[1,0]
	v_lshlrev_b32_e32 v18, 16, v150
	v_and_b32_e32 v19, 0xffff0000, v150
	v_and_b32_e32 v47, 0xffff0000, v151
	v_pk_mul_f32 v[18:19], v[122:123], v[18:19] op_sel_hi:[0,1]
	v_pk_mul_f32 v[46:47], v[122:123], v[46:47] op_sel_hi:[0,1]
	s_waitcnt lgkmcnt(0)
	v_pk_fma_f32 v[28:29], v[28:29], v[18:19], v[22:23]
	v_pk_fma_f32 v[30:31], v[30:31], v[46:47], v[24:25]
	global_store_dwordx4 v[116:117], v[28:31], off offset:1024 nt
	s_waitcnt vmcnt(16)
	s_nop 1
	v_mov_b32_e32 v18, v252
	v_mov_b32_e32 v19, v253
	s_waitcnt vmcnt(17)
	s_nop 1
	v_mov_b32_e32 v22, v216
	v_mov_b32_e32 v23, v217
	v_mov_b32_e32 v24, v218
	v_mov_b32_e32 v25, v219
	ds_read_b128 v[140:143], v154 offset:14336
	v_mov_b32_e32 v47, v30
	v_mov_b32_e32 v30, v29
	v_mov_b32_e32 v46, v28
	v_pk_mul_f32 v[28:29], v[30:31], v[30:31]
	s_waitcnt lgkmcnt(0)
	v_lshlrev_b32_e32 v148, 16, v18
	v_and_b32_e32 v149, 0xffff0000, v18
	v_lshlrev_b32_e32 v18, 16, v19
	v_and_b32_e32 v19, 0xffff0000, v19
	v_pk_mul_f32 v[148:149], v[122:123], v[148:149] op_sel_hi:[0,1]
	v_pk_mul_f32 v[18:19], v[122:123], v[18:19] op_sel_hi:[0,1]
	s_waitcnt lgkmcnt(0)
	v_pk_fma_f32 v[22:23], v[140:141], v[148:149], v[22:23]
	v_pk_fma_f32 v[24:25], v[142:143], v[18:19], v[24:25]
	global_store_dwordx4 v[116:117], v[22:25], off offset:2048 nt
	s_waitcnt vmcnt(15)
	s_nop 1
	v_mov_b32_e32 v152, v254
	v_mov_b32_e32 v153, v255
	s_nop 0
	s_waitcnt vmcnt(16)
	s_nop 1
	v_mov_b32_e32 v16, v220
	v_mov_b32_e32 v17, v221
	v_mov_b32_e32 v18, v222
	v_mov_b32_e32 v19, v223
	ds_read_b128 v[140:143], v154 offset:15360
	v_pk_fma_f32 v[28:29], v[46:47], v[46:47], v[28:29]
	v_mul_f32_e32 v148, v23, v23
	v_mul_f32_e32 v150, v25, v25
	v_pk_add_f32 v[28:29], v[28:29], v[28:29] op_sel:[0,1] op_sel_hi:[1,0]
	v_pk_fma_f32 v[148:149], v[22:23], v[22:23], v[148:149] op_sel_hi:[1,1,0]
	v_pk_fma_f32 v[150:151], v[24:25], v[24:25], v[150:151] op_sel_hi:[1,1,0]
	s_waitcnt lgkmcnt(0)
	v_lshlrev_b32_e32 v114, 16, v152
	v_and_b32_e32 v115, 0xffff0000, v152
	v_lshlrev_b32_e32 v152, 16, v153
	v_and_b32_e32 v153, 0xffff0000, v153
	v_pk_mul_f32 v[114:115], v[122:123], v[114:115] op_sel_hi:[0,1]
	v_pk_mul_f32 v[152:153], v[122:123], v[152:153] op_sel_hi:[0,1]
	s_waitcnt lgkmcnt(0)
	v_pk_fma_f32 v[16:17], v[140:141], v[114:115], v[16:17]
	v_pk_fma_f32 v[18:19], v[142:143], v[152:153], v[18:19]
	global_store_dwordx4 v[116:117], v[16:19], off offset:3072 nt
	v_pk_mul_f32 v[114:115], v[16:17], v[16:17]
	v_pk_mul_f32 v[116:117], v[18:19], v[18:19]
	v_mov_b32_e32 v147, v114
	v_mov_b32_e32 v29, v115
	v_mov_b32_e32 v149, v116
	v_mov_b32_e32 v151, v117
	ds_read_b128 v[114:117], v154 offset:16384
	v_pk_add_f32 v[28:29], v[146:147], v[28:29]
	v_pk_add_f32 v[140:141], v[148:149], v[150:151]
	s_nop 0
	v_pk_add_f32 v[28:29], v[28:29], v[140:141]
	s_nop 0
	v_add_f32_e32 v28, v28, v29
	ds_bpermute_b32 v29, v123, v28
	s_waitcnt lgkmcnt(0)
	v_add_f32_e32 v28, v28, v29
	ds_bpermute_b32 v29, v132, v28
	s_waitcnt lgkmcnt(0)
	v_add_f32_e32 v28, v28, v29
	ds_bpermute_b32 v29, v133, v28
	s_waitcnt lgkmcnt(0)
	v_add_f32_e32 v28, v28, v29
	ds_bpermute_b32 v29, v134, v28
	s_waitcnt lgkmcnt(0)
	v_add_f32_e32 v28, v28, v29
	ds_bpermute_b32 v29, v135, v28
	s_waitcnt lgkmcnt(0)
	v_add_f32_e32 v28, v28, v29
	ds_bpermute_b32 v29, v136, v28
	s_waitcnt lgkmcnt(0)
	v_add_f32_e32 v28, v28, v29
	v_fmamk_f32 v28, v28, 0x39800000, v137
	v_mul_f32_e32 v29, 0x4f800000, v28
	v_cmp_gt_f32_e32 vcc, s11, v28
	s_nop 1
	v_cndmask_b32_e32 v28, v28, v29, vcc
	v_sqrt_f32_e32 v29, v28
	s_nop 0
	v_add_u32_e32 v122, -1, v29
	v_add_u32_e32 v140, 1, v29
	v_fma_f32 v141, -v122, v29, v28
	v_fma_f32 v142, -v140, v29, v28
	v_cmp_ge_f32_e64 s[2:3], 0, v141
	s_nop 1
	v_cndmask_b32_e64 v29, v29, v122, s[2:3]
	v_cmp_lt_f32_e64 s[2:3], 0, v142
	s_nop 1
	v_cndmask_b32_e64 v29, v29, v140, s[2:3]
	v_mul_f32_e32 v122, 0x37800000, v29
	v_cndmask_b32_e32 v29, v29, v122, vcc
	v_cmp_class_f32_e32 vcc, v28, v138
	s_nop 1
	v_cndmask_b32_e32 v28, v29, v28, vcc
	v_div_scale_f32 v29, s[2:3], v28, v28, 1.0
	v_rcp_f32_e32 v140, v29
	v_div_scale_f32 v122, vcc, 1.0, v28, 1.0
	v_fma_f32 v141, -v29, v140, 1.0
	v_fmac_f32_e32 v140, v141, v140
	v_mul_f32_e32 v141, v122, v140
	v_fma_f32 v142, -v29, v141, v122
	v_fmac_f32_e32 v141, v142, v140
	v_fma_f32 v29, -v29, v141, v122
	v_div_fmas_f32 v29, v29, v140, v141
	v_div_fixup_f32 v28, v29, v28, 1.0
	v_pk_mul_f32 v[2:3], v[2:3], v[28:29] op_sel_hi:[1,0]
	v_pk_mul_f32 v[140:141], v[0:1], v[28:29] op_sel_hi:[1,0]
	s_waitcnt lgkmcnt(0)
	v_mov_b32_e32 v1, v116
	v_mov_b32_e32 v116, v115
	v_pk_mul_f32 v[120:121], v[120:121], v[28:29] op_sel_hi:[1,0]
	v_mov_b32_e32 v0, v114
	v_pk_mul_f32 v[2:3], v[116:117], v[2:3]
	v_pk_mul_f32 v[0:1], v[0:1], v[120:121]
	v_and_b32_sdwa v115, v3, v139 dst_sel:DWORD dst_unused:UNUSED_PAD src0_sel:WORD_1 src1_sel:DWORD
	v_and_b32_sdwa v116, v2, v139 dst_sel:DWORD dst_unused:UNUSED_PAD src0_sel:WORD_1 src1_sel:DWORD
	v_pk_mul_f32 v[6:7], v[6:7], v[28:29] op_sel_hi:[1,0]
	v_pk_mul_f32 v[4:5], v[4:5], v[28:29] op_sel_hi:[1,0]
	v_pk_mul_f32 v[10:11], v[10:11], v[28:29] op_sel_hi:[1,0]
	v_pk_mul_f32 v[8:9], v[8:9], v[28:29] op_sel_hi:[1,0]
	v_pk_mul_f32 v[14:15], v[14:15], v[28:29] op_sel_hi:[1,0]
	v_pk_mul_f32 v[12:13], v[12:13], v[28:29] op_sel_hi:[1,0]
	v_pk_mul_f32 v[20:21], v[20:21], v[28:29] op_sel_hi:[1,0]
	v_pk_mul_f32 v[124:125], v[124:125], v[28:29] op_sel_hi:[1,0]
	v_pk_mul_f32 v[26:27], v[26:27], v[28:29] op_sel_hi:[1,0]
	v_pk_mul_f32 v[128:129], v[128:129], v[28:29] op_sel_hi:[1,0]
	v_pk_mul_f32 v[44:45], v[44:45], v[28:29] op_sel_hi:[1,0]
	v_pk_mul_f32 v[130:131], v[130:131], v[28:29] op_sel_hi:[1,0]
	v_pk_mul_f32 v[48:49], v[48:49], v[28:29] op_sel_hi:[1,0]
	v_pk_mul_f32 v[142:143], v[144:145], v[28:29] op_sel_hi:[1,0]
	v_pk_mul_f32 v[52:53], v[52:53], v[28:29] op_sel_hi:[1,0]
	v_and_b32_sdwa v29, v1, v139 dst_sel:DWORD dst_unused:UNUSED_PAD src0_sel:WORD_1 src1_sel:DWORD
	v_and_b32_sdwa v114, v0, v139 dst_sel:DWORD dst_unused:UNUSED_PAD src0_sel:WORD_1 src1_sel:DWORD
	v_add3_u32 v3, v3, v115, s29
	v_add3_u32 v2, v2, v116, s29
	v_add3_u32 v0, v0, v114, s29
	v_add3_u32 v1, v1, v29, s29
	v_and_b32_e32 v3, 0xffff0000, v3
	v_and_b32_e32 v2, 0xffff0000, v2
	v_or_b32_sdwa v1, v3, v1 dst_sel:DWORD dst_unused:UNUSED_PAD src0_sel:DWORD src1_sel:WORD_1
	v_or_b32_sdwa v0, v2, v0 dst_sel:DWORD dst_unused:UNUSED_PAD src0_sel:DWORD src1_sel:WORD_1
	global_store_dwordx2 v[112:113], v[0:1], off offset:-4096
	ds_read_b128 v[0:3], v154 offset:17408
	s_waitcnt lgkmcnt(0)
	v_mov_b32_e32 v115, v2
	v_mov_b32_e32 v2, v1
	v_mov_b32_e32 v114, v0
	v_pk_mul_f32 v[2:3], v[2:3], v[6:7]
	v_pk_mul_f32 v[0:1], v[114:115], v[140:141]
	v_and_b32_sdwa v29, v3, v139 dst_sel:DWORD dst_unused:UNUSED_PAD src0_sel:WORD_1 src1_sel:DWORD
	v_and_b32_sdwa v114, v2, v139 dst_sel:DWORD dst_unused:UNUSED_PAD src0_sel:WORD_1 src1_sel:DWORD
	v_and_b32_sdwa v6, v1, v139 dst_sel:DWORD dst_unused:UNUSED_PAD src0_sel:WORD_1 src1_sel:DWORD
	v_and_b32_sdwa v7, v0, v139 dst_sel:DWORD dst_unused:UNUSED_PAD src0_sel:WORD_1 src1_sel:DWORD
	v_add3_u32 v3, v3, v29, s29
	v_add3_u32 v2, v2, v114, s29
	v_add3_u32 v0, v0, v7, s29
	v_add3_u32 v1, v1, v6, s29
	v_and_b32_e32 v3, 0xffff0000, v3
	v_and_b32_e32 v2, 0xffff0000, v2
	v_or_b32_sdwa v1, v3, v1 dst_sel:DWORD dst_unused:UNUSED_PAD src0_sel:DWORD src1_sel:WORD_1
	v_or_b32_sdwa v0, v2, v0 dst_sel:DWORD dst_unused:UNUSED_PAD src0_sel:DWORD src1_sel:WORD_1
	global_store_dwordx2 v[118:119], v[0:1], off offset:512
	ds_read_b128 v[0:3], v154 offset:18432
	s_waitcnt lgkmcnt(0)
	v_mov_b32_e32 v7, v2
	v_mov_b32_e32 v2, v1
	v_mov_b32_e32 v6, v0
	v_pk_mul_f32 v[2:3], v[2:3], v[10:11]
	v_pk_mul_f32 v[0:1], v[6:7], v[4:5]
	v_and_b32_sdwa v6, v3, v139 dst_sel:DWORD dst_unused:UNUSED_PAD src0_sel:WORD_1 src1_sel:DWORD
	v_and_b32_sdwa v7, v2, v139 dst_sel:DWORD dst_unused:UNUSED_PAD src0_sel:WORD_1 src1_sel:DWORD
	v_and_b32_sdwa v4, v1, v139 dst_sel:DWORD dst_unused:UNUSED_PAD src0_sel:WORD_1 src1_sel:DWORD
	v_and_b32_sdwa v5, v0, v139 dst_sel:DWORD dst_unused:UNUSED_PAD src0_sel:WORD_1 src1_sel:DWORD
	v_add3_u32 v3, v3, v6, s29
	v_add3_u32 v2, v2, v7, s29
	v_add3_u32 v0, v0, v5, s29
	v_add3_u32 v1, v1, v4, s29
	v_and_b32_e32 v3, 0xffff0000, v3
	v_and_b32_e32 v2, 0xffff0000, v2
	v_or_b32_sdwa v1, v3, v1 dst_sel:DWORD dst_unused:UNUSED_PAD src0_sel:DWORD src1_sel:WORD_1
	v_or_b32_sdwa v0, v2, v0 dst_sel:DWORD dst_unused:UNUSED_PAD src0_sel:DWORD src1_sel:WORD_1
	global_store_dwordx2 v[118:119], v[0:1], off offset:1024
	ds_read_b128 v[0:3], v154 offset:19456
	s_waitcnt lgkmcnt(0)
	v_mov_b32_e32 v5, v2
	v_mov_b32_e32 v2, v1
	v_mov_b32_e32 v4, v0
	v_pk_mul_f32 v[2:3], v[2:3], v[14:15]
	v_pk_mul_f32 v[0:1], v[4:5], v[8:9]
	v_and_b32_sdwa v6, v3, v139 dst_sel:DWORD dst_unused:UNUSED_PAD src0_sel:WORD_1 src1_sel:DWORD
	v_and_b32_sdwa v7, v2, v139 dst_sel:DWORD dst_unused:UNUSED_PAD src0_sel:WORD_1 src1_sel:DWORD
	v_and_b32_sdwa v4, v1, v139 dst_sel:DWORD dst_unused:UNUSED_PAD src0_sel:WORD_1 src1_sel:DWORD
	v_and_b32_sdwa v5, v0, v139 dst_sel:DWORD dst_unused:UNUSED_PAD src0_sel:WORD_1 src1_sel:DWORD
	v_add3_u32 v3, v3, v6, s29
	v_add3_u32 v2, v2, v7, s29
	v_add3_u32 v0, v0, v5, s29
	v_add3_u32 v1, v1, v4, s29
	v_and_b32_e32 v3, 0xffff0000, v3
	v_and_b32_e32 v2, 0xffff0000, v2
	v_or_b32_sdwa v1, v3, v1 dst_sel:DWORD dst_unused:UNUSED_PAD src0_sel:DWORD src1_sel:WORD_1
	v_or_b32_sdwa v0, v2, v0 dst_sel:DWORD dst_unused:UNUSED_PAD src0_sel:DWORD src1_sel:WORD_1
	global_store_dwordx2 v[118:119], v[0:1], off offset:1536
	ds_read_b128 v[0:3], v154 offset:20480
	s_waitcnt lgkmcnt(0)
	v_mov_b32_e32 v5, v2
	v_mov_b32_e32 v2, v1
	v_mov_b32_e32 v4, v0
	v_pk_mul_f32 v[2:3], v[2:3], v[20:21]
	v_pk_mul_f32 v[0:1], v[4:5], v[12:13]
	v_and_b32_sdwa v6, v3, v139 dst_sel:DWORD dst_unused:UNUSED_PAD src0_sel:WORD_1 src1_sel:DWORD
	v_and_b32_sdwa v7, v2, v139 dst_sel:DWORD dst_unused:UNUSED_PAD src0_sel:WORD_1 src1_sel:DWORD
	v_and_b32_sdwa v4, v1, v139 dst_sel:DWORD dst_unused:UNUSED_PAD src0_sel:WORD_1 src1_sel:DWORD
	v_and_b32_sdwa v5, v0, v139 dst_sel:DWORD dst_unused:UNUSED_PAD src0_sel:WORD_1 src1_sel:DWORD
	v_add3_u32 v3, v3, v6, s29
	v_add3_u32 v2, v2, v7, s29
	v_add3_u32 v0, v0, v5, s29
	v_add3_u32 v1, v1, v4, s29
	v_and_b32_e32 v3, 0xffff0000, v3
	v_and_b32_e32 v2, 0xffff0000, v2
	v_or_b32_sdwa v1, v3, v1 dst_sel:DWORD dst_unused:UNUSED_PAD src0_sel:DWORD src1_sel:WORD_1
	v_or_b32_sdwa v0, v2, v0 dst_sel:DWORD dst_unused:UNUSED_PAD src0_sel:DWORD src1_sel:WORD_1
	global_store_dwordx2 v[118:119], v[0:1], off offset:2048
	ds_read_b128 v[0:3], v154 offset:21504
	s_waitcnt lgkmcnt(0)
	v_mov_b32_e32 v5, v2
	v_mov_b32_e32 v2, v1
	v_mov_b32_e32 v4, v0
	v_pk_mul_f32 v[2:3], v[2:3], v[26:27]
	v_pk_mul_f32 v[0:1], v[4:5], v[124:125]
	v_and_b32_sdwa v6, v3, v139 dst_sel:DWORD dst_unused:UNUSED_PAD src0_sel:WORD_1 src1_sel:DWORD
	v_and_b32_sdwa v7, v2, v139 dst_sel:DWORD dst_unused:UNUSED_PAD src0_sel:WORD_1 src1_sel:DWORD
	v_and_b32_sdwa v4, v1, v139 dst_sel:DWORD dst_unused:UNUSED_PAD src0_sel:WORD_1 src1_sel:DWORD
	v_and_b32_sdwa v5, v0, v139 dst_sel:DWORD dst_unused:UNUSED_PAD src0_sel:WORD_1 src1_sel:DWORD
	v_add3_u32 v3, v3, v6, s29
	v_add3_u32 v2, v2, v7, s29
	v_add3_u32 v0, v0, v5, s29
	v_add3_u32 v1, v1, v4, s29
	v_and_b32_e32 v3, 0xffff0000, v3
	v_and_b32_e32 v2, 0xffff0000, v2
	v_or_b32_sdwa v1, v3, v1 dst_sel:DWORD dst_unused:UNUSED_PAD src0_sel:DWORD src1_sel:WORD_1
	v_or_b32_sdwa v0, v2, v0 dst_sel:DWORD dst_unused:UNUSED_PAD src0_sel:DWORD src1_sel:WORD_1
	global_store_dwordx2 v[118:119], v[0:1], off offset:2560
	ds_read_b128 v[0:3], v154 offset:22528
	s_waitcnt lgkmcnt(0)
	v_mov_b32_e32 v5, v2
	v_mov_b32_e32 v2, v1
	v_mov_b32_e32 v4, v0
	v_pk_mul_f32 v[2:3], v[44:45], v[2:3]
	v_pk_mul_f32 v[0:1], v[128:129], v[4:5]
	v_and_b32_sdwa v6, v3, v139 dst_sel:DWORD dst_unused:UNUSED_PAD src0_sel:WORD_1 src1_sel:DWORD
	v_and_b32_sdwa v7, v2, v139 dst_sel:DWORD dst_unused:UNUSED_PAD src0_sel:WORD_1 src1_sel:DWORD
	v_and_b32_sdwa v4, v1, v139 dst_sel:DWORD dst_unused:UNUSED_PAD src0_sel:WORD_1 src1_sel:DWORD
	v_and_b32_sdwa v5, v0, v139 dst_sel:DWORD dst_unused:UNUSED_PAD src0_sel:WORD_1 src1_sel:DWORD
	v_add3_u32 v3, v3, v6, s29
	v_add3_u32 v2, v2, v7, s29
	v_add3_u32 v0, v0, v5, s29
	v_add3_u32 v1, v1, v4, s29
	v_and_b32_e32 v3, 0xffff0000, v3
	v_and_b32_e32 v2, 0xffff0000, v2
	v_or_b32_sdwa v1, v3, v1 dst_sel:DWORD dst_unused:UNUSED_PAD src0_sel:DWORD src1_sel:WORD_1
	v_or_b32_sdwa v0, v2, v0 dst_sel:DWORD dst_unused:UNUSED_PAD src0_sel:DWORD src1_sel:WORD_1
	global_store_dwordx2 v[118:119], v[0:1], off offset:3072
	ds_read_b128 v[0:3], v154 offset:23552
	s_waitcnt lgkmcnt(0)
	v_mov_b32_e32 v5, v2
	v_mov_b32_e32 v2, v1
	v_mov_b32_e32 v4, v0
	v_pk_mul_f32 v[2:3], v[48:49], v[2:3]
	v_pk_mul_f32 v[0:1], v[130:131], v[4:5]
	v_and_b32_sdwa v6, v3, v139 dst_sel:DWORD dst_unused:UNUSED_PAD src0_sel:WORD_1 src1_sel:DWORD
	v_and_b32_sdwa v7, v2, v139 dst_sel:DWORD dst_unused:UNUSED_PAD src0_sel:WORD_1 src1_sel:DWORD
	v_and_b32_sdwa v4, v1, v139 dst_sel:DWORD dst_unused:UNUSED_PAD src0_sel:WORD_1 src1_sel:DWORD
	v_and_b32_sdwa v5, v0, v139 dst_sel:DWORD dst_unused:UNUSED_PAD src0_sel:WORD_1 src1_sel:DWORD
	v_add3_u32 v3, v3, v6, s29
	v_add3_u32 v2, v2, v7, s29
	v_add3_u32 v0, v0, v5, s29
	v_add3_u32 v1, v1, v4, s29
	v_and_b32_e32 v3, 0xffff0000, v3
	v_and_b32_e32 v2, 0xffff0000, v2
	v_or_b32_sdwa v1, v3, v1 dst_sel:DWORD dst_unused:UNUSED_PAD src0_sel:DWORD src1_sel:WORD_1
	v_or_b32_sdwa v0, v2, v0 dst_sel:DWORD dst_unused:UNUSED_PAD src0_sel:DWORD src1_sel:WORD_1
	global_store_dwordx2 v[118:119], v[0:1], off offset:3584
	ds_read_b128 v[0:3], v154 offset:24576
	s_waitcnt lgkmcnt(0)
	v_mov_b32_e32 v5, v2
	v_mov_b32_e32 v2, v1
	v_mov_b32_e32 v4, v0
	v_pk_mul_f32 v[2:3], v[52:53], v[2:3]
	v_pk_mul_f32 v[0:1], v[142:143], v[4:5]
	v_and_b32_sdwa v6, v3, v139 dst_sel:DWORD dst_unused:UNUSED_PAD src0_sel:WORD_1 src1_sel:DWORD
	v_and_b32_sdwa v7, v2, v139 dst_sel:DWORD dst_unused:UNUSED_PAD src0_sel:WORD_1 src1_sel:DWORD
	v_and_b32_sdwa v4, v1, v139 dst_sel:DWORD dst_unused:UNUSED_PAD src0_sel:WORD_1 src1_sel:DWORD
	v_and_b32_sdwa v5, v0, v139 dst_sel:DWORD dst_unused:UNUSED_PAD src0_sel:WORD_1 src1_sel:DWORD
	v_add3_u32 v3, v3, v6, s29
	v_add3_u32 v2, v2, v7, s29
	v_add3_u32 v0, v0, v5, s29
	v_add3_u32 v1, v1, v4, s29
	v_and_b32_e32 v3, 0xffff0000, v3
	v_and_b32_e32 v2, 0xffff0000, v2
	v_or_b32_sdwa v1, v3, v1 dst_sel:DWORD dst_unused:UNUSED_PAD src0_sel:DWORD src1_sel:WORD_1
	v_or_b32_sdwa v0, v2, v0 dst_sel:DWORD dst_unused:UNUSED_PAD src0_sel:DWORD src1_sel:WORD_1
	global_store_dwordx2 v[112:113], v[0:1], off
	ds_read_b128 v[0:3], v154 offset:25600
	v_pk_mul_f32 v[6:7], v[36:37], v[28:29] op_sel_hi:[1,0]
	v_pk_mul_f32 v[4:5], v[50:51], v[28:29] op_sel_hi:[1,0]
	s_waitcnt lgkmcnt(0)
	v_mov_b32_e32 v9, v2
	v_mov_b32_e32 v2, v1
	v_mov_b32_e32 v8, v0
	v_pk_mul_f32 v[2:3], v[6:7], v[2:3]
	v_pk_mul_f32 v[0:1], v[4:5], v[8:9]
	v_and_b32_sdwa v6, v3, v139 dst_sel:DWORD dst_unused:UNUSED_PAD src0_sel:WORD_1 src1_sel:DWORD
	v_and_b32_sdwa v7, v2, v139 dst_sel:DWORD dst_unused:UNUSED_PAD src0_sel:WORD_1 src1_sel:DWORD
	v_and_b32_sdwa v4, v1, v139 dst_sel:DWORD dst_unused:UNUSED_PAD src0_sel:WORD_1 src1_sel:DWORD
	v_and_b32_sdwa v5, v0, v139 dst_sel:DWORD dst_unused:UNUSED_PAD src0_sel:WORD_1 src1_sel:DWORD
	v_add3_u32 v3, v3, v6, s29
	v_add3_u32 v2, v2, v7, s29
	v_add3_u32 v0, v0, v5, s29
	v_add3_u32 v1, v1, v4, s29
	v_and_b32_e32 v3, 0xffff0000, v3
	v_and_b32_e32 v2, 0xffff0000, v2
	v_or_b32_sdwa v1, v3, v1 dst_sel:DWORD dst_unused:UNUSED_PAD src0_sel:DWORD src1_sel:WORD_1
	v_or_b32_sdwa v0, v2, v0 dst_sel:DWORD dst_unused:UNUSED_PAD src0_sel:DWORD src1_sel:WORD_1
	global_store_dwordx2 v[112:113], v[0:1], off offset:512
	ds_read_b128 v[0:3], v154 offset:26624
	v_pk_mul_f32 v[6:7], v[42:43], v[28:29] op_sel_hi:[1,0]
	v_pk_mul_f32 v[4:5], v[126:127], v[28:29] op_sel_hi:[1,0]
	s_waitcnt lgkmcnt(0)
	v_mov_b32_e32 v9, v2
	v_mov_b32_e32 v2, v1
	v_mov_b32_e32 v8, v0
	v_pk_mul_f32 v[2:3], v[6:7], v[2:3]
	v_pk_mul_f32 v[0:1], v[4:5], v[8:9]
	v_and_b32_sdwa v6, v3, v139 dst_sel:DWORD dst_unused:UNUSED_PAD src0_sel:WORD_1 src1_sel:DWORD
	v_and_b32_sdwa v7, v2, v139 dst_sel:DWORD dst_unused:UNUSED_PAD src0_sel:WORD_1 src1_sel:DWORD
	v_and_b32_sdwa v4, v1, v139 dst_sel:DWORD dst_unused:UNUSED_PAD src0_sel:WORD_1 src1_sel:DWORD
	v_and_b32_sdwa v5, v0, v139 dst_sel:DWORD dst_unused:UNUSED_PAD src0_sel:WORD_1 src1_sel:DWORD
	v_add3_u32 v3, v3, v6, s29
	v_add3_u32 v2, v2, v7, s29
	v_add3_u32 v0, v0, v5, s29
	v_add3_u32 v1, v1, v4, s29
	v_and_b32_e32 v3, 0xffff0000, v3
	v_and_b32_e32 v2, 0xffff0000, v2
	v_or_b32_sdwa v1, v3, v1 dst_sel:DWORD dst_unused:UNUSED_PAD src0_sel:DWORD src1_sel:WORD_1
	v_or_b32_sdwa v0, v2, v0 dst_sel:DWORD dst_unused:UNUSED_PAD src0_sel:DWORD src1_sel:WORD_1
	global_store_dwordx2 v[112:113], v[0:1], off offset:1024
	ds_read_b128 v[0:3], v154 offset:27648
	v_mov_b32_e32 v5, v40
	v_mov_b32_e32 v40, v39
	v_mov_b32_e32 v4, v38
	v_pk_mul_f32 v[6:7], v[40:41], v[28:29] op_sel_hi:[1,0]
	v_pk_mul_f32 v[4:5], v[4:5], v[28:29] op_sel_hi:[1,0]
	s_waitcnt lgkmcnt(0)
	v_mov_b32_e32 v9, v2
	v_mov_b32_e32 v2, v1
	v_mov_b32_e32 v8, v0
	v_pk_mul_f32 v[2:3], v[6:7], v[2:3]
	v_pk_mul_f32 v[0:1], v[4:5], v[8:9]
	v_and_b32_sdwa v6, v3, v139 dst_sel:DWORD dst_unused:UNUSED_PAD src0_sel:WORD_1 src1_sel:DWORD
	v_and_b32_sdwa v7, v2, v139 dst_sel:DWORD dst_unused:UNUSED_PAD src0_sel:WORD_1 src1_sel:DWORD
	v_and_b32_sdwa v4, v1, v139 dst_sel:DWORD dst_unused:UNUSED_PAD src0_sel:WORD_1 src1_sel:DWORD
	v_and_b32_sdwa v5, v0, v139 dst_sel:DWORD dst_unused:UNUSED_PAD src0_sel:WORD_1 src1_sel:DWORD
	v_add3_u32 v3, v3, v6, s29
	v_add3_u32 v2, v2, v7, s29
	v_add3_u32 v0, v0, v5, s29
	v_add3_u32 v1, v1, v4, s29
	v_and_b32_e32 v3, 0xffff0000, v3
	v_and_b32_e32 v2, 0xffff0000, v2
	v_or_b32_sdwa v1, v3, v1 dst_sel:DWORD dst_unused:UNUSED_PAD src0_sel:DWORD src1_sel:WORD_1
	v_or_b32_sdwa v0, v2, v0 dst_sel:DWORD dst_unused:UNUSED_PAD src0_sel:DWORD src1_sel:WORD_1
	global_store_dwordx2 v[112:113], v[0:1], off offset:1536
	ds_read_b128 v[0:3], v154 offset:28672
	v_mov_b32_e32 v5, v34
	v_mov_b32_e32 v34, v33
	v_mov_b32_e32 v4, v32
	v_pk_mul_f32 v[6:7], v[34:35], v[28:29] op_sel_hi:[1,0]
	v_pk_mul_f32 v[4:5], v[4:5], v[28:29] op_sel_hi:[1,0]
	s_waitcnt lgkmcnt(0)
	v_mov_b32_e32 v9, v2
	v_mov_b32_e32 v2, v1
	v_mov_b32_e32 v8, v0
	v_pk_mul_f32 v[2:3], v[6:7], v[2:3]
	v_pk_mul_f32 v[0:1], v[4:5], v[8:9]
	v_and_b32_sdwa v6, v3, v139 dst_sel:DWORD dst_unused:UNUSED_PAD src0_sel:WORD_1 src1_sel:DWORD
	v_and_b32_sdwa v7, v2, v139 dst_sel:DWORD dst_unused:UNUSED_PAD src0_sel:WORD_1 src1_sel:DWORD
	v_and_b32_sdwa v4, v1, v139 dst_sel:DWORD dst_unused:UNUSED_PAD src0_sel:WORD_1 src1_sel:DWORD
	v_and_b32_sdwa v5, v0, v139 dst_sel:DWORD dst_unused:UNUSED_PAD src0_sel:WORD_1 src1_sel:DWORD
	v_add3_u32 v3, v3, v6, s29
	v_add3_u32 v2, v2, v7, s29
	v_add3_u32 v0, v0, v5, s29
	v_add3_u32 v1, v1, v4, s29
	v_and_b32_e32 v3, 0xffff0000, v3
	v_and_b32_e32 v2, 0xffff0000, v2
	v_or_b32_sdwa v1, v3, v1 dst_sel:DWORD dst_unused:UNUSED_PAD src0_sel:DWORD src1_sel:WORD_1
	v_or_b32_sdwa v0, v2, v0 dst_sel:DWORD dst_unused:UNUSED_PAD src0_sel:DWORD src1_sel:WORD_1
	global_store_dwordx2 v[112:113], v[0:1], off offset:2048
	ds_read_b128 v[0:3], v154 offset:29696
	v_pk_mul_f32 v[6:7], v[30:31], v[28:29] op_sel_hi:[1,0]
	v_pk_mul_f32 v[4:5], v[46:47], v[28:29] op_sel_hi:[1,0]
	s_waitcnt lgkmcnt(0)
	v_mov_b32_e32 v9, v2
	v_mov_b32_e32 v2, v1
	v_mov_b32_e32 v8, v0
	v_pk_mul_f32 v[2:3], v[6:7], v[2:3]
	v_pk_mul_f32 v[0:1], v[4:5], v[8:9]
	v_and_b32_sdwa v6, v3, v139 dst_sel:DWORD dst_unused:UNUSED_PAD src0_sel:WORD_1 src1_sel:DWORD
	v_and_b32_sdwa v7, v2, v139 dst_sel:DWORD dst_unused:UNUSED_PAD src0_sel:WORD_1 src1_sel:DWORD
	v_and_b32_sdwa v4, v1, v139 dst_sel:DWORD dst_unused:UNUSED_PAD src0_sel:WORD_1 src1_sel:DWORD
	v_and_b32_sdwa v5, v0, v139 dst_sel:DWORD dst_unused:UNUSED_PAD src0_sel:WORD_1 src1_sel:DWORD
	v_add3_u32 v3, v3, v6, s29
	v_add3_u32 v2, v2, v7, s29
	v_add3_u32 v0, v0, v5, s29
	v_add3_u32 v1, v1, v4, s29
	v_and_b32_e32 v3, 0xffff0000, v3
	v_and_b32_e32 v2, 0xffff0000, v2
	v_or_b32_sdwa v1, v3, v1 dst_sel:DWORD dst_unused:UNUSED_PAD src0_sel:DWORD src1_sel:WORD_1
	v_or_b32_sdwa v0, v2, v0 dst_sel:DWORD dst_unused:UNUSED_PAD src0_sel:DWORD src1_sel:WORD_1
	global_store_dwordx2 v[112:113], v[0:1], off offset:2560
	ds_read_b128 v[0:3], v154 offset:30720
	v_mov_b32_e32 v5, v24
	v_mov_b32_e32 v24, v23
	v_mov_b32_e32 v4, v22
	v_pk_mul_f32 v[6:7], v[24:25], v[28:29] op_sel_hi:[1,0]
	v_pk_mul_f32 v[4:5], v[4:5], v[28:29] op_sel_hi:[1,0]
	s_waitcnt lgkmcnt(0)
	v_mov_b32_e32 v9, v2
	v_mov_b32_e32 v2, v1
	v_mov_b32_e32 v8, v0
	v_pk_mul_f32 v[2:3], v[6:7], v[2:3]
	v_pk_mul_f32 v[0:1], v[4:5], v[8:9]
	v_and_b32_sdwa v6, v3, v139 dst_sel:DWORD dst_unused:UNUSED_PAD src0_sel:WORD_1 src1_sel:DWORD
	v_and_b32_sdwa v7, v2, v139 dst_sel:DWORD dst_unused:UNUSED_PAD src0_sel:WORD_1 src1_sel:DWORD
	v_and_b32_sdwa v4, v1, v139 dst_sel:DWORD dst_unused:UNUSED_PAD src0_sel:WORD_1 src1_sel:DWORD
	v_and_b32_sdwa v5, v0, v139 dst_sel:DWORD dst_unused:UNUSED_PAD src0_sel:WORD_1 src1_sel:DWORD
	v_add3_u32 v3, v3, v6, s29
	v_add3_u32 v2, v2, v7, s29
	v_add3_u32 v0, v0, v5, s29
	v_add3_u32 v1, v1, v4, s29
	v_and_b32_e32 v3, 0xffff0000, v3
	v_and_b32_e32 v2, 0xffff0000, v2
	v_or_b32_sdwa v1, v3, v1 dst_sel:DWORD dst_unused:UNUSED_PAD src0_sel:DWORD src1_sel:WORD_1
	v_or_b32_sdwa v0, v2, v0 dst_sel:DWORD dst_unused:UNUSED_PAD src0_sel:DWORD src1_sel:WORD_1
	global_store_dwordx2 v[112:113], v[0:1], off offset:3072
	ds_read_b128 v[0:3], v154 offset:31744
	v_mov_b32_e32 v5, v18
	v_mov_b32_e32 v18, v17
	v_mov_b32_e32 v4, v16
	v_pk_mul_f32 v[6:7], v[18:19], v[28:29] op_sel_hi:[1,0]
	v_pk_mul_f32 v[4:5], v[4:5], v[28:29] op_sel_hi:[1,0]
	s_waitcnt lgkmcnt(0)
	v_mov_b32_e32 v9, v2
	v_mov_b32_e32 v2, v1
	v_mov_b32_e32 v8, v0
	v_pk_mul_f32 v[2:3], v[6:7], v[2:3]
	v_pk_mul_f32 v[0:1], v[4:5], v[8:9]
	v_and_b32_sdwa v6, v3, v139 dst_sel:DWORD dst_unused:UNUSED_PAD src0_sel:WORD_1 src1_sel:DWORD
	v_and_b32_sdwa v7, v2, v139 dst_sel:DWORD dst_unused:UNUSED_PAD src0_sel:WORD_1 src1_sel:DWORD
	v_and_b32_sdwa v4, v1, v139 dst_sel:DWORD dst_unused:UNUSED_PAD src0_sel:WORD_1 src1_sel:DWORD
	v_and_b32_sdwa v5, v0, v139 dst_sel:DWORD dst_unused:UNUSED_PAD src0_sel:WORD_1 src1_sel:DWORD
	v_add3_u32 v3, v3, v6, s29
	v_add3_u32 v2, v2, v7, s29
	v_add3_u32 v0, v0, v5, s29
	v_add3_u32 v1, v1, v4, s29
	v_and_b32_e32 v3, 0xffff0000, v3
	v_and_b32_e32 v2, 0xffff0000, v2
	v_or_b32_sdwa v1, v3, v1 dst_sel:DWORD dst_unused:UNUSED_PAD src0_sel:DWORD src1_sel:WORD_1
	v_or_b32_sdwa v0, v2, v0 dst_sel:DWORD dst_unused:UNUSED_PAD src0_sel:DWORD src1_sel:WORD_1
	global_store_dwordx2 v[112:113], v[0:1], off offset:3584
	s_cbranch_scc0 .LBB0_2076

.LBB0_3749:
	v_lshl_add_u64 v[4:5], s[6:7], 0, v[112:113]
	global_load_dword v10, v[4:5], off
	global_load_dwordx4 v[160:163], v116, s[80:81] offset:0 nt
	global_load_dwordx2 v[224:225], v114, s[88:89] offset:0
	global_load_dwordx4 v[164:167], v116, s[80:81] offset:1024 nt
	global_load_dwordx2 v[226:227], v114, s[88:89] offset:512
	global_load_dwordx4 v[168:171], v116, s[80:81] offset:2048 nt
	global_load_dwordx2 v[228:229], v114, s[88:89] offset:1024
	global_load_dwordx4 v[172:175], v116, s[80:81] offset:3072 nt
	global_load_dwordx2 v[230:231], v114, s[88:89] offset:1536
	global_load_dwordx4 v[176:179], v116, s[82:83] offset:0 nt
	global_load_dwordx2 v[232:233], v114, s[88:89] offset:2048
	global_load_dwordx4 v[180:183], v116, s[82:83] offset:1024 nt
	global_load_dwordx2 v[234:235], v114, s[88:89] offset:2560
	global_load_dwordx4 v[184:187], v116, s[82:83] offset:2048 nt
	global_load_dwordx2 v[236:237], v114, s[88:89] offset:3072
	global_load_dwordx4 v[188:191], v116, s[82:83] offset:3072 nt
	global_load_dwordx2 v[238:239], v114, s[88:89] offset:3584
	global_load_dwordx4 v[192:195], v116, s[84:85] offset:0 nt
	global_load_dwordx2 v[240:241], v114, s[90:91] offset:0
	global_load_dwordx4 v[196:199], v116, s[84:85] offset:1024 nt
	global_load_dwordx2 v[242:243], v114, s[90:91] offset:512
	global_load_dwordx4 v[200:203], v116, s[84:85] offset:2048 nt
	global_load_dwordx2 v[244:245], v114, s[90:91] offset:1024
	global_load_dwordx4 v[204:207], v116, s[84:85] offset:3072 nt
	global_load_dwordx2 v[246:247], v114, s[90:91] offset:1536
	global_load_dwordx4 v[208:211], v116, s[86:87] offset:0 nt
	global_load_dwordx2 v[248:249], v114, s[90:91] offset:2048
	global_load_dwordx4 v[212:215], v116, s[86:87] offset:1024 nt
	global_load_dwordx2 v[250:251], v114, s[90:91] offset:2560
	global_load_dwordx4 v[216:219], v116, s[86:87] offset:2048 nt
	global_load_dwordx2 v[252:253], v114, s[90:91] offset:3072
	global_load_dwordx4 v[220:223], v116, s[86:87] offset:3072 nt
	global_load_dwordx2 v[254:255], v114, s[90:91] offset:3584
	v_lshl_add_u64 v[8:9], s[6:7], 0, v[114:115]
	v_add_co_u32_e32 v30, vcc, s17, v8
	v_lshl_add_u64 v[14:15], s[6:7], 0, v[116:117]
	s_nop 0
	v_addc_co_u32_e32 v31, vcc, 0, v9, vcc
	v_add_co_u32_e32 v16, vcc, s26, v8
	v_lshl_add_u64 v[12:13], s[4:5], 0, v[116:117]
	s_nop 0
	v_addc_co_u32_e32 v17, vcc, 0, v9, vcc
	v_add_co_u32_e32 v18, vcc, s24, v14
	ds_read_b128 v[0:3], v144 offset:0
	s_nop 0
	v_addc_co_u32_e32 v19, vcc, 0, v15, vcc
	v_add_co_u32_e32 v28, vcc, s25, v14
	s_add_i32 s14, s14, s16
	s_nop 0
	v_addc_co_u32_e32 v29, vcc, 0, v15, vcc
	v_add_co_u32_e32 v34, vcc, s21, v12
	v_lshl_add_u64 v[112:113], v[112:113], 0, s[8:9]
	s_nop 0
	v_addc_co_u32_e32 v35, vcc, 0, v13, vcc
	v_add_co_u32_e32 v22, vcc, s22, v12
	v_lshl_add_u64 v[114:115], v[114:115], 0, s[10:11]
	s_nop 0
	v_addc_co_u32_e32 v23, vcc, 0, v13, vcc
	v_add_co_u32_e32 v32, vcc, s27, v14
	v_lshl_add_u64 v[116:117], v[116:117], 0, s[18:19]
	s_nop 0
	v_addc_co_u32_e32 v33, vcc, 0, v15, vcc
	v_add_co_u32_e32 v120, vcc, s28, v14
	s_cmpk_gt_i32 s14, 0x3fff
	s_nop 0
	v_addc_co_u32_e32 v121, vcc, 0, v15, vcc
	v_add_co_u32_e32 v122, vcc, s23, v12
	s_nop 1
	v_addc_co_u32_e32 v123, vcc, 0, v13, vcc
	v_add_co_u32_e32 v124, vcc, s30, v8
	s_nop 1
	v_addc_co_u32_e32 v125, vcc, 0, v9, vcc
	v_add_co_u32_e32 v118, vcc, s31, v8
	s_nop 1
	v_addc_co_u32_e32 v119, vcc, 0, v9, vcc
	s_waitcnt vmcnt(30)
	s_nop 1
	v_mov_b32_e32 v8, v224
	v_mov_b32_e32 v9, v225
	s_waitcnt vmcnt(31)
	s_nop 1
	v_mov_b32_e32 v4, v160
	v_mov_b32_e32 v5, v161
	v_mov_b32_e32 v6, v162
	v_mov_b32_e32 v7, v163
	s_waitcnt vmcnt(32) lgkmcnt(0)
	ds_bpermute_b32 v11, v129, v10
	s_waitcnt lgkmcnt(0)
	v_add_f32_e32 v10, v10, v11
	ds_bpermute_b32 v11, v138, v10
	s_waitcnt lgkmcnt(0)
	v_add_f32_e32 v10, v10, v11
	ds_bpermute_b32 v11, v139, v10
	s_waitcnt lgkmcnt(0)
	v_add_f32_e32 v10, v10, v11
	ds_bpermute_b32 v11, v140, v10
	s_waitcnt lgkmcnt(0)
	v_add_f32_e32 v10, v10, v11
	ds_bpermute_b32 v11, v141, v10
	s_waitcnt lgkmcnt(0)
	v_add_f32_e32 v10, v10, v11
	ds_bpermute_b32 v11, v142, v10
	s_waitcnt lgkmcnt(0)
	v_add_f32_e32 v10, v10, v11
	v_fmamk_f32 v10, v10, 0x39800000, v143
	v_mul_f32_e32 v11, 0x4f800000, v10
	v_cmp_gt_f32_e32 vcc, s15, v10
	s_waitcnt lgkmcnt(0)
	v_lshlrev_b32_e32 v14, 16, v8
	v_cndmask_b32_e32 v10, v10, v11, vcc
	v_sqrt_f32_e32 v11, v10
	v_and_b32_e32 v15, 0xffff0000, v8
	v_lshlrev_b32_e32 v8, 16, v9
	v_and_b32_e32 v9, 0xffff0000, v9
	v_add_u32_e32 v20, -1, v11
	v_add_u32_e32 v21, 1, v11
	v_fma_f32 v24, -v20, v11, v10
	v_fma_f32 v25, -v21, v11, v10
	v_cmp_ge_f32_e64 s[2:3], 0, v24
	s_nop 1
	v_cndmask_b32_e64 v11, v11, v20, s[2:3]
	v_cmp_lt_f32_e64 s[2:3], 0, v25
	s_nop 1
	v_cndmask_b32_e64 v11, v11, v21, s[2:3]
	v_mul_f32_e32 v20, 0x37800000, v11
	v_cndmask_b32_e32 v11, v11, v20, vcc
	v_cmp_class_f32_e64 vcc, v10, s92
	s_nop 1
	v_cndmask_b32_e32 v10, v11, v10, vcc
	v_div_scale_f32 v11, s[2:3], v10, v10, 1.0
	v_rcp_f32_e32 v21, v11
	v_div_scale_f32 v20, vcc, 1.0, v10, 1.0
	v_fma_f32 v24, -v11, v21, 1.0
	v_fmac_f32_e32 v21, v24, v21
	v_mul_f32_e32 v24, v20, v21
	v_fma_f32 v25, -v11, v24, v20
	v_fmac_f32_e32 v24, v25, v21
	v_fma_f32 v11, -v11, v24, v20
	v_div_fmas_f32 v11, v11, v21, v24
	v_div_fixup_f32 v128, v11, v10, 1.0
	v_pk_mul_f32 v[10:11], v[128:129], v[14:15] op_sel_hi:[0,1]
	v_pk_mul_f32 v[8:9], v[128:129], v[8:9] op_sel_hi:[0,1]
	s_waitcnt lgkmcnt(0)
	v_pk_fma_f32 v[0:1], v[0:1], v[10:11], v[4:5]
	v_pk_fma_f32 v[2:3], v[2:3], v[8:9], v[6:7]
	global_store_dwordx4 v[28:29], v[0:3], off offset:-4096 nt
	v_mov_b32_e32 v126, v0
	v_mov_b32_e32 v127, v2
	v_mov_b32_e32 v2, v1
	s_waitcnt vmcnt(29)
	s_nop 1
	v_mov_b32_e32 v0, v226
	v_mov_b32_e32 v1, v227
	s_waitcnt vmcnt(30)
	s_nop 1
	v_mov_b32_e32 v4, v164
	v_mov_b32_e32 v5, v165
	v_mov_b32_e32 v6, v166
	v_mov_b32_e32 v7, v167
	ds_read_b128 v[8:11], v144 offset:1024
	v_pk_mul_f32 v[14:15], v[2:3], v[2:3]
	s_nop 0
	v_pk_fma_f32 v[14:15], v[126:127], v[126:127], v[14:15]
	s_nop 0
	v_pk_add_f32 v[40:41], v[14:15], v[14:15] op_sel:[0,1] op_sel_hi:[1,0]
	s_waitcnt lgkmcnt(0)
	v_lshlrev_b32_e32 v14, 16, v0
	v_and_b32_e32 v15, 0xffff0000, v0
	v_lshlrev_b32_e32 v0, 16, v1
	v_and_b32_e32 v1, 0xffff0000, v1
	v_pk_mul_f32 v[14:15], v[128:129], v[14:15] op_sel_hi:[0,1]
	v_pk_mul_f32 v[0:1], v[128:129], v[0:1] op_sel_hi:[0,1]
	s_waitcnt lgkmcnt(0)
	v_pk_fma_f32 v[4:5], v[8:9], v[14:15], v[4:5]
	v_pk_fma_f32 v[6:7], v[10:11], v[0:1], v[6:7]
	global_store_dwordx4 v[18:19], v[4:7], off offset:1024 nt
	v_mov_b32_e32 v0, v4
	v_mov_b32_e32 v1, v6
	v_mov_b32_e32 v6, v5
	s_waitcnt vmcnt(28)
	s_nop 1
	v_mov_b32_e32 v4, v228
	v_mov_b32_e32 v5, v229
	s_waitcnt vmcnt(29)
	s_nop 1
	v_mov_b32_e32 v8, v168
	v_mov_b32_e32 v9, v169
	v_mov_b32_e32 v10, v170
	v_mov_b32_e32 v11, v171
	ds_read_b128 v[24:27], v144 offset:2048
	v_pk_mul_f32 v[14:15], v[6:7], v[6:7]
	s_nop 0
	v_pk_fma_f32 v[14:15], v[0:1], v[0:1], v[14:15]
	s_nop 0
	v_pk_add_f32 v[42:43], v[14:15], v[14:15] op_sel:[0,1] op_sel_hi:[1,0]
	s_waitcnt lgkmcnt(0)
	v_lshlrev_b32_e32 v14, 16, v4
	v_and_b32_e32 v15, 0xffff0000, v4
	v_lshlrev_b32_e32 v4, 16, v5
	v_and_b32_e32 v5, 0xffff0000, v5
	v_pk_mul_f32 v[14:15], v[128:129], v[14:15] op_sel_hi:[0,1]
	v_pk_mul_f32 v[4:5], v[128:129], v[4:5] op_sel_hi:[0,1]
	s_waitcnt lgkmcnt(0)
	v_pk_fma_f32 v[8:9], v[24:25], v[14:15], v[8:9]
	v_pk_fma_f32 v[10:11], v[26:27], v[4:5], v[10:11]
	global_store_dwordx4 v[18:19], v[8:11], off offset:2048 nt
	s_waitcnt vmcnt(27)
	s_nop 1
	v_mov_b32_e32 v44, v230
	v_mov_b32_e32 v45, v231
	s_waitcnt vmcnt(28)
	s_nop 1
	v_mov_b32_e32 v24, v172
	v_mov_b32_e32 v25, v173
	v_mov_b32_e32 v26, v174
	v_mov_b32_e32 v27, v175
	ds_read_b128 v[36:39], v144 offset:3072
	v_mul_f32_e32 v14, v9, v9
	v_mul_f32_e32 v20, v11, v11
	v_mov_b32_e32 v4, v8
	v_mov_b32_e32 v5, v10
	v_pk_fma_f32 v[46:47], v[8:9], v[8:9], v[14:15] op_sel_hi:[1,1,0]
	v_pk_fma_f32 v[48:49], v[10:11], v[10:11], v[20:21] op_sel_hi:[1,1,0]
	v_mov_b32_e32 v10, v9
	s_waitcnt lgkmcnt(0)
	v_lshlrev_b32_e32 v8, 16, v44
	v_and_b32_e32 v9, 0xffff0000, v44
	v_lshlrev_b32_e32 v12, 16, v45
	v_and_b32_e32 v13, 0xffff0000, v45
	v_pk_mul_f32 v[8:9], v[128:129], v[8:9] op_sel_hi:[0,1]
	v_pk_mul_f32 v[14:15], v[128:129], v[12:13] op_sel_hi:[0,1]
	s_waitcnt lgkmcnt(0)
	v_pk_fma_f32 v[12:13], v[36:37], v[8:9], v[24:25]
	v_pk_fma_f32 v[14:15], v[38:39], v[14:15], v[26:27]
	global_store_dwordx4 v[18:19], v[12:15], off offset:3072 nt
	v_pk_mul_f32 v[36:37], v[12:13], v[12:13]
	v_pk_mul_f32 v[38:39], v[14:15], v[14:15]
	v_mov_b32_e32 v8, v12
	v_mov_b32_e32 v9, v14
	v_mov_b32_e32 v14, v13
	s_waitcnt vmcnt(26)
	s_nop 1
	v_mov_b32_e32 v12, v232
	v_mov_b32_e32 v13, v233
	s_waitcnt vmcnt(27)
	s_nop 1
	v_mov_b32_e32 v18, v176
	v_mov_b32_e32 v19, v177
	v_mov_b32_e32 v20, v178
	v_mov_b32_e32 v21, v179
	ds_read_b128 v[24:27], v144 offset:4096
	v_mov_b32_e32 v41, v36
	v_mov_b32_e32 v43, v37
	v_mov_b32_e32 v47, v38
	v_mov_b32_e32 v49, v39
	v_pk_add_f32 v[36:37], v[40:41], v[42:43]
	v_pk_add_f32 v[38:39], v[46:47], v[48:49]
	s_nop 0
	v_pk_add_f32 v[36:37], v[36:37], v[38:39]
	s_nop 0
	v_pk_add_f32 v[46:47], v[36:37], v[36:37] op_sel:[0,1] op_sel_hi:[1,0]
	s_waitcnt lgkmcnt(0)
	v_lshlrev_b32_e32 v36, 16, v12
	v_and_b32_e32 v37, 0xffff0000, v12
	v_lshlrev_b32_e32 v12, 16, v13
	v_and_b32_e32 v13, 0xffff0000, v13
	v_pk_mul_f32 v[36:37], v[128:129], v[36:37] op_sel_hi:[0,1]
	v_pk_mul_f32 v[12:13], v[128:129], v[12:13] op_sel_hi:[0,1]
	s_waitcnt lgkmcnt(0)
	v_pk_fma_f32 v[18:19], v[24:25], v[36:37], v[18:19]
	v_pk_fma_f32 v[20:21], v[26:27], v[12:13], v[20:21]
	global_store_dwordx4 v[28:29], v[18:21], off nt
	v_mov_b32_e32 v12, v18
	v_mov_b32_e32 v13, v20
	v_mov_b32_e32 v20, v19
	s_waitcnt vmcnt(25)
	s_nop 1
	v_mov_b32_e32 v18, v234
	v_mov_b32_e32 v19, v235
	s_waitcnt vmcnt(26)
	s_nop 1
	v_mov_b32_e32 v24, v180
	v_mov_b32_e32 v25, v181
	v_mov_b32_e32 v26, v182
	v_mov_b32_e32 v27, v183
	ds_read_b128 v[36:39], v144 offset:5120
	v_pk_mul_f32 v[40:41], v[20:21], v[20:21]
	s_nop 0
	v_pk_fma_f32 v[40:41], v[12:13], v[12:13], v[40:41]
	s_nop 0
	v_pk_add_f32 v[48:49], v[40:41], v[40:41] op_sel:[0,1] op_sel_hi:[1,0]
	s_waitcnt lgkmcnt(0)
	v_lshlrev_b32_e32 v40, 16, v18
	v_and_b32_e32 v41, 0xffff0000, v18
	v_lshlrev_b32_e32 v18, 16, v19
	v_and_b32_e32 v19, 0xffff0000, v19
	v_pk_mul_f32 v[40:41], v[128:129], v[40:41] op_sel_hi:[0,1]
	v_pk_mul_f32 v[18:19], v[128:129], v[18:19] op_sel_hi:[0,1]
	s_waitcnt lgkmcnt(0)
	v_pk_fma_f32 v[24:25], v[36:37], v[40:41], v[24:25]
	v_pk_fma_f32 v[26:27], v[38:39], v[18:19], v[26:27]
	global_store_dwordx4 v[28:29], v[24:27], off offset:1024 nt
	s_waitcnt vmcnt(24)
	s_nop 1
	v_mov_b32_e32 v50, v236
	v_mov_b32_e32 v51, v237
	s_waitcnt vmcnt(25)
	s_nop 1
	v_mov_b32_e32 v36, v184
	v_mov_b32_e32 v37, v185
	v_mov_b32_e32 v38, v186
	v_mov_b32_e32 v39, v187
	ds_read_b128 v[42:45], v144 offset:6144
	v_mul_f32_e32 v18, v25, v25
	v_mul_f32_e32 v40, v27, v27
	v_mov_b32_e32 v130, v24
	v_mov_b32_e32 v131, v26
	v_pk_fma_f32 v[18:19], v[24:25], v[24:25], v[18:19] op_sel_hi:[1,1,0]
	v_pk_fma_f32 v[52:53], v[26:27], v[26:27], v[40:41] op_sel_hi:[1,1,0]
	v_mov_b32_e32 v26, v25
	s_waitcnt lgkmcnt(0)
	v_lshlrev_b32_e32 v24, 16, v50
	v_and_b32_e32 v25, 0xffff0000, v50
	v_lshlrev_b32_e32 v40, 16, v51
	v_and_b32_e32 v41, 0xffff0000, v51
	v_pk_mul_f32 v[24:25], v[128:129], v[24:25] op_sel_hi:[0,1]
	v_pk_mul_f32 v[40:41], v[128:129], v[40:41] op_sel_hi:[0,1]
	s_waitcnt lgkmcnt(0)
	v_pk_fma_f32 v[42:43], v[42:43], v[24:25], v[36:37]
	v_pk_fma_f32 v[44:45], v[44:45], v[40:41], v[38:39]
	global_store_dwordx4 v[28:29], v[42:45], off offset:2048 nt
	s_waitcnt vmcnt(23)
	s_nop 1
	v_mov_b32_e32 v30, v238
	v_mov_b32_e32 v31, v239
	s_nop 0
	s_waitcnt vmcnt(24)
	s_nop 1
	v_mov_b32_e32 v34, v188
	v_mov_b32_e32 v35, v189
	v_mov_b32_e32 v36, v190
	v_mov_b32_e32 v37, v191
	s_nop 0
	ds_read_b128 v[38:41], v144 offset:7168
	v_pk_mul_f32 v[24:25], v[42:43], v[42:43]
	v_pk_mul_f32 v[50:51], v[44:45], v[44:45]
	v_mov_b32_e32 v47, v24
	v_mov_b32_e32 v49, v25
	v_mov_b32_e32 v19, v50
	v_mov_b32_e32 v53, v51
	v_pk_add_f32 v[24:25], v[46:47], v[48:49]
	v_pk_add_f32 v[18:19], v[18:19], v[52:53]
	v_mov_b32_e32 v134, v42
	v_pk_add_f32 v[18:19], v[24:25], v[18:19]
	v_mov_b32_e32 v135, v44
	v_mov_b32_e32 v44, v43
	v_pk_add_f32 v[18:19], v[18:19], v[18:19] op_sel:[0,1] op_sel_hi:[1,0]
	s_waitcnt lgkmcnt(0)
	v_lshlrev_b32_e32 v24, 16, v30
	v_and_b32_e32 v25, 0xffff0000, v30
	v_lshlrev_b32_e32 v30, 16, v31
	v_and_b32_e32 v31, 0xffff0000, v31
	v_pk_mul_f32 v[24:25], v[128:129], v[24:25] op_sel_hi:[0,1]
	v_pk_mul_f32 v[30:31], v[128:129], v[30:31] op_sel_hi:[0,1]
	s_waitcnt lgkmcnt(0)
	v_pk_fma_f32 v[46:47], v[38:39], v[24:25], v[34:35]
	v_pk_fma_f32 v[48:49], v[40:41], v[30:31], v[36:37]
	global_store_dwordx4 v[28:29], v[46:49], off offset:3072 nt
	s_waitcnt vmcnt(22)
	s_nop 1
	v_mov_b32_e32 v24, v240
	v_mov_b32_e32 v25, v241
	s_nop 0
	s_waitcnt vmcnt(23)
	s_nop 1
	v_mov_b32_e32 v28, v192
	v_mov_b32_e32 v29, v193
	v_mov_b32_e32 v30, v194
	v_mov_b32_e32 v31, v195
	ds_read_b128 v[34:37], v144 offset:8192
	v_mov_b32_e32 v136, v46
	v_mov_b32_e32 v137, v48
	v_mov_b32_e32 v48, v47
	v_pk_mul_f32 v[38:39], v[48:49], v[48:49]
	s_waitcnt lgkmcnt(0)
	v_lshlrev_b32_e32 v40, 16, v24
	v_and_b32_e32 v41, 0xffff0000, v24
	v_lshlrev_b32_e32 v24, 16, v25
	v_and_b32_e32 v25, 0xffff0000, v25
	v_pk_mul_f32 v[40:41], v[128:129], v[40:41] op_sel_hi:[0,1]
	v_pk_mul_f32 v[24:25], v[128:129], v[24:25] op_sel_hi:[0,1]
	s_waitcnt lgkmcnt(0)
	v_pk_fma_f32 v[50:51], v[34:35], v[40:41], v[28:29]
	v_pk_fma_f32 v[52:53], v[36:37], v[24:25], v[30:31]
	global_store_dwordx4 v[120:121], v[50:53], off offset:-4096 nt
	s_waitcnt vmcnt(21)
	s_nop 1
	v_mov_b32_e32 v42, v242
	v_mov_b32_e32 v43, v243
	s_waitcnt vmcnt(22)
	s_nop 1
	v_mov_b32_e32 v28, v196
	v_mov_b32_e32 v29, v197
	v_mov_b32_e32 v30, v198
	v_mov_b32_e32 v31, v199
	ds_read_b128 v[34:37], v144 offset:9216
	v_mul_f32_e32 v40, v53, v53
	v_pk_fma_f32 v[46:47], v[52:53], v[52:53], v[40:41] op_sel_hi:[1,1,0]
	v_mul_f32_e32 v24, v51, v51
	v_mov_b32_e32 v150, v50
	v_mov_b32_e32 v151, v52
	v_pk_fma_f32 v[24:25], v[50:51], v[50:51], v[24:25] op_sel_hi:[1,1,0]
	v_mov_b32_e32 v52, v51
	v_pk_fma_f32 v[38:39], v[136:137], v[136:137], v[38:39]
	s_waitcnt lgkmcnt(0)
	v_lshlrev_b32_e32 v40, 16, v42
	v_and_b32_e32 v41, 0xffff0000, v42
	v_lshlrev_b32_e32 v42, 16, v43
	v_and_b32_e32 v43, 0xffff0000, v43
	v_pk_mul_f32 v[40:41], v[128:129], v[40:41] op_sel_hi:[0,1]
	v_pk_mul_f32 v[42:43], v[128:129], v[42:43] op_sel_hi:[0,1]
	s_waitcnt lgkmcnt(0)
	v_pk_fma_f32 v[34:35], v[34:35], v[40:41], v[28:29]
	v_pk_fma_f32 v[36:37], v[36:37], v[42:43], v[30:31]
	global_store_dwordx4 v[32:33], v[34:37], off offset:1024 nt
	v_pk_mul_f32 v[132:133], v[34:35], v[34:35]
	v_pk_mul_f32 v[146:147], v[36:37], v[36:37]
	v_mov_b32_e32 v50, v34
	v_mov_b32_e32 v51, v36
	v_mov_b32_e32 v36, v35
	s_waitcnt vmcnt(20)
	s_nop 1
	v_mov_b32_e32 v34, v244
	v_mov_b32_e32 v35, v245
	s_waitcnt vmcnt(21)
	s_nop 1
	v_mov_b32_e32 v28, v200
	v_mov_b32_e32 v29, v201
	v_mov_b32_e32 v30, v202
	v_mov_b32_e32 v31, v203
	ds_read_b128 v[40:43], v144 offset:10240
	v_pk_add_f32 v[38:39], v[38:39], v[38:39] op_sel:[0,1] op_sel_hi:[1,0]
	v_mov_b32_e32 v19, v132
	v_mov_b32_e32 v39, v133
	v_mov_b32_e32 v25, v146
	v_mov_b32_e32 v47, v147
	v_pk_add_f32 v[18:19], v[18:19], v[38:39]
	v_pk_add_f32 v[24:25], v[24:25], v[46:47]
	s_nop 0
	v_pk_add_f32 v[18:19], v[18:19], v[24:25]
	s_waitcnt lgkmcnt(0)
	v_lshlrev_b32_e32 v24, 16, v34
	v_and_b32_e32 v25, 0xffff0000, v34
	v_lshlrev_b32_e32 v34, 16, v35
	v_and_b32_e32 v35, 0xffff0000, v35
	v_pk_mul_f32 v[24:25], v[128:129], v[24:25] op_sel_hi:[0,1]
	v_pk_mul_f32 v[34:35], v[128:129], v[34:35] op_sel_hi:[0,1]
	s_waitcnt lgkmcnt(0)
	v_pk_fma_f32 v[40:41], v[40:41], v[24:25], v[28:29]
	v_pk_fma_f32 v[42:43], v[42:43], v[34:35], v[30:31]
	global_store_dwordx4 v[32:33], v[40:43], off offset:2048 nt
	s_waitcnt vmcnt(19)
	s_nop 1
	v_mov_b32_e32 v34, v246
	v_mov_b32_e32 v35, v247
	s_nop 0
	s_waitcnt vmcnt(20)
	s_nop 1
	v_mov_b32_e32 v22, v204
	v_mov_b32_e32 v23, v205
	v_mov_b32_e32 v24, v206
	v_mov_b32_e32 v25, v207
	s_nop 0
	ds_read_b128 v[28:31], v144 offset:11264
	v_mov_b32_e32 v133, v42
	v_mov_b32_e32 v42, v41
	v_mov_b32_e32 v132, v40
	v_pk_mul_f32 v[38:39], v[42:43], v[42:43]
	v_pk_add_f32 v[18:19], v[18:19], v[18:19] op_sel:[0,1] op_sel_hi:[1,0]
	v_pk_fma_f32 v[38:39], v[132:133], v[132:133], v[38:39]
	s_nop 0
	v_pk_add_f32 v[46:47], v[38:39], v[38:39] op_sel:[0,1] op_sel_hi:[1,0]
	s_waitcnt lgkmcnt(0)
	v_lshlrev_b32_e32 v38, 16, v34
	v_and_b32_e32 v39, 0xffff0000, v34
	v_lshlrev_b32_e32 v34, 16, v35
	v_and_b32_e32 v35, 0xffff0000, v35
	v_pk_mul_f32 v[38:39], v[128:129], v[38:39] op_sel_hi:[0,1]
	v_pk_mul_f32 v[34:35], v[128:129], v[34:35] op_sel_hi:[0,1]
	s_waitcnt lgkmcnt(0)
	v_pk_fma_f32 v[38:39], v[28:29], v[38:39], v[22:23]
	v_pk_fma_f32 v[40:41], v[30:31], v[34:35], v[24:25]
	global_store_dwordx4 v[32:33], v[38:41], off offset:3072 nt
	s_waitcnt vmcnt(18)
	s_nop 1
	v_mov_b32_e32 v146, v248
	v_mov_b32_e32 v147, v249
	s_waitcnt vmcnt(19)
	s_nop 1
	v_mov_b32_e32 v22, v208
	v_mov_b32_e32 v23, v209
	v_mov_b32_e32 v24, v210
	v_mov_b32_e32 v25, v211
	ds_read_b128 v[28:31], v144 offset:12288
	v_mul_f32_e32 v32, v39, v39
	v_mul_f32_e32 v34, v41, v41
	v_pk_fma_f32 v[148:149], v[38:39], v[38:39], v[32:33] op_sel_hi:[1,1,0]
	v_pk_fma_f32 v[152:153], v[40:41], v[40:41], v[34:35] op_sel_hi:[1,1,0]
	s_waitcnt lgkmcnt(0)
	v_lshlrev_b32_e32 v32, 16, v146
	v_and_b32_e32 v33, 0xffff0000, v146
	v_lshlrev_b32_e32 v34, 16, v147
	v_and_b32_e32 v35, 0xffff0000, v147
	v_pk_mul_f32 v[32:33], v[128:129], v[32:33] op_sel_hi:[0,1]
	v_pk_mul_f32 v[34:35], v[128:129], v[34:35] op_sel_hi:[0,1]
	s_waitcnt lgkmcnt(0)
	v_pk_fma_f32 v[32:33], v[28:29], v[32:33], v[22:23]
	v_pk_fma_f32 v[34:35], v[30:31], v[34:35], v[24:25]
	global_store_dwordx4 v[120:121], v[32:35], off nt
	s_waitcnt vmcnt(17)
	s_nop 1
	v_mov_b32_e32 v156, v250
	v_mov_b32_e32 v157, v251
	s_waitcnt vmcnt(18)
	s_nop 1
	v_mov_b32_e32 v22, v212
	v_mov_b32_e32 v23, v213
	v_mov_b32_e32 v24, v214
	v_mov_b32_e32 v25, v215
	ds_read_b128 v[28:31], v144 offset:13312
	v_pk_mul_f32 v[146:147], v[32:33], v[32:33]
	v_pk_mul_f32 v[154:155], v[34:35], v[34:35]
	v_mov_b32_e32 v19, v146
	v_mov_b32_e32 v47, v147
	v_mov_b32_e32 v149, v154
	v_mov_b32_e32 v153, v155
	v_pk_add_f32 v[18:19], v[18:19], v[46:47]
	v_pk_add_f32 v[46:47], v[148:149], v[152:153]
	s_nop 0
	v_pk_add_f32 v[18:19], v[18:19], v[46:47]
	s_waitcnt lgkmcnt(0)
	v_lshlrev_b32_e32 v46, 16, v157
	v_pk_add_f32 v[152:153], v[18:19], v[18:19] op_sel:[0,1] op_sel_hi:[1,0]
	v_lshlrev_b32_e32 v18, 16, v156
	v_and_b32_e32 v19, 0xffff0000, v156
	v_and_b32_e32 v47, 0xffff0000, v157
	v_pk_mul_f32 v[18:19], v[128:129], v[18:19] op_sel_hi:[0,1]
	v_pk_mul_f32 v[46:47], v[128:129], v[46:47] op_sel_hi:[0,1]
	s_waitcnt lgkmcnt(0)
	v_pk_fma_f32 v[28:29], v[28:29], v[18:19], v[22:23]
	v_pk_fma_f32 v[30:31], v[30:31], v[46:47], v[24:25]
	global_store_dwordx4 v[120:121], v[28:31], off offset:1024 nt
	s_waitcnt vmcnt(16)
	s_nop 1
	v_mov_b32_e32 v18, v252
	v_mov_b32_e32 v19, v253
	s_waitcnt vmcnt(17)
	s_nop 1
	v_mov_b32_e32 v22, v216
	v_mov_b32_e32 v23, v217
	v_mov_b32_e32 v24, v218
	v_mov_b32_e32 v25, v219
	ds_read_b128 v[146:149], v144 offset:14336
	v_mov_b32_e32 v47, v30
	v_mov_b32_e32 v30, v29
	v_mov_b32_e32 v46, v28
	v_pk_mul_f32 v[28:29], v[30:31], v[30:31]
	s_waitcnt lgkmcnt(0)
	v_lshlrev_b32_e32 v154, 16, v18
	v_and_b32_e32 v155, 0xffff0000, v18
	v_lshlrev_b32_e32 v18, 16, v19
	v_and_b32_e32 v19, 0xffff0000, v19
	v_pk_mul_f32 v[154:155], v[128:129], v[154:155] op_sel_hi:[0,1]
	v_pk_mul_f32 v[18:19], v[128:129], v[18:19] op_sel_hi:[0,1]
	s_waitcnt lgkmcnt(0)
	v_pk_fma_f32 v[22:23], v[146:147], v[154:155], v[22:23]
	v_pk_fma_f32 v[24:25], v[148:149], v[18:19], v[24:25]
	global_store_dwordx4 v[120:121], v[22:25], off offset:2048 nt
	s_waitcnt vmcnt(15)
	s_nop 1
	v_mov_b32_e32 v158, v254
	v_mov_b32_e32 v159, v255
	s_nop 0
	s_waitcnt vmcnt(16)
	s_nop 1
	v_mov_b32_e32 v16, v220
	v_mov_b32_e32 v17, v221
	v_mov_b32_e32 v18, v222
	v_mov_b32_e32 v19, v223
	ds_read_b128 v[146:149], v144 offset:15360
	v_pk_fma_f32 v[28:29], v[46:47], v[46:47], v[28:29]
	v_mul_f32_e32 v154, v23, v23
	v_mul_f32_e32 v156, v25, v25
	v_pk_add_f32 v[28:29], v[28:29], v[28:29] op_sel:[0,1] op_sel_hi:[1,0]
	v_pk_fma_f32 v[154:155], v[22:23], v[22:23], v[154:155] op_sel_hi:[1,1,0]
	v_pk_fma_f32 v[156:157], v[24:25], v[24:25], v[156:157] op_sel_hi:[1,1,0]
	s_waitcnt lgkmcnt(0)
	v_lshlrev_b32_e32 v122, 16, v158
	v_and_b32_e32 v123, 0xffff0000, v158
	v_lshlrev_b32_e32 v158, 16, v159
	v_and_b32_e32 v159, 0xffff0000, v159
	v_pk_mul_f32 v[122:123], v[128:129], v[122:123] op_sel_hi:[0,1]
	v_pk_mul_f32 v[158:159], v[128:129], v[158:159] op_sel_hi:[0,1]
	s_waitcnt lgkmcnt(0)
	v_pk_fma_f32 v[16:17], v[146:147], v[122:123], v[16:17]
	v_pk_fma_f32 v[18:19], v[148:149], v[158:159], v[18:19]
	global_store_dwordx4 v[120:121], v[16:19], off offset:3072 nt
	v_pk_mul_f32 v[120:121], v[16:17], v[16:17]
	v_pk_mul_f32 v[122:123], v[18:19], v[18:19]
	v_mov_b32_e32 v153, v120
	v_mov_b32_e32 v29, v121
	v_mov_b32_e32 v155, v122
	v_mov_b32_e32 v157, v123
	ds_read_b128 v[120:123], v144 offset:16384
	v_pk_add_f32 v[28:29], v[152:153], v[28:29]
	v_pk_add_f32 v[146:147], v[154:155], v[156:157]
	s_nop 0
	v_pk_add_f32 v[28:29], v[28:29], v[146:147]
	s_nop 0
	v_add_f32_e32 v28, v28, v29
	ds_bpermute_b32 v29, v129, v28
	s_waitcnt lgkmcnt(0)
	v_add_f32_e32 v28, v28, v29
	ds_bpermute_b32 v29, v138, v28
	s_waitcnt lgkmcnt(0)
	v_add_f32_e32 v28, v28, v29
	ds_bpermute_b32 v29, v139, v28
	s_waitcnt lgkmcnt(0)
	v_add_f32_e32 v28, v28, v29
	ds_bpermute_b32 v29, v140, v28
	s_waitcnt lgkmcnt(0)
	v_add_f32_e32 v28, v28, v29
	ds_bpermute_b32 v29, v141, v28
	s_waitcnt lgkmcnt(0)
	v_add_f32_e32 v28, v28, v29
	ds_bpermute_b32 v29, v142, v28
	s_waitcnt lgkmcnt(0)
	v_add_f32_e32 v28, v28, v29
	v_fmamk_f32 v28, v28, 0x39800000, v143
	v_mul_f32_e32 v29, 0x4f800000, v28
	v_cmp_gt_f32_e32 vcc, s15, v28
	s_nop 1
	v_cndmask_b32_e32 v28, v28, v29, vcc
	v_sqrt_f32_e32 v29, v28
	s_nop 0
	v_add_u32_e32 v128, -1, v29
	v_add_u32_e32 v146, 1, v29
	v_fma_f32 v147, -v128, v29, v28
	v_fma_f32 v148, -v146, v29, v28
	v_cmp_ge_f32_e64 s[2:3], 0, v147
	s_nop 1
	v_cndmask_b32_e64 v29, v29, v128, s[2:3]
	v_cmp_lt_f32_e64 s[2:3], 0, v148
	s_nop 1
	v_cndmask_b32_e64 v29, v29, v146, s[2:3]
	v_mul_f32_e32 v128, 0x37800000, v29
	v_cndmask_b32_e32 v29, v29, v128, vcc
	v_cmp_class_f32_e64 vcc, v28, s92
	s_nop 1
	v_cndmask_b32_e32 v28, v29, v28, vcc
	v_div_scale_f32 v29, s[2:3], v28, v28, 1.0
	v_rcp_f32_e32 v146, v29
	v_div_scale_f32 v128, vcc, 1.0, v28, 1.0
	v_fma_f32 v147, -v29, v146, 1.0
	v_fmac_f32_e32 v146, v147, v146
	v_mul_f32_e32 v147, v128, v146
	v_fma_f32 v148, -v29, v147, v128
	v_fmac_f32_e32 v147, v148, v146
	v_fma_f32 v29, -v29, v147, v128
	v_div_fmas_f32 v29, v29, v146, v147
	v_div_fixup_f32 v28, v29, v28, 1.0
	v_pk_mul_f32 v[2:3], v[2:3], v[28:29] op_sel_hi:[1,0]
	v_pk_mul_f32 v[146:147], v[0:1], v[28:29] op_sel_hi:[1,0]
	s_waitcnt lgkmcnt(0)
	v_mov_b32_e32 v1, v122
	v_mov_b32_e32 v122, v121
	v_pk_mul_f32 v[126:127], v[126:127], v[28:29] op_sel_hi:[1,0]
	v_mov_b32_e32 v0, v120
	v_pk_mul_f32 v[2:3], v[122:123], v[2:3]
	v_pk_mul_f32 v[0:1], v[0:1], v[126:127]
	v_and_b32_sdwa v121, v3, v145 dst_sel:DWORD dst_unused:UNUSED_PAD src0_sel:WORD_1 src1_sel:DWORD
	v_and_b32_sdwa v122, v2, v145 dst_sel:DWORD dst_unused:UNUSED_PAD src0_sel:WORD_1 src1_sel:DWORD
	v_pk_mul_f32 v[6:7], v[6:7], v[28:29] op_sel_hi:[1,0]
	v_pk_mul_f32 v[4:5], v[4:5], v[28:29] op_sel_hi:[1,0]
	v_pk_mul_f32 v[10:11], v[10:11], v[28:29] op_sel_hi:[1,0]
	v_pk_mul_f32 v[8:9], v[8:9], v[28:29] op_sel_hi:[1,0]
	v_pk_mul_f32 v[14:15], v[14:15], v[28:29] op_sel_hi:[1,0]
	v_pk_mul_f32 v[12:13], v[12:13], v[28:29] op_sel_hi:[1,0]
	v_pk_mul_f32 v[20:21], v[20:21], v[28:29] op_sel_hi:[1,0]
	v_pk_mul_f32 v[130:131], v[130:131], v[28:29] op_sel_hi:[1,0]
	v_pk_mul_f32 v[26:27], v[26:27], v[28:29] op_sel_hi:[1,0]
	v_pk_mul_f32 v[134:135], v[134:135], v[28:29] op_sel_hi:[1,0]
	v_pk_mul_f32 v[44:45], v[44:45], v[28:29] op_sel_hi:[1,0]
	v_pk_mul_f32 v[136:137], v[136:137], v[28:29] op_sel_hi:[1,0]
	v_pk_mul_f32 v[48:49], v[48:49], v[28:29] op_sel_hi:[1,0]
	v_pk_mul_f32 v[148:149], v[150:151], v[28:29] op_sel_hi:[1,0]
	v_pk_mul_f32 v[52:53], v[52:53], v[28:29] op_sel_hi:[1,0]
	v_and_b32_sdwa v29, v1, v145 dst_sel:DWORD dst_unused:UNUSED_PAD src0_sel:WORD_1 src1_sel:DWORD
	v_and_b32_sdwa v120, v0, v145 dst_sel:DWORD dst_unused:UNUSED_PAD src0_sel:WORD_1 src1_sel:DWORD
	v_add3_u32 v3, v3, v121, s29
	v_add3_u32 v2, v2, v122, s29
	v_add3_u32 v0, v0, v120, s29
	v_add3_u32 v1, v1, v29, s29
	v_and_b32_e32 v3, 0xffff0000, v3
	v_and_b32_e32 v2, 0xffff0000, v2
	v_or_b32_sdwa v1, v3, v1 dst_sel:DWORD dst_unused:UNUSED_PAD src0_sel:DWORD src1_sel:WORD_1
	v_or_b32_sdwa v0, v2, v0 dst_sel:DWORD dst_unused:UNUSED_PAD src0_sel:DWORD src1_sel:WORD_1
	global_store_dwordx2 v[118:119], v[0:1], off offset:-4096
	ds_read_b128 v[0:3], v144 offset:17408
	s_waitcnt lgkmcnt(0)
	v_mov_b32_e32 v121, v2
	v_mov_b32_e32 v2, v1
	v_mov_b32_e32 v120, v0
	v_pk_mul_f32 v[2:3], v[2:3], v[6:7]
	v_pk_mul_f32 v[0:1], v[120:121], v[146:147]
	v_and_b32_sdwa v29, v3, v145 dst_sel:DWORD dst_unused:UNUSED_PAD src0_sel:WORD_1 src1_sel:DWORD
	v_and_b32_sdwa v120, v2, v145 dst_sel:DWORD dst_unused:UNUSED_PAD src0_sel:WORD_1 src1_sel:DWORD
	v_and_b32_sdwa v6, v1, v145 dst_sel:DWORD dst_unused:UNUSED_PAD src0_sel:WORD_1 src1_sel:DWORD
	v_and_b32_sdwa v7, v0, v145 dst_sel:DWORD dst_unused:UNUSED_PAD src0_sel:WORD_1 src1_sel:DWORD
	v_add3_u32 v3, v3, v29, s29
	v_add3_u32 v2, v2, v120, s29
	v_add3_u32 v0, v0, v7, s29
	v_add3_u32 v1, v1, v6, s29
	v_and_b32_e32 v3, 0xffff0000, v3
	v_and_b32_e32 v2, 0xffff0000, v2
	v_or_b32_sdwa v1, v3, v1 dst_sel:DWORD dst_unused:UNUSED_PAD src0_sel:DWORD src1_sel:WORD_1
	v_or_b32_sdwa v0, v2, v0 dst_sel:DWORD dst_unused:UNUSED_PAD src0_sel:DWORD src1_sel:WORD_1
	global_store_dwordx2 v[124:125], v[0:1], off offset:512
	ds_read_b128 v[0:3], v144 offset:18432
	s_waitcnt lgkmcnt(0)
	v_mov_b32_e32 v7, v2
	v_mov_b32_e32 v2, v1
	v_mov_b32_e32 v6, v0
	v_pk_mul_f32 v[2:3], v[2:3], v[10:11]
	v_pk_mul_f32 v[0:1], v[6:7], v[4:5]
	v_and_b32_sdwa v6, v3, v145 dst_sel:DWORD dst_unused:UNUSED_PAD src0_sel:WORD_1 src1_sel:DWORD
	v_and_b32_sdwa v7, v2, v145 dst_sel:DWORD dst_unused:UNUSED_PAD src0_sel:WORD_1 src1_sel:DWORD
	v_and_b32_sdwa v4, v1, v145 dst_sel:DWORD dst_unused:UNUSED_PAD src0_sel:WORD_1 src1_sel:DWORD
	v_and_b32_sdwa v5, v0, v145 dst_sel:DWORD dst_unused:UNUSED_PAD src0_sel:WORD_1 src1_sel:DWORD
	v_add3_u32 v3, v3, v6, s29
	v_add3_u32 v2, v2, v7, s29
	v_add3_u32 v0, v0, v5, s29
	v_add3_u32 v1, v1, v4, s29
	v_and_b32_e32 v3, 0xffff0000, v3
	v_and_b32_e32 v2, 0xffff0000, v2
	v_or_b32_sdwa v1, v3, v1 dst_sel:DWORD dst_unused:UNUSED_PAD src0_sel:DWORD src1_sel:WORD_1
	v_or_b32_sdwa v0, v2, v0 dst_sel:DWORD dst_unused:UNUSED_PAD src0_sel:DWORD src1_sel:WORD_1
	global_store_dwordx2 v[124:125], v[0:1], off offset:1024
	ds_read_b128 v[0:3], v144 offset:19456
	s_waitcnt lgkmcnt(0)
	v_mov_b32_e32 v5, v2
	v_mov_b32_e32 v2, v1
	v_mov_b32_e32 v4, v0
	v_pk_mul_f32 v[2:3], v[2:3], v[14:15]
	v_pk_mul_f32 v[0:1], v[4:5], v[8:9]
	v_and_b32_sdwa v6, v3, v145 dst_sel:DWORD dst_unused:UNUSED_PAD src0_sel:WORD_1 src1_sel:DWORD
	v_and_b32_sdwa v7, v2, v145 dst_sel:DWORD dst_unused:UNUSED_PAD src0_sel:WORD_1 src1_sel:DWORD
	v_and_b32_sdwa v4, v1, v145 dst_sel:DWORD dst_unused:UNUSED_PAD src0_sel:WORD_1 src1_sel:DWORD
	v_and_b32_sdwa v5, v0, v145 dst_sel:DWORD dst_unused:UNUSED_PAD src0_sel:WORD_1 src1_sel:DWORD
	v_add3_u32 v3, v3, v6, s29
	v_add3_u32 v2, v2, v7, s29
	v_add3_u32 v0, v0, v5, s29
	v_add3_u32 v1, v1, v4, s29
	v_and_b32_e32 v3, 0xffff0000, v3
	v_and_b32_e32 v2, 0xffff0000, v2
	v_or_b32_sdwa v1, v3, v1 dst_sel:DWORD dst_unused:UNUSED_PAD src0_sel:DWORD src1_sel:WORD_1
	v_or_b32_sdwa v0, v2, v0 dst_sel:DWORD dst_unused:UNUSED_PAD src0_sel:DWORD src1_sel:WORD_1
	global_store_dwordx2 v[124:125], v[0:1], off offset:1536
	ds_read_b128 v[0:3], v144 offset:20480
	s_waitcnt lgkmcnt(0)
	v_mov_b32_e32 v5, v2
	v_mov_b32_e32 v2, v1
	v_mov_b32_e32 v4, v0
	v_pk_mul_f32 v[2:3], v[2:3], v[20:21]
	v_pk_mul_f32 v[0:1], v[4:5], v[12:13]
	v_and_b32_sdwa v6, v3, v145 dst_sel:DWORD dst_unused:UNUSED_PAD src0_sel:WORD_1 src1_sel:DWORD
	v_and_b32_sdwa v7, v2, v145 dst_sel:DWORD dst_unused:UNUSED_PAD src0_sel:WORD_1 src1_sel:DWORD
	v_and_b32_sdwa v4, v1, v145 dst_sel:DWORD dst_unused:UNUSED_PAD src0_sel:WORD_1 src1_sel:DWORD
	v_and_b32_sdwa v5, v0, v145 dst_sel:DWORD dst_unused:UNUSED_PAD src0_sel:WORD_1 src1_sel:DWORD
	v_add3_u32 v3, v3, v6, s29
	v_add3_u32 v2, v2, v7, s29
	v_add3_u32 v0, v0, v5, s29
	v_add3_u32 v1, v1, v4, s29
	v_and_b32_e32 v3, 0xffff0000, v3
	v_and_b32_e32 v2, 0xffff0000, v2
	v_or_b32_sdwa v1, v3, v1 dst_sel:DWORD dst_unused:UNUSED_PAD src0_sel:DWORD src1_sel:WORD_1
	v_or_b32_sdwa v0, v2, v0 dst_sel:DWORD dst_unused:UNUSED_PAD src0_sel:DWORD src1_sel:WORD_1
	global_store_dwordx2 v[124:125], v[0:1], off offset:2048
	ds_read_b128 v[0:3], v144 offset:21504
	s_waitcnt lgkmcnt(0)
	v_mov_b32_e32 v5, v2
	v_mov_b32_e32 v2, v1
	v_mov_b32_e32 v4, v0
	v_pk_mul_f32 v[2:3], v[2:3], v[26:27]
	v_pk_mul_f32 v[0:1], v[4:5], v[130:131]
	v_and_b32_sdwa v6, v3, v145 dst_sel:DWORD dst_unused:UNUSED_PAD src0_sel:WORD_1 src1_sel:DWORD
	v_and_b32_sdwa v7, v2, v145 dst_sel:DWORD dst_unused:UNUSED_PAD src0_sel:WORD_1 src1_sel:DWORD
	v_and_b32_sdwa v4, v1, v145 dst_sel:DWORD dst_unused:UNUSED_PAD src0_sel:WORD_1 src1_sel:DWORD
	v_and_b32_sdwa v5, v0, v145 dst_sel:DWORD dst_unused:UNUSED_PAD src0_sel:WORD_1 src1_sel:DWORD
	v_add3_u32 v3, v3, v6, s29
	v_add3_u32 v2, v2, v7, s29
	v_add3_u32 v0, v0, v5, s29
	v_add3_u32 v1, v1, v4, s29
	v_and_b32_e32 v3, 0xffff0000, v3
	v_and_b32_e32 v2, 0xffff0000, v2
	v_or_b32_sdwa v1, v3, v1 dst_sel:DWORD dst_unused:UNUSED_PAD src0_sel:DWORD src1_sel:WORD_1
	v_or_b32_sdwa v0, v2, v0 dst_sel:DWORD dst_unused:UNUSED_PAD src0_sel:DWORD src1_sel:WORD_1
	global_store_dwordx2 v[124:125], v[0:1], off offset:2560
	ds_read_b128 v[0:3], v144 offset:22528
	s_waitcnt lgkmcnt(0)
	v_mov_b32_e32 v5, v2
	v_mov_b32_e32 v2, v1
	v_mov_b32_e32 v4, v0
	v_pk_mul_f32 v[2:3], v[44:45], v[2:3]
	v_pk_mul_f32 v[0:1], v[134:135], v[4:5]
	v_and_b32_sdwa v6, v3, v145 dst_sel:DWORD dst_unused:UNUSED_PAD src0_sel:WORD_1 src1_sel:DWORD
	v_and_b32_sdwa v7, v2, v145 dst_sel:DWORD dst_unused:UNUSED_PAD src0_sel:WORD_1 src1_sel:DWORD
	v_and_b32_sdwa v4, v1, v145 dst_sel:DWORD dst_unused:UNUSED_PAD src0_sel:WORD_1 src1_sel:DWORD
	v_and_b32_sdwa v5, v0, v145 dst_sel:DWORD dst_unused:UNUSED_PAD src0_sel:WORD_1 src1_sel:DWORD
	v_add3_u32 v3, v3, v6, s29
	v_add3_u32 v2, v2, v7, s29
	v_add3_u32 v0, v0, v5, s29
	v_add3_u32 v1, v1, v4, s29
	v_and_b32_e32 v3, 0xffff0000, v3
	v_and_b32_e32 v2, 0xffff0000, v2
	v_or_b32_sdwa v1, v3, v1 dst_sel:DWORD dst_unused:UNUSED_PAD src0_sel:DWORD src1_sel:WORD_1
	v_or_b32_sdwa v0, v2, v0 dst_sel:DWORD dst_unused:UNUSED_PAD src0_sel:DWORD src1_sel:WORD_1
	global_store_dwordx2 v[124:125], v[0:1], off offset:3072
	ds_read_b128 v[0:3], v144 offset:23552
	s_waitcnt lgkmcnt(0)
	v_mov_b32_e32 v5, v2
	v_mov_b32_e32 v2, v1
	v_mov_b32_e32 v4, v0
	v_pk_mul_f32 v[2:3], v[48:49], v[2:3]
	v_pk_mul_f32 v[0:1], v[136:137], v[4:5]
	v_and_b32_sdwa v6, v3, v145 dst_sel:DWORD dst_unused:UNUSED_PAD src0_sel:WORD_1 src1_sel:DWORD
	v_and_b32_sdwa v7, v2, v145 dst_sel:DWORD dst_unused:UNUSED_PAD src0_sel:WORD_1 src1_sel:DWORD
	v_and_b32_sdwa v4, v1, v145 dst_sel:DWORD dst_unused:UNUSED_PAD src0_sel:WORD_1 src1_sel:DWORD
	v_and_b32_sdwa v5, v0, v145 dst_sel:DWORD dst_unused:UNUSED_PAD src0_sel:WORD_1 src1_sel:DWORD
	v_add3_u32 v3, v3, v6, s29
	v_add3_u32 v2, v2, v7, s29
	v_add3_u32 v0, v0, v5, s29
	v_add3_u32 v1, v1, v4, s29
	v_and_b32_e32 v3, 0xffff0000, v3
	v_and_b32_e32 v2, 0xffff0000, v2
	v_or_b32_sdwa v1, v3, v1 dst_sel:DWORD dst_unused:UNUSED_PAD src0_sel:DWORD src1_sel:WORD_1
	v_or_b32_sdwa v0, v2, v0 dst_sel:DWORD dst_unused:UNUSED_PAD src0_sel:DWORD src1_sel:WORD_1
	global_store_dwordx2 v[124:125], v[0:1], off offset:3584
	ds_read_b128 v[0:3], v144 offset:24576
	s_waitcnt lgkmcnt(0)
	v_mov_b32_e32 v5, v2
	v_mov_b32_e32 v2, v1
	v_mov_b32_e32 v4, v0
	v_pk_mul_f32 v[2:3], v[52:53], v[2:3]
	v_pk_mul_f32 v[0:1], v[148:149], v[4:5]
	v_and_b32_sdwa v6, v3, v145 dst_sel:DWORD dst_unused:UNUSED_PAD src0_sel:WORD_1 src1_sel:DWORD
	v_and_b32_sdwa v7, v2, v145 dst_sel:DWORD dst_unused:UNUSED_PAD src0_sel:WORD_1 src1_sel:DWORD
	v_and_b32_sdwa v4, v1, v145 dst_sel:DWORD dst_unused:UNUSED_PAD src0_sel:WORD_1 src1_sel:DWORD
	v_and_b32_sdwa v5, v0, v145 dst_sel:DWORD dst_unused:UNUSED_PAD src0_sel:WORD_1 src1_sel:DWORD
	v_add3_u32 v3, v3, v6, s29
	v_add3_u32 v2, v2, v7, s29
	v_add3_u32 v0, v0, v5, s29
	v_add3_u32 v1, v1, v4, s29
	v_and_b32_e32 v3, 0xffff0000, v3
	v_and_b32_e32 v2, 0xffff0000, v2
	v_or_b32_sdwa v1, v3, v1 dst_sel:DWORD dst_unused:UNUSED_PAD src0_sel:DWORD src1_sel:WORD_1
	v_or_b32_sdwa v0, v2, v0 dst_sel:DWORD dst_unused:UNUSED_PAD src0_sel:DWORD src1_sel:WORD_1
	global_store_dwordx2 v[118:119], v[0:1], off
	ds_read_b128 v[0:3], v144 offset:25600
	v_pk_mul_f32 v[6:7], v[36:37], v[28:29] op_sel_hi:[1,0]
	v_pk_mul_f32 v[4:5], v[50:51], v[28:29] op_sel_hi:[1,0]
	s_waitcnt lgkmcnt(0)
	v_mov_b32_e32 v9, v2
	v_mov_b32_e32 v2, v1
	v_mov_b32_e32 v8, v0
	v_pk_mul_f32 v[2:3], v[6:7], v[2:3]
	v_pk_mul_f32 v[0:1], v[4:5], v[8:9]
	v_and_b32_sdwa v6, v3, v145 dst_sel:DWORD dst_unused:UNUSED_PAD src0_sel:WORD_1 src1_sel:DWORD
	v_and_b32_sdwa v7, v2, v145 dst_sel:DWORD dst_unused:UNUSED_PAD src0_sel:WORD_1 src1_sel:DWORD
	v_and_b32_sdwa v4, v1, v145 dst_sel:DWORD dst_unused:UNUSED_PAD src0_sel:WORD_1 src1_sel:DWORD
	v_and_b32_sdwa v5, v0, v145 dst_sel:DWORD dst_unused:UNUSED_PAD src0_sel:WORD_1 src1_sel:DWORD
	v_add3_u32 v3, v3, v6, s29
	v_add3_u32 v2, v2, v7, s29
	v_add3_u32 v0, v0, v5, s29
	v_add3_u32 v1, v1, v4, s29
	v_and_b32_e32 v3, 0xffff0000, v3
	v_and_b32_e32 v2, 0xffff0000, v2
	v_or_b32_sdwa v1, v3, v1 dst_sel:DWORD dst_unused:UNUSED_PAD src0_sel:DWORD src1_sel:WORD_1
	v_or_b32_sdwa v0, v2, v0 dst_sel:DWORD dst_unused:UNUSED_PAD src0_sel:DWORD src1_sel:WORD_1
	global_store_dwordx2 v[118:119], v[0:1], off offset:512
	ds_read_b128 v[0:3], v144 offset:26624
	v_pk_mul_f32 v[6:7], v[42:43], v[28:29] op_sel_hi:[1,0]
	v_pk_mul_f32 v[4:5], v[132:133], v[28:29] op_sel_hi:[1,0]
	s_waitcnt lgkmcnt(0)
	v_mov_b32_e32 v9, v2
	v_mov_b32_e32 v2, v1
	v_mov_b32_e32 v8, v0
	v_pk_mul_f32 v[2:3], v[6:7], v[2:3]
	v_pk_mul_f32 v[0:1], v[4:5], v[8:9]
	v_and_b32_sdwa v6, v3, v145 dst_sel:DWORD dst_unused:UNUSED_PAD src0_sel:WORD_1 src1_sel:DWORD
	v_and_b32_sdwa v7, v2, v145 dst_sel:DWORD dst_unused:UNUSED_PAD src0_sel:WORD_1 src1_sel:DWORD
	v_and_b32_sdwa v4, v1, v145 dst_sel:DWORD dst_unused:UNUSED_PAD src0_sel:WORD_1 src1_sel:DWORD
	v_and_b32_sdwa v5, v0, v145 dst_sel:DWORD dst_unused:UNUSED_PAD src0_sel:WORD_1 src1_sel:DWORD
	v_add3_u32 v3, v3, v6, s29
	v_add3_u32 v2, v2, v7, s29
	v_add3_u32 v0, v0, v5, s29
	v_add3_u32 v1, v1, v4, s29
	v_and_b32_e32 v3, 0xffff0000, v3
	v_and_b32_e32 v2, 0xffff0000, v2
	v_or_b32_sdwa v1, v3, v1 dst_sel:DWORD dst_unused:UNUSED_PAD src0_sel:DWORD src1_sel:WORD_1
	v_or_b32_sdwa v0, v2, v0 dst_sel:DWORD dst_unused:UNUSED_PAD src0_sel:DWORD src1_sel:WORD_1
	global_store_dwordx2 v[118:119], v[0:1], off offset:1024
	ds_read_b128 v[0:3], v144 offset:27648
	v_mov_b32_e32 v5, v40
	v_mov_b32_e32 v40, v39
	v_mov_b32_e32 v4, v38
	v_pk_mul_f32 v[6:7], v[40:41], v[28:29] op_sel_hi:[1,0]
	v_pk_mul_f32 v[4:5], v[4:5], v[28:29] op_sel_hi:[1,0]
	s_waitcnt lgkmcnt(0)
	v_mov_b32_e32 v9, v2
	v_mov_b32_e32 v2, v1
	v_mov_b32_e32 v8, v0
	v_pk_mul_f32 v[2:3], v[6:7], v[2:3]
	v_pk_mul_f32 v[0:1], v[4:5], v[8:9]
	v_and_b32_sdwa v6, v3, v145 dst_sel:DWORD dst_unused:UNUSED_PAD src0_sel:WORD_1 src1_sel:DWORD
	v_and_b32_sdwa v7, v2, v145 dst_sel:DWORD dst_unused:UNUSED_PAD src0_sel:WORD_1 src1_sel:DWORD
	v_and_b32_sdwa v4, v1, v145 dst_sel:DWORD dst_unused:UNUSED_PAD src0_sel:WORD_1 src1_sel:DWORD
	v_and_b32_sdwa v5, v0, v145 dst_sel:DWORD dst_unused:UNUSED_PAD src0_sel:WORD_1 src1_sel:DWORD
	v_add3_u32 v3, v3, v6, s29
	v_add3_u32 v2, v2, v7, s29
	v_add3_u32 v0, v0, v5, s29
	v_add3_u32 v1, v1, v4, s29
	v_and_b32_e32 v3, 0xffff0000, v3
	v_and_b32_e32 v2, 0xffff0000, v2
	v_or_b32_sdwa v1, v3, v1 dst_sel:DWORD dst_unused:UNUSED_PAD src0_sel:DWORD src1_sel:WORD_1
	v_or_b32_sdwa v0, v2, v0 dst_sel:DWORD dst_unused:UNUSED_PAD src0_sel:DWORD src1_sel:WORD_1
	global_store_dwordx2 v[118:119], v[0:1], off offset:1536
	ds_read_b128 v[0:3], v144 offset:28672
	v_mov_b32_e32 v5, v34
	v_mov_b32_e32 v34, v33
	v_mov_b32_e32 v4, v32
	v_pk_mul_f32 v[6:7], v[34:35], v[28:29] op_sel_hi:[1,0]
	v_pk_mul_f32 v[4:5], v[4:5], v[28:29] op_sel_hi:[1,0]
	s_waitcnt lgkmcnt(0)
	v_mov_b32_e32 v9, v2
	v_mov_b32_e32 v2, v1
	v_mov_b32_e32 v8, v0
	v_pk_mul_f32 v[2:3], v[6:7], v[2:3]
	v_pk_mul_f32 v[0:1], v[4:5], v[8:9]
	v_and_b32_sdwa v6, v3, v145 dst_sel:DWORD dst_unused:UNUSED_PAD src0_sel:WORD_1 src1_sel:DWORD
	v_and_b32_sdwa v7, v2, v145 dst_sel:DWORD dst_unused:UNUSED_PAD src0_sel:WORD_1 src1_sel:DWORD
	v_and_b32_sdwa v4, v1, v145 dst_sel:DWORD dst_unused:UNUSED_PAD src0_sel:WORD_1 src1_sel:DWORD
	v_and_b32_sdwa v5, v0, v145 dst_sel:DWORD dst_unused:UNUSED_PAD src0_sel:WORD_1 src1_sel:DWORD
	v_add3_u32 v3, v3, v6, s29
	v_add3_u32 v2, v2, v7, s29
	v_add3_u32 v0, v0, v5, s29
	v_add3_u32 v1, v1, v4, s29
	v_and_b32_e32 v3, 0xffff0000, v3
	v_and_b32_e32 v2, 0xffff0000, v2
	v_or_b32_sdwa v1, v3, v1 dst_sel:DWORD dst_unused:UNUSED_PAD src0_sel:DWORD src1_sel:WORD_1
	v_or_b32_sdwa v0, v2, v0 dst_sel:DWORD dst_unused:UNUSED_PAD src0_sel:DWORD src1_sel:WORD_1
	global_store_dwordx2 v[118:119], v[0:1], off offset:2048
	ds_read_b128 v[0:3], v144 offset:29696
	v_pk_mul_f32 v[6:7], v[30:31], v[28:29] op_sel_hi:[1,0]
	v_pk_mul_f32 v[4:5], v[46:47], v[28:29] op_sel_hi:[1,0]
	s_waitcnt lgkmcnt(0)
	v_mov_b32_e32 v9, v2
	v_mov_b32_e32 v2, v1
	v_mov_b32_e32 v8, v0
	v_pk_mul_f32 v[2:3], v[6:7], v[2:3]
	v_pk_mul_f32 v[0:1], v[4:5], v[8:9]
	v_and_b32_sdwa v6, v3, v145 dst_sel:DWORD dst_unused:UNUSED_PAD src0_sel:WORD_1 src1_sel:DWORD
	v_and_b32_sdwa v7, v2, v145 dst_sel:DWORD dst_unused:UNUSED_PAD src0_sel:WORD_1 src1_sel:DWORD
	v_and_b32_sdwa v4, v1, v145 dst_sel:DWORD dst_unused:UNUSED_PAD src0_sel:WORD_1 src1_sel:DWORD
	v_and_b32_sdwa v5, v0, v145 dst_sel:DWORD dst_unused:UNUSED_PAD src0_sel:WORD_1 src1_sel:DWORD
	v_add3_u32 v3, v3, v6, s29
	v_add3_u32 v2, v2, v7, s29
	v_add3_u32 v0, v0, v5, s29
	v_add3_u32 v1, v1, v4, s29
	v_and_b32_e32 v3, 0xffff0000, v3
	v_and_b32_e32 v2, 0xffff0000, v2
	v_or_b32_sdwa v1, v3, v1 dst_sel:DWORD dst_unused:UNUSED_PAD src0_sel:DWORD src1_sel:WORD_1
	v_or_b32_sdwa v0, v2, v0 dst_sel:DWORD dst_unused:UNUSED_PAD src0_sel:DWORD src1_sel:WORD_1
	global_store_dwordx2 v[118:119], v[0:1], off offset:2560
	ds_read_b128 v[0:3], v144 offset:30720
	v_mov_b32_e32 v5, v24
	v_mov_b32_e32 v24, v23
	v_mov_b32_e32 v4, v22
	v_pk_mul_f32 v[6:7], v[24:25], v[28:29] op_sel_hi:[1,0]
	v_pk_mul_f32 v[4:5], v[4:5], v[28:29] op_sel_hi:[1,0]
	s_waitcnt lgkmcnt(0)
	v_mov_b32_e32 v9, v2
	v_mov_b32_e32 v2, v1
	v_mov_b32_e32 v8, v0
	v_pk_mul_f32 v[2:3], v[6:7], v[2:3]
	v_pk_mul_f32 v[0:1], v[4:5], v[8:9]
	v_and_b32_sdwa v6, v3, v145 dst_sel:DWORD dst_unused:UNUSED_PAD src0_sel:WORD_1 src1_sel:DWORD
	v_and_b32_sdwa v7, v2, v145 dst_sel:DWORD dst_unused:UNUSED_PAD src0_sel:WORD_1 src1_sel:DWORD
	v_and_b32_sdwa v4, v1, v145 dst_sel:DWORD dst_unused:UNUSED_PAD src0_sel:WORD_1 src1_sel:DWORD
	v_and_b32_sdwa v5, v0, v145 dst_sel:DWORD dst_unused:UNUSED_PAD src0_sel:WORD_1 src1_sel:DWORD
	v_add3_u32 v3, v3, v6, s29
	v_add3_u32 v2, v2, v7, s29
	v_add3_u32 v0, v0, v5, s29
	v_add3_u32 v1, v1, v4, s29
	v_and_b32_e32 v3, 0xffff0000, v3
	v_and_b32_e32 v2, 0xffff0000, v2
	v_or_b32_sdwa v1, v3, v1 dst_sel:DWORD dst_unused:UNUSED_PAD src0_sel:DWORD src1_sel:WORD_1
	v_or_b32_sdwa v0, v2, v0 dst_sel:DWORD dst_unused:UNUSED_PAD src0_sel:DWORD src1_sel:WORD_1
	global_store_dwordx2 v[118:119], v[0:1], off offset:3072
	ds_read_b128 v[0:3], v144 offset:31744
	v_mov_b32_e32 v5, v18
	v_mov_b32_e32 v18, v17
	v_mov_b32_e32 v4, v16
	v_pk_mul_f32 v[6:7], v[18:19], v[28:29] op_sel_hi:[1,0]
	v_pk_mul_f32 v[4:5], v[4:5], v[28:29] op_sel_hi:[1,0]
	s_waitcnt lgkmcnt(0)
	v_mov_b32_e32 v9, v2
	v_mov_b32_e32 v2, v1
	v_mov_b32_e32 v8, v0
	v_pk_mul_f32 v[2:3], v[6:7], v[2:3]
	v_pk_mul_f32 v[0:1], v[4:5], v[8:9]
	v_and_b32_sdwa v6, v3, v145 dst_sel:DWORD dst_unused:UNUSED_PAD src0_sel:WORD_1 src1_sel:DWORD
	v_and_b32_sdwa v7, v2, v145 dst_sel:DWORD dst_unused:UNUSED_PAD src0_sel:WORD_1 src1_sel:DWORD
	v_and_b32_sdwa v4, v1, v145 dst_sel:DWORD dst_unused:UNUSED_PAD src0_sel:WORD_1 src1_sel:DWORD
	v_and_b32_sdwa v5, v0, v145 dst_sel:DWORD dst_unused:UNUSED_PAD src0_sel:WORD_1 src1_sel:DWORD
	v_add3_u32 v3, v3, v6, s29
	v_add3_u32 v2, v2, v7, s29
	v_add3_u32 v0, v0, v5, s29
	v_add3_u32 v1, v1, v4, s29
	v_and_b32_e32 v3, 0xffff0000, v3
	v_and_b32_e32 v2, 0xffff0000, v2
	v_or_b32_sdwa v1, v3, v1 dst_sel:DWORD dst_unused:UNUSED_PAD src0_sel:DWORD src1_sel:WORD_1
	v_or_b32_sdwa v0, v2, v0 dst_sel:DWORD dst_unused:UNUSED_PAD src0_sel:DWORD src1_sel:WORD_1
	global_store_dwordx2 v[118:119], v[0:1], off offset:3584
	s_cbranch_scc0 .LBB0_3749

.LBB0_4009:
	v_lshl_add_u64 v[38:39], s[14:15], 0, v[36:37]
	v_add_co_u32_e32 v64, vcc, s13, v38
	v_lshl_add_u64 v[44:45], s[14:15], 0, v[34:35]
	s_nop 0
	v_addc_co_u32_e32 v65, vcc, 0, v39, vcc
	v_add_co_u32_e32 v38, vcc, s26, v38
	v_lshl_add_u64 v[62:63], s[14:15], 0, v[32:33]
	global_load_dword v40, v[62:63], off
	global_load_dwordx4 v[160:163], v34, s[80:81] offset:0 nt
	global_load_dwordx2 v[224:225], v36, s[88:89] offset:0
	global_load_dwordx4 v[164:167], v34, s[80:81] offset:1024 nt
	global_load_dwordx2 v[226:227], v36, s[88:89] offset:512
	global_load_dwordx4 v[168:171], v34, s[80:81] offset:2048 nt
	global_load_dwordx2 v[228:229], v36, s[88:89] offset:1024
	global_load_dwordx4 v[172:175], v34, s[80:81] offset:3072 nt
	global_load_dwordx2 v[230:231], v36, s[88:89] offset:1536
	global_load_dwordx4 v[176:179], v34, s[82:83] offset:0 nt
	global_load_dwordx2 v[232:233], v36, s[88:89] offset:2048
	global_load_dwordx4 v[180:183], v34, s[82:83] offset:1024 nt
	global_load_dwordx2 v[234:235], v36, s[88:89] offset:2560
	global_load_dwordx4 v[184:187], v34, s[82:83] offset:2048 nt
	global_load_dwordx2 v[236:237], v36, s[88:89] offset:3072
	global_load_dwordx4 v[188:191], v34, s[82:83] offset:3072 nt
	global_load_dwordx2 v[238:239], v36, s[88:89] offset:3584
	global_load_dwordx4 v[192:195], v34, s[84:85] offset:0 nt
	global_load_dwordx2 v[240:241], v36, s[90:91] offset:0
	global_load_dwordx4 v[196:199], v34, s[84:85] offset:1024 nt
	global_load_dwordx2 v[242:243], v36, s[90:91] offset:512
	global_load_dwordx4 v[200:203], v34, s[84:85] offset:2048 nt
	global_load_dwordx2 v[244:245], v36, s[90:91] offset:1024
	global_load_dwordx4 v[204:207], v34, s[84:85] offset:3072 nt
	global_load_dwordx2 v[246:247], v36, s[90:91] offset:1536
	global_load_dwordx4 v[208:211], v34, s[86:87] offset:0 nt
	global_load_dwordx2 v[248:249], v36, s[90:91] offset:2048
	global_load_dwordx4 v[212:215], v34, s[86:87] offset:1024 nt
	global_load_dwordx2 v[250:251], v36, s[90:91] offset:2560
	global_load_dwordx4 v[216:219], v34, s[86:87] offset:2048 nt
	global_load_dwordx2 v[252:253], v36, s[90:91] offset:3072
	global_load_dwordx4 v[220:223], v34, s[86:87] offset:3072 nt
	global_load_dwordx2 v[254:255], v36, s[90:91] offset:3584
	s_nop 0
	v_addc_co_u32_e32 v39, vcc, 0, v39, vcc
	v_add_co_u32_e32 v66, vcc, s24, v44
	ds_read_b128 v[54:57], v76 offset:0
	s_nop 0
	v_addc_co_u32_e32 v67, vcc, 0, v45, vcc
	v_add_co_u32_e32 v68, vcc, s25, v44
	v_lshl_add_u64 v[42:43], s[6:7], 0, v[34:35]
	s_nop 0
	v_addc_co_u32_e32 v69, vcc, 0, v45, vcc
	s_waitcnt vmcnt(30)
	s_nop 1
	v_mov_b32_e32 v70, v224
	v_mov_b32_e32 v71, v225
	s_waitcnt vmcnt(31)
	s_nop 1
	v_mov_b32_e32 v58, v160
	v_mov_b32_e32 v59, v161
	v_mov_b32_e32 v60, v162
	v_mov_b32_e32 v61, v163
	s_add_i32 s10, s10, s12
	v_lshl_add_u64 v[32:33], v[32:33], 0, s[4:5]
	v_lshl_add_u64 v[34:35], v[34:35], 0, s[16:17]
	v_lshl_add_u64 v[36:37], v[36:37], 0, s[18:19]
	s_cmpk_gt_i32 s10, 0x3fff
	s_waitcnt vmcnt(32) lgkmcnt(0)
	ds_bpermute_b32 v53, v41, v40
	s_waitcnt lgkmcnt(0)
	v_lshlrev_b32_e32 v62, 16, v70
	v_and_b32_e32 v63, 0xffff0000, v70
	v_lshlrev_b32_e32 v70, 16, v71
	v_and_b32_e32 v71, 0xffff0000, v71
	s_waitcnt lgkmcnt(0)
	v_add_f32_e32 v40, v40, v53
	ds_bpermute_b32 v53, v46, v40
	s_waitcnt lgkmcnt(0)
	v_add_f32_e32 v40, v40, v53
	ds_bpermute_b32 v53, v47, v40
	s_waitcnt lgkmcnt(0)
	v_add_f32_e32 v40, v40, v53
	ds_bpermute_b32 v53, v48, v40
	s_waitcnt lgkmcnt(0)
	v_add_f32_e32 v40, v40, v53
	ds_bpermute_b32 v53, v49, v40
	s_waitcnt lgkmcnt(0)
	v_add_f32_e32 v40, v40, v53
	ds_bpermute_b32 v53, v50, v40
	s_waitcnt lgkmcnt(0)
	v_add_f32_e32 v40, v40, v53
	v_fmamk_f32 v40, v40, 0x39800000, v51
	v_mul_f32_e32 v53, 0x4f800000, v40
	v_cmp_gt_f32_e32 vcc, s11, v40
	s_nop 1
	v_cndmask_b32_e32 v40, v40, v53, vcc
	v_sqrt_f32_e32 v53, v40
	s_nop 0
	v_add_u32_e32 v72, -1, v53
	v_add_u32_e32 v73, 1, v53
	v_fma_f32 v74, -v72, v53, v40
	v_fma_f32 v75, -v73, v53, v40
	v_cmp_ge_f32_e64 s[2:3], 0, v74
	s_nop 1
	v_cndmask_b32_e64 v53, v53, v72, s[2:3]
	v_cmp_lt_f32_e64 s[2:3], 0, v75
	s_nop 1
	v_cndmask_b32_e64 v53, v53, v73, s[2:3]
	v_mul_f32_e32 v72, 0x37800000, v53
	v_cndmask_b32_e32 v53, v53, v72, vcc
	v_cmp_class_f32_e32 vcc, v40, v52
	s_nop 1
	v_cndmask_b32_e32 v40, v53, v40, vcc
	v_div_scale_f32 v53, s[2:3], v40, v40, 1.0
	v_rcp_f32_e32 v73, v53
	v_div_scale_f32 v72, vcc, 1.0, v40, 1.0
	v_fma_f32 v74, -v53, v73, 1.0
	v_fmac_f32_e32 v73, v74, v73
	v_mul_f32_e32 v74, v72, v73
	v_fma_f32 v75, -v53, v74, v72
	v_fmac_f32_e32 v74, v75, v73
	v_fma_f32 v53, -v53, v74, v72
	v_div_fmas_f32 v53, v53, v73, v74
	v_div_fixup_f32 v40, v53, v40, 1.0
	v_pk_mul_f32 v[62:63], v[40:41], v[62:63] op_sel_hi:[0,1]
	v_pk_mul_f32 v[70:71], v[40:41], v[70:71] op_sel_hi:[0,1]
	s_waitcnt lgkmcnt(0)
	v_pk_fma_f32 v[54:55], v[54:55], v[62:63], v[58:59]
	v_pk_fma_f32 v[56:57], v[56:57], v[70:71], v[60:61]
	global_store_dwordx4 v[42:43], v[54:57], off nt
	s_waitcnt vmcnt(29)
	s_nop 1
	v_mov_b32_e32 v62, v226
	v_mov_b32_e32 v63, v227
	s_nop 0
	s_waitcnt vmcnt(30)
	s_nop 1
	v_mov_b32_e32 v54, v164
	v_mov_b32_e32 v55, v165
	v_mov_b32_e32 v56, v166
	v_mov_b32_e32 v57, v167
	ds_read_b128 v[58:61], v76 offset:1024
	s_waitcnt lgkmcnt(0)
	v_lshlrev_b32_e32 v70, 16, v62
	v_and_b32_e32 v71, 0xffff0000, v62
	v_lshlrev_b32_e32 v62, 16, v63
	v_and_b32_e32 v63, 0xffff0000, v63
	v_pk_mul_f32 v[70:71], v[40:41], v[70:71] op_sel_hi:[0,1]
	v_pk_mul_f32 v[62:63], v[40:41], v[62:63] op_sel_hi:[0,1]
	s_waitcnt lgkmcnt(0)
	v_pk_fma_f32 v[54:55], v[58:59], v[70:71], v[54:55]
	v_pk_fma_f32 v[56:57], v[60:61], v[62:63], v[56:57]
	global_store_dwordx4 v[42:43], v[54:57], off offset:1024 nt
	s_waitcnt vmcnt(28)
	s_nop 1
	v_mov_b32_e32 v62, v228
	v_mov_b32_e32 v63, v229
	s_nop 0
	s_waitcnt vmcnt(29)
	s_nop 1
	v_mov_b32_e32 v54, v168
	v_mov_b32_e32 v55, v169
	v_mov_b32_e32 v56, v170
	v_mov_b32_e32 v57, v171
	ds_read_b128 v[58:61], v76 offset:2048
	s_waitcnt lgkmcnt(0)
	v_lshlrev_b32_e32 v70, 16, v62
	v_and_b32_e32 v71, 0xffff0000, v62
	v_lshlrev_b32_e32 v62, 16, v63
	v_and_b32_e32 v63, 0xffff0000, v63
	v_pk_mul_f32 v[70:71], v[40:41], v[70:71] op_sel_hi:[0,1]
	v_pk_mul_f32 v[62:63], v[40:41], v[62:63] op_sel_hi:[0,1]
	s_waitcnt lgkmcnt(0)
	v_pk_fma_f32 v[54:55], v[58:59], v[70:71], v[54:55]
	v_pk_fma_f32 v[56:57], v[60:61], v[62:63], v[56:57]
	global_store_dwordx4 v[42:43], v[54:57], off offset:2048 nt
	s_waitcnt vmcnt(27)
	s_nop 1
	v_mov_b32_e32 v62, v230
	v_mov_b32_e32 v63, v231
	s_nop 0
	s_waitcnt vmcnt(28)
	s_nop 1
	v_mov_b32_e32 v54, v172
	v_mov_b32_e32 v55, v173
	v_mov_b32_e32 v56, v174
	v_mov_b32_e32 v57, v175
	ds_read_b128 v[58:61], v76 offset:3072
	s_waitcnt lgkmcnt(0)
	v_lshlrev_b32_e32 v66, 16, v62
	v_and_b32_e32 v67, 0xffff0000, v62
	v_lshlrev_b32_e32 v62, 16, v63
	v_and_b32_e32 v63, 0xffff0000, v63
	v_pk_mul_f32 v[66:67], v[40:41], v[66:67] op_sel_hi:[0,1]
	v_pk_mul_f32 v[62:63], v[40:41], v[62:63] op_sel_hi:[0,1]
	s_waitcnt lgkmcnt(0)
	v_pk_fma_f32 v[54:55], v[58:59], v[66:67], v[54:55]
	v_pk_fma_f32 v[56:57], v[60:61], v[62:63], v[56:57]
	global_store_dwordx4 v[42:43], v[54:57], off offset:3072 nt
	s_waitcnt vmcnt(26)
	s_nop 1
	v_mov_b32_e32 v62, v232
	v_mov_b32_e32 v63, v233
	s_nop 0
	s_waitcnt vmcnt(27)
	s_nop 1
	v_mov_b32_e32 v54, v176
	v_mov_b32_e32 v55, v177
	v_mov_b32_e32 v56, v178
	v_mov_b32_e32 v57, v179
	ds_read_b128 v[58:61], v76 offset:4096
	v_add_co_u32_e32 v66, vcc, s22, v42
	s_waitcnt lgkmcnt(0)
	v_lshlrev_b32_e32 v70, 16, v62
	v_and_b32_e32 v71, 0xffff0000, v62
	v_lshlrev_b32_e32 v62, 16, v63
	v_and_b32_e32 v63, 0xffff0000, v63
	v_pk_mul_f32 v[70:71], v[40:41], v[70:71] op_sel_hi:[0,1]
	v_pk_mul_f32 v[62:63], v[40:41], v[62:63] op_sel_hi:[0,1]
	v_addc_co_u32_e32 v67, vcc, 0, v43, vcc
	s_waitcnt lgkmcnt(0)
	v_pk_fma_f32 v[54:55], v[58:59], v[70:71], v[54:55]
	v_pk_fma_f32 v[56:57], v[60:61], v[62:63], v[56:57]
	global_store_dwordx4 v[66:67], v[54:57], off offset:-4096 nt
	s_waitcnt vmcnt(25)
	s_nop 1
	v_mov_b32_e32 v62, v234
	v_mov_b32_e32 v63, v235
	s_nop 0
	s_waitcnt vmcnt(26)
	s_nop 1
	v_mov_b32_e32 v54, v180
	v_mov_b32_e32 v55, v181
	v_mov_b32_e32 v56, v182
	v_mov_b32_e32 v57, v183
	ds_read_b128 v[58:61], v76 offset:5120
	v_add_co_u32_e32 v70, vcc, s21, v42
	s_waitcnt lgkmcnt(0)
	v_lshlrev_b32_e32 v72, 16, v62
	v_and_b32_e32 v73, 0xffff0000, v62
	v_lshlrev_b32_e32 v62, 16, v63
	v_and_b32_e32 v63, 0xffff0000, v63
	v_pk_mul_f32 v[72:73], v[40:41], v[72:73] op_sel_hi:[0,1]
	v_pk_mul_f32 v[62:63], v[40:41], v[62:63] op_sel_hi:[0,1]
	v_addc_co_u32_e32 v71, vcc, 0, v43, vcc
	s_waitcnt lgkmcnt(0)
	v_pk_fma_f32 v[54:55], v[58:59], v[72:73], v[54:55]
	v_pk_fma_f32 v[56:57], v[60:61], v[62:63], v[56:57]
	global_store_dwordx4 v[70:71], v[54:57], off offset:1024 nt
	s_waitcnt vmcnt(24)
	s_nop 1
	v_mov_b32_e32 v62, v236
	v_mov_b32_e32 v63, v237
	s_nop 0
	s_waitcnt vmcnt(25)
	s_nop 1
	v_mov_b32_e32 v54, v184
	v_mov_b32_e32 v55, v185
	v_mov_b32_e32 v56, v186
	v_mov_b32_e32 v57, v187
	ds_read_b128 v[58:61], v76 offset:6144
	s_waitcnt lgkmcnt(0)
	v_lshlrev_b32_e32 v72, 16, v62
	v_and_b32_e32 v73, 0xffff0000, v62
	v_lshlrev_b32_e32 v62, 16, v63
	v_and_b32_e32 v63, 0xffff0000, v63
	v_pk_mul_f32 v[72:73], v[40:41], v[72:73] op_sel_hi:[0,1]
	v_pk_mul_f32 v[62:63], v[40:41], v[62:63] op_sel_hi:[0,1]
	s_waitcnt lgkmcnt(0)
	v_pk_fma_f32 v[54:55], v[58:59], v[72:73], v[54:55]
	v_pk_fma_f32 v[56:57], v[60:61], v[62:63], v[56:57]
	global_store_dwordx4 v[70:71], v[54:57], off offset:2048 nt
	s_waitcnt vmcnt(23)
	s_nop 1
	v_mov_b32_e32 v62, v238
	v_mov_b32_e32 v63, v239
	s_nop 0
	s_waitcnt vmcnt(24)
	s_nop 1
	v_mov_b32_e32 v54, v188
	v_mov_b32_e32 v55, v189
	v_mov_b32_e32 v56, v190
	v_mov_b32_e32 v57, v191
	ds_read_b128 v[58:61], v76 offset:7168
	v_add_co_u32_e32 v64, vcc, s28, v44
	s_waitcnt lgkmcnt(0)
	v_lshlrev_b32_e32 v68, 16, v62
	v_and_b32_e32 v69, 0xffff0000, v62
	v_lshlrev_b32_e32 v62, 16, v63
	v_and_b32_e32 v63, 0xffff0000, v63
	v_pk_mul_f32 v[68:69], v[40:41], v[68:69] op_sel_hi:[0,1]
	v_pk_mul_f32 v[62:63], v[40:41], v[62:63] op_sel_hi:[0,1]
	s_waitcnt lgkmcnt(0)
	v_pk_fma_f32 v[54:55], v[58:59], v[68:69], v[54:55]
	v_pk_fma_f32 v[56:57], v[60:61], v[62:63], v[56:57]
	global_store_dwordx4 v[70:71], v[54:57], off offset:3072 nt
	v_addc_co_u32_e32 v65, vcc, 0, v45, vcc
	s_waitcnt vmcnt(22)
	s_nop 1
	v_mov_b32_e32 v62, v240
	v_mov_b32_e32 v63, v241
	s_waitcnt vmcnt(23)
	s_nop 1
	v_mov_b32_e32 v54, v192
	v_mov_b32_e32 v55, v193
	v_mov_b32_e32 v56, v194
	v_mov_b32_e32 v57, v195
	ds_read_b128 v[58:61], v76 offset:8192
	v_add_co_u32_e32 v44, vcc, s27, v44
	s_waitcnt lgkmcnt(0)
	v_lshlrev_b32_e32 v68, 16, v62
	v_and_b32_e32 v69, 0xffff0000, v62
	v_lshlrev_b32_e32 v62, 16, v63
	v_and_b32_e32 v63, 0xffff0000, v63
	v_pk_mul_f32 v[68:69], v[40:41], v[68:69] op_sel_hi:[0,1]
	v_pk_mul_f32 v[62:63], v[40:41], v[62:63] op_sel_hi:[0,1]
	s_waitcnt lgkmcnt(0)
	v_pk_fma_f32 v[54:55], v[58:59], v[68:69], v[54:55]
	v_pk_fma_f32 v[56:57], v[60:61], v[62:63], v[56:57]
	global_store_dwordx4 v[66:67], v[54:57], off nt
	v_addc_co_u32_e32 v45, vcc, 0, v45, vcc
	s_waitcnt vmcnt(21)
	s_nop 1
	v_mov_b32_e32 v62, v242
	v_mov_b32_e32 v63, v243
	s_waitcnt vmcnt(22)
	s_nop 1
	v_mov_b32_e32 v54, v196
	v_mov_b32_e32 v55, v197
	v_mov_b32_e32 v56, v198
	v_mov_b32_e32 v57, v199
	ds_read_b128 v[58:61], v76 offset:9216
	s_waitcnt lgkmcnt(0)
	v_lshlrev_b32_e32 v68, 16, v62
	v_and_b32_e32 v69, 0xffff0000, v62
	v_lshlrev_b32_e32 v62, 16, v63
	v_and_b32_e32 v63, 0xffff0000, v63
	v_pk_mul_f32 v[68:69], v[40:41], v[68:69] op_sel_hi:[0,1]
	v_pk_mul_f32 v[62:63], v[40:41], v[62:63] op_sel_hi:[0,1]
	s_waitcnt lgkmcnt(0)
	v_pk_fma_f32 v[54:55], v[58:59], v[68:69], v[54:55]
	v_pk_fma_f32 v[56:57], v[60:61], v[62:63], v[56:57]
	global_store_dwordx4 v[66:67], v[54:57], off offset:1024 nt
	s_waitcnt vmcnt(20)
	s_nop 1
	v_mov_b32_e32 v62, v244
	v_mov_b32_e32 v63, v245
	s_nop 0
	s_waitcnt vmcnt(21)
	s_nop 1
	v_mov_b32_e32 v54, v200
	v_mov_b32_e32 v55, v201
	v_mov_b32_e32 v56, v202
	v_mov_b32_e32 v57, v203
	ds_read_b128 v[58:61], v76 offset:10240
	s_waitcnt lgkmcnt(0)
	v_lshlrev_b32_e32 v68, 16, v62
	v_and_b32_e32 v69, 0xffff0000, v62
	v_lshlrev_b32_e32 v62, 16, v63
	v_and_b32_e32 v63, 0xffff0000, v63
	v_pk_mul_f32 v[68:69], v[40:41], v[68:69] op_sel_hi:[0,1]
	v_pk_mul_f32 v[62:63], v[40:41], v[62:63] op_sel_hi:[0,1]
	s_waitcnt lgkmcnt(0)
	v_pk_fma_f32 v[54:55], v[58:59], v[68:69], v[54:55]
	v_pk_fma_f32 v[56:57], v[60:61], v[62:63], v[56:57]
	global_store_dwordx4 v[66:67], v[54:57], off offset:2048 nt
	s_waitcnt vmcnt(19)
	s_nop 1
	v_mov_b32_e32 v62, v246
	v_mov_b32_e32 v63, v247
	s_nop 0
	s_waitcnt vmcnt(20)
	s_nop 1
	v_mov_b32_e32 v54, v204
	v_mov_b32_e32 v55, v205
	v_mov_b32_e32 v56, v206
	v_mov_b32_e32 v57, v207
	ds_read_b128 v[58:61], v76 offset:11264
	s_waitcnt lgkmcnt(0)
	v_lshlrev_b32_e32 v44, 16, v62
	v_and_b32_e32 v45, 0xffff0000, v62
	v_lshlrev_b32_e32 v62, 16, v63
	v_and_b32_e32 v63, 0xffff0000, v63
	v_pk_mul_f32 v[44:45], v[40:41], v[44:45] op_sel_hi:[0,1]
	v_pk_mul_f32 v[62:63], v[40:41], v[62:63] op_sel_hi:[0,1]
	s_waitcnt lgkmcnt(0)
	v_pk_fma_f32 v[54:55], v[58:59], v[44:45], v[54:55]
	v_pk_fma_f32 v[56:57], v[60:61], v[62:63], v[56:57]
	global_store_dwordx4 v[66:67], v[54:57], off offset:3072 nt
	s_waitcnt vmcnt(18)
	s_nop 1
	v_mov_b32_e32 v44, v248
	v_mov_b32_e32 v45, v249
	s_nop 0
	s_waitcnt vmcnt(19)
	s_nop 1
	v_mov_b32_e32 v54, v208
	v_mov_b32_e32 v55, v209
	v_mov_b32_e32 v56, v210
	v_mov_b32_e32 v57, v211
	ds_read_b128 v[58:61], v76 offset:12288
	v_add_co_u32_e32 v62, vcc, s23, v42
	s_waitcnt lgkmcnt(0)
	v_lshlrev_b32_e32 v42, 16, v44
	v_addc_co_u32_e32 v63, vcc, 0, v43, vcc
	v_and_b32_e32 v43, 0xffff0000, v44
	v_lshlrev_b32_e32 v44, 16, v45
	v_and_b32_e32 v45, 0xffff0000, v45
	v_pk_mul_f32 v[42:43], v[40:41], v[42:43] op_sel_hi:[0,1]
	v_pk_mul_f32 v[44:45], v[40:41], v[44:45] op_sel_hi:[0,1]
	s_waitcnt lgkmcnt(0)
	v_pk_fma_f32 v[42:43], v[58:59], v[42:43], v[54:55]
	v_pk_fma_f32 v[44:45], v[60:61], v[44:45], v[56:57]
	global_store_dwordx4 v[62:63], v[42:45], off nt
	s_waitcnt vmcnt(17)
	s_nop 1
	v_mov_b32_e32 v58, v250
	v_mov_b32_e32 v59, v251
	s_nop 0
	s_waitcnt vmcnt(18)
	s_nop 1
	v_mov_b32_e32 v42, v212
	v_mov_b32_e32 v43, v213
	v_mov_b32_e32 v44, v214
	v_mov_b32_e32 v45, v215
	ds_read_b128 v[54:57], v76 offset:13312
	s_waitcnt lgkmcnt(0)
	v_lshlrev_b32_e32 v60, 16, v58
	v_and_b32_e32 v61, 0xffff0000, v58
	v_lshlrev_b32_e32 v58, 16, v59
	v_and_b32_e32 v59, 0xffff0000, v59
	v_pk_mul_f32 v[60:61], v[40:41], v[60:61] op_sel_hi:[0,1]
	v_pk_mul_f32 v[58:59], v[40:41], v[58:59] op_sel_hi:[0,1]
	s_waitcnt lgkmcnt(0)
	v_pk_fma_f32 v[42:43], v[54:55], v[60:61], v[42:43]
	v_pk_fma_f32 v[44:45], v[56:57], v[58:59], v[44:45]
	global_store_dwordx4 v[62:63], v[42:45], off offset:1024 nt
	s_waitcnt vmcnt(16)
	s_nop 1
	v_mov_b32_e32 v58, v252
	v_mov_b32_e32 v59, v253
	s_nop 0
	s_waitcnt vmcnt(17)
	s_nop 1
	v_mov_b32_e32 v42, v216
	v_mov_b32_e32 v43, v217
	v_mov_b32_e32 v44, v218
	v_mov_b32_e32 v45, v219
	ds_read_b128 v[54:57], v76 offset:14336
	s_waitcnt lgkmcnt(0)
	v_lshlrev_b32_e32 v60, 16, v58
	v_and_b32_e32 v61, 0xffff0000, v58
	v_lshlrev_b32_e32 v58, 16, v59
	v_and_b32_e32 v59, 0xffff0000, v59
	v_pk_mul_f32 v[60:61], v[40:41], v[60:61] op_sel_hi:[0,1]
	v_pk_mul_f32 v[58:59], v[40:41], v[58:59] op_sel_hi:[0,1]
	s_waitcnt lgkmcnt(0)
	v_pk_fma_f32 v[42:43], v[54:55], v[60:61], v[42:43]
	v_pk_fma_f32 v[44:45], v[56:57], v[58:59], v[44:45]
	global_store_dwordx4 v[62:63], v[42:45], off offset:2048 nt
	s_waitcnt vmcnt(15)
	s_nop 1
	v_mov_b32_e32 v58, v254
	v_mov_b32_e32 v59, v255
	s_nop 0
	s_waitcnt vmcnt(16)
	s_nop 1
	v_mov_b32_e32 v42, v220
	v_mov_b32_e32 v43, v221
	v_mov_b32_e32 v44, v222
	v_mov_b32_e32 v45, v223
	ds_read_b128 v[54:57], v76 offset:15360
	s_waitcnt lgkmcnt(0)
	v_lshlrev_b32_e32 v38, 16, v58
	v_and_b32_e32 v39, 0xffff0000, v58
	v_lshlrev_b32_e32 v58, 16, v59
	v_and_b32_e32 v59, 0xffff0000, v59
	v_pk_mul_f32 v[38:39], v[40:41], v[38:39] op_sel_hi:[0,1]
	v_pk_mul_f32 v[58:59], v[40:41], v[58:59] op_sel_hi:[0,1]
	s_waitcnt lgkmcnt(0)
	v_pk_fma_f32 v[42:43], v[54:55], v[38:39], v[42:43]
	v_pk_fma_f32 v[44:45], v[56:57], v[58:59], v[44:45]
	global_store_dwordx4 v[62:63], v[42:45], off offset:3072 nt
	s_cbranch_scc0 .LBB0_4009
